# even_prep forward substitution hand-scheduled: L pieces streamed through a 12-deep register ring with counted lgkmcnt, 4 accumulators per row; software prefetch of chunk q/k/v rows
# speedup vs baseline: 1.0374x; 1.0300x over previous
; __device__ __forceinline__ void conv4h(const bf16_t* zc, int row, const bf16_t* hp, bool has_prev, const float* cw, float* y) {
;     ...
;     for (int j = 0; j < 4; ++j) { const int rr = row - 3 + j;
;         if (rr >= 0 || has_prev) { const bf16_t* src = (rr >= 0) ? zc + (size_t)rr * ZLD_E : hp + (3 + rr) * 384; float xv[8]; unpack8(*(const u32x4*)src, xv);
;             const f32x4 w0 = *(const f32x4*)(cw + j * 2304), w1 = *(const f32x4*)(cw + j * 2304 + 4);
;             y[0] += w0.x * xv[0]; y[1] += w0.y * xv[1]; y[2] += w0.z * xv[2]; y[3] += w0.w * xv[3];
;             y[4] += w1.x * xv[4]; y[5] += w1.y * xv[5]; y[6] += w1.z * xv[6]; y[7] += w1.w * xv[7]; } }
; __device__ __forceinline__ void even_prep(const Ctx& c, const Params& p, int e) {
;     ...
;         for (int rep = 0; rep < 2; ++rep) { const int vi = tid_i + 512 * rep, row = vi >> 4, c8 = (vi & 15) * 8;
;             const bf16_t* zc = Z + (size_t)m0 * ZLD_E + 768 + h * 128 + c8; const bf16_t* hp = HALO + (size_t)(bh * 128 + n) * 1152 + c8; float y[8], yd[8];
;             conv4h(zc, row, hp, n > 0, conv_qkv + h * 128 + c8, y);
.LBB0_551:
	v_add_u32_e32 v1, s6, v18
	v_ashrrev_i32_e32 v72, 4, v1
	s_cmp_lg_u32 s6, 0
	s_cbranch_scc1 .Lep_nopf
	v_mad_u64_u32 v[92:93], s[12:13], v72, s69, v[10:11]
	v_lshl_add_u64 v[94:95], v[92:93], 0, s[78:79]
	global_load_dwordx4 v[96:99], v[92:93], off offset:1536
	global_load_dwordx4 v[96:99], v[92:93], off offset:3072
	global_load_dwordx4 v[96:99], v[94:95], off offset:3072
	v_add_co_u32_e32 v92, vcc, 0x3c400, v92
	s_nop 1
	v_addc_co_u32_e32 v93, vcc, 0, v93, vcc
	v_lshl_add_u64 v[94:95], v[92:93], 0, s[78:79]
	global_load_dwordx4 v[96:99], v[92:93], off offset:1536
	global_load_dwordx4 v[96:99], v[92:93], off offset:3072
	global_load_dwordx4 v[96:99], v[94:95], off offset:3072
.Lep_nopf:
	v_cmp_lt_i32_e32 vcc, 2, v72
	v_mov_b32_e32 v1, v0
	v_add_u32_e32 v64, -3, v72
	v_cmp_gt_i32_e64 s[10:11], 3, v72
	s_or_b64 s[86:87], s[82:83], vcc
	v_mov_b64_e32 v[6:7], v[0:1]
	v_mov_b64_e32 v[8:9], v[0:1]
	v_mov_b64_e32 v[42:43], v[0:1]
	v_mov_b64_e32 v[44:45], v[0:1]
	s_and_saveexec_b64 s[6:7], s[86:87]
	s_cbranch_execz .LBB0_557
	s_and_saveexec_b64 s[8:9], s[10:11]
	s_xor_b64 s[8:9], exec, s[8:9]
	v_mul_lo_u32 v6, v72, s64
	v_ashrrev_i32_e32 v7, 31, v6
	v_lshl_add_u64 v[6:7], v[6:7], 1, v[14:15]
	s_andn2_saveexec_b64 s[8:9], s[8:9]
	v_mad_u64_u32 v[6:7], s[12:13], v64, s69, v[10:11]
	v_lshl_add_u64 v[6:7], v[6:7], 0, s[78:79]
	s_or_b64 exec, exec, s[8:9]
	global_load_dwordx4 v[42:45], v[6:7], off
	global_load_dwordx4 v[46:49], v[16:17], off offset:16
	s_nop 0
	global_load_dwordx4 v[6:9], v[16:17], off
	s_waitcnt vmcnt(0) lgkmcnt(0)
	v_and_b32_e32 v51, 0xffff0000, v42
	v_lshlrev_b32_e32 v50, 16, v42
	v_pk_fma_f32 v[6:7], v[6:7], v[50:51], 0 op_sel_hi:[1,1,0]
	v_and_b32_e32 v51, 0xffff0000, v43
	v_lshlrev_b32_e32 v50, 16, v43
	v_and_b32_e32 v43, 0xffff0000, v44
	v_lshlrev_b32_e32 v42, 16, v44
	v_pk_fma_f32 v[42:43], v[46:47], v[42:43], 0 op_sel_hi:[1,1,0]
	v_and_b32_e32 v47, 0xffff0000, v45
	v_lshlrev_b32_e32 v46, 16, v45
	v_pk_fma_f32 v[8:9], v[8:9], v[50:51], 0 op_sel_hi:[1,1,0]
	v_pk_fma_f32 v[44:45], v[48:49], v[46:47], 0 op_sel_hi:[1,1,0]

; #define LAS __attribute__((address_space(3)))
; __device__ __forceinline__ void even_prep(const Ctx& c, const Params& p, int e) {
;     ...
;         if (tid_i < 256) { const int cc = tid_i & 127; const LAS float* src = (tid_i < 128) ? VB : KBG; float x[64];
;             int vz = 0; asm volatile("" : "+v"(vz)); const LAS float* Lv = Lm + vz;
; #pragma unroll
;             for (int i = 0; i < 64; ++i) x[i] = src[i * 128 + cc];
; #pragma unroll
;             for (int i = 1; i < 64; ++i) { const LAS f32x4* Lr = (const LAS f32x4*)(Lv + i * 64); float a0 = x[i], a1 = 0.f;
; #pragma unroll
;                 for (int j4 = 0; j4 < (i + 3) / 4; ++j4) { const f32x4 l = Lr[j4];
;                     if (4 * j4 + 0 < i) a0 -= l[0] * x[4 * j4 + 0];
;                     if (4 * j4 + 1 < i) a1 -= l[1] * x[4 * j4 + 1];
;                     if (4 * j4 + 2 < i) a0 -= l[2] * x[4 * j4 + 2];
;                     if (4 * j4 + 3 < i) a1 -= l[3] * x[4 * j4 + 3]; }
;                 x[i] = a0 + a1; }
;             LAS float* dstl = (tid_i < 128) ? VB : KBG; const float sg = (tid_i < 128) ? 1.f : -1.f;
; #pragma unroll
;             for (int i = 0; i < 64; ++i) dstl[i * 128 + cc] = x[i] * sg; }
.LBB0_788:
	s_movk_i32 s0, 0x100
	v_cmp_gt_i32_e32 vcc, s0, v18
	s_waitcnt lgkmcnt(0)
	s_barrier
	s_and_saveexec_b64 s[6:7], vcc
	s_cbranch_execz .LBB0_790
	v_mov_b32_e32 v1, s42
	v_mov_b32_e32 v2, s39
	v_and_b32_e32 v16, 0x7f, v18
	v_cndmask_b32_e64 v1, v1, v2, s[4:5]
	v_mov_b32_e32 v17, s48
	v_lshl_add_u32 v16, v16, 2, v1
	ds_read2st64_b32 v[92:93], v16 offset0:0 offset1:2
	ds_read2st64_b32 v[94:95], v16 offset0:4 offset1:6
	ds_read2st64_b32 v[96:97], v16 offset0:8 offset1:10
	ds_read2st64_b32 v[98:99], v16 offset0:12 offset1:14
	ds_read2st64_b32 v[100:101], v16 offset0:16 offset1:18
	ds_read2st64_b32 v[102:103], v16 offset0:20 offset1:22
	ds_read2st64_b32 v[104:105], v16 offset0:24 offset1:26
	ds_read2st64_b32 v[106:107], v16 offset0:28 offset1:30
	ds_read2st64_b32 v[108:109], v16 offset0:32 offset1:34
	ds_read2st64_b32 v[110:111], v16 offset0:36 offset1:38
	ds_read2st64_b32 v[112:113], v16 offset0:40 offset1:42
	ds_read2st64_b32 v[114:115], v16 offset0:44 offset1:46
	ds_read2st64_b32 v[116:117], v16 offset0:48 offset1:50
	ds_read2st64_b32 v[118:119], v16 offset0:52 offset1:54
	ds_read2st64_b32 v[120:121], v16 offset0:56 offset1:58
	s_waitcnt lgkmcnt(7)
	ds_read2st64_b32 v[122:123], v16 offset0:60 offset1:62
	ds_read2st64_b32 v[124:125], v16 offset0:64 offset1:66
	ds_read2st64_b32 v[126:127], v16 offset0:68 offset1:70
	ds_read2st64_b32 v[128:129], v16 offset0:72 offset1:74
	ds_read2st64_b32 v[130:131], v16 offset0:76 offset1:78
	ds_read2st64_b32 v[132:133], v16 offset0:80 offset1:82
	ds_read2st64_b32 v[134:135], v16 offset0:84 offset1:86
	ds_read2st64_b32 v[136:137], v16 offset0:88 offset1:90
	s_waitcnt lgkmcnt(7)
	ds_read2st64_b32 v[138:139], v16 offset0:92 offset1:94
	ds_read2st64_b32 v[140:141], v16 offset0:96 offset1:98
	ds_read2st64_b32 v[142:143], v16 offset0:100 offset1:102
	ds_read2st64_b32 v[60:61], v16 offset0:104 offset1:106
	ds_read2st64_b32 v[62:63], v16 offset0:108 offset1:110
	ds_read2st64_b32 v[64:65], v16 offset0:112 offset1:114
	ds_read2st64_b32 v[66:67], v16 offset0:116 offset1:118
	ds_read2st64_b32 v[68:69], v16 offset0:120 offset1:122
	s_waitcnt lgkmcnt(7)
	ds_read2st64_b32 v[70:71], v16 offset0:124 offset1:126
	s_waitcnt lgkmcnt(0)
	ds_read_b128 v[24:27], v17 offset:256
	ds_read_b128 v[28:31], v17 offset:512
	ds_read_b128 v[32:35], v17 offset:768
	ds_read_b128 v[36:39], v17 offset:1024
	ds_read_b128 v[40:43], v17 offset:1280
	ds_read_b128 v[44:47], v17 offset:1296
	ds_read_b128 v[48:51], v17 offset:1536
	ds_read_b128 v[52:55], v17 offset:1552
	ds_read_b128 v[56:59], v17 offset:1792
	ds_read_b128 v[4:7], v17 offset:1808
	ds_read_b128 v[8:11], v17 offset:2048
	ds_read_b128 v[12:15], v17 offset:2064
	s_waitcnt lgkmcnt(11)
	v_mul_f32_e64 v72, -v24, v92
	ds_read_b128 v[24:27], v17 offset:2304
	v_add_f32_e32 v93, v93, v72
	s_waitcnt lgkmcnt(11)
	v_mul_f32_e64 v72, -v28, v92
	v_mul_f32_e64 v73, -v29, v93
	ds_read_b128 v[28:31], v17 offset:2320
	v_add_f32_e32 v72, v72, v73
	v_add_f32_e32 v94, v94, v72
	s_waitcnt lgkmcnt(11)
	v_mul_f32_e64 v72, -v32, v92
	v_mul_f32_e64 v73, -v33, v93
	v_mul_f32_e64 v74, -v34, v94
	ds_read_b128 v[32:35], v17 offset:2336
	v_add_f32_e32 v72, v72, v73
	v_add_f32_e32 v95, v95, v74
	v_add_f32_e32 v95, v95, v72
	s_waitcnt lgkmcnt(11)
	v_mul_f32_e64 v72, -v36, v92
	v_mul_f32_e64 v73, -v37, v93
	v_mul_f32_e64 v74, -v38, v94
	v_mul_f32_e64 v75, -v39, v95
	ds_read_b128 v[36:39], v17 offset:2560
	v_add_f32_e32 v72, v72, v73
	v_add_f32_e32 v74, v74, v75
	v_add_f32_e32 v96, v96, v72
	v_add_f32_e32 v96, v96, v74
	s_waitcnt lgkmcnt(11)
	v_mul_f32_e64 v72, -v40, v92
	v_mul_f32_e64 v73, -v41, v93
	v_mul_f32_e64 v74, -v42, v94
	v_mul_f32_e64 v75, -v43, v95
	ds_read_b128 v[40:43], v17 offset:2576
	s_waitcnt lgkmcnt(11)
	v_fma_f32 v72, -v44, v96, v72
	ds_read_b128 v[44:47], v17 offset:2592
	v_add_f32_e32 v72, v72, v73
	v_add_f32_e32 v74, v74, v75
	v_add_f32_e32 v97, v97, v72
	v_add_f32_e32 v97, v97, v74
	s_waitcnt lgkmcnt(11)
	v_mul_f32_e64 v72, -v48, v92
	v_mul_f32_e64 v73, -v49, v93
	v_mul_f32_e64 v74, -v50, v94
	v_mul_f32_e64 v75, -v51, v95
	ds_read_b128 v[48:51], v17 offset:2816
	s_waitcnt lgkmcnt(11)
	v_fma_f32 v72, -v52, v96, v72
	v_fma_f32 v73, -v53, v97, v73
	ds_read_b128 v[52:55], v17 offset:2832
	v_add_f32_e32 v72, v72, v73
	v_add_f32_e32 v74, v74, v75
	v_add_f32_e32 v98, v98, v72
	v_add_f32_e32 v98, v98, v74
	s_waitcnt lgkmcnt(11)
	v_mul_f32_e64 v72, -v56, v92
	v_mul_f32_e64 v73, -v57, v93
	v_mul_f32_e64 v74, -v58, v94
	v_mul_f32_e64 v75, -v59, v95
	ds_read_b128 v[56:59], v17 offset:2848
	s_waitcnt lgkmcnt(11)
	v_fma_f32 v72, -v4, v96, v72
	v_fma_f32 v73, -v5, v97, v73
	v_fma_f32 v74, -v6, v98, v74
	ds_read_b128 v[4:7], v17 offset:3072
	v_add_f32_e32 v72, v72, v73
	v_add_f32_e32 v74, v74, v75
	v_add_f32_e32 v99, v99, v72
	v_add_f32_e32 v99, v99, v74
	s_waitcnt lgkmcnt(11)
	v_mul_f32_e64 v72, -v8, v92
	v_mul_f32_e64 v73, -v9, v93
	v_mul_f32_e64 v74, -v10, v94
	v_mul_f32_e64 v75, -v11, v95
	ds_read_b128 v[8:11], v17 offset:3088
	s_waitcnt lgkmcnt(11)
	v_fma_f32 v72, -v12, v96, v72
	v_fma_f32 v73, -v13, v97, v73
	v_fma_f32 v74, -v14, v98, v74
	v_fma_f32 v75, -v15, v99, v75
	ds_read_b128 v[12:15], v17 offset:3104
	v_add_f32_e32 v72, v72, v73
	v_add_f32_e32 v74, v74, v75
	v_add_f32_e32 v100, v100, v72
	v_add_f32_e32 v100, v100, v74
	s_waitcnt lgkmcnt(11)
	v_mul_f32_e64 v72, -v24, v92
	v_mul_f32_e64 v73, -v25, v93
	v_mul_f32_e64 v74, -v26, v94
	v_mul_f32_e64 v75, -v27, v95
	ds_read_b128 v[24:27], v17 offset:3328
	s_waitcnt lgkmcnt(11)
	v_fma_f32 v72, -v28, v96, v72
	v_fma_f32 v73, -v29, v97, v73
	v_fma_f32 v74, -v30, v98, v74
	v_fma_f32 v75, -v31, v99, v75
	ds_read_b128 v[28:31], v17 offset:3344
	s_waitcnt lgkmcnt(11)
; #define LAS __attribute__((address_space(3)))
; __device__ __forceinline__ void even_prep(const Ctx& c, const Params& p, int e) {
;     ...
; #pragma unroll
;             for (int i = 1; i < 64; ++i) { const LAS f32x4* Lr = (const LAS f32x4*)(Lv + i * 64); float a0 = x[i], a1 = 0.f;
; #pragma unroll
;                 for (int j4 = 0; j4 < (i + 3) / 4; ++j4) { const f32x4 l = Lr[j4];
;                     if (4 * j4 + 0 < i) a0 -= l[0] * x[4 * j4 + 0];
;                     if (4 * j4 + 1 < i) a1 -= l[1] * x[4 * j4 + 1];
;                     if (4 * j4 + 2 < i) a0 -= l[2] * x[4 * j4 + 2];
;                     if (4 * j4 + 3 < i) a1 -= l[3] * x[4 * j4 + 3]; }
;                 x[i] = a0 + a1; }
	v_fma_f32 v72, -v32, v100, v72
	ds_read_b128 v[32:35], v17 offset:3360
	v_add_f32_e32 v72, v72, v73
	v_add_f32_e32 v74, v74, v75
	v_add_f32_e32 v101, v101, v72
	v_add_f32_e32 v101, v101, v74
	s_waitcnt lgkmcnt(11)
	v_mul_f32_e64 v72, -v36, v92
	v_mul_f32_e64 v73, -v37, v93
	v_mul_f32_e64 v74, -v38, v94
	v_mul_f32_e64 v75, -v39, v95
	ds_read_b128 v[36:39], v17 offset:3376
	s_waitcnt lgkmcnt(11)
	v_fma_f32 v72, -v40, v96, v72
	v_fma_f32 v73, -v41, v97, v73
	v_fma_f32 v74, -v42, v98, v74
	v_fma_f32 v75, -v43, v99, v75
	ds_read_b128 v[40:43], v17 offset:3584
	s_waitcnt lgkmcnt(11)
	v_fma_f32 v72, -v44, v100, v72
	v_fma_f32 v73, -v45, v101, v73
	ds_read_b128 v[44:47], v17 offset:3600
	v_add_f32_e32 v72, v72, v73
	v_add_f32_e32 v74, v74, v75
	v_add_f32_e32 v102, v102, v72
	v_add_f32_e32 v102, v102, v74
	s_waitcnt lgkmcnt(11)
	v_mul_f32_e64 v72, -v48, v92
	v_mul_f32_e64 v73, -v49, v93
	v_mul_f32_e64 v74, -v50, v94
	v_mul_f32_e64 v75, -v51, v95
	ds_read_b128 v[48:51], v17 offset:3616
	s_waitcnt lgkmcnt(11)
	v_fma_f32 v72, -v52, v96, v72
	v_fma_f32 v73, -v53, v97, v73
	v_fma_f32 v74, -v54, v98, v74
	v_fma_f32 v75, -v55, v99, v75
	ds_read_b128 v[52:55], v17 offset:3632
	s_waitcnt lgkmcnt(11)
	v_fma_f32 v72, -v56, v100, v72
	v_fma_f32 v73, -v57, v101, v73
	v_fma_f32 v74, -v58, v102, v74
	ds_read_b128 v[56:59], v17 offset:3840
	v_add_f32_e32 v72, v72, v73
	v_add_f32_e32 v74, v74, v75
	v_add_f32_e32 v103, v103, v72
	v_add_f32_e32 v103, v103, v74
	s_waitcnt lgkmcnt(11)
	v_mul_f32_e64 v72, -v4, v92
	v_mul_f32_e64 v73, -v5, v93
	v_mul_f32_e64 v74, -v6, v94
	v_mul_f32_e64 v75, -v7, v95
	ds_read_b128 v[4:7], v17 offset:3856
	s_waitcnt lgkmcnt(11)
	v_fma_f32 v72, -v8, v96, v72
	v_fma_f32 v73, -v9, v97, v73
	v_fma_f32 v74, -v10, v98, v74
	v_fma_f32 v75, -v11, v99, v75
	ds_read_b128 v[8:11], v17 offset:3872
	s_waitcnt lgkmcnt(11)
	v_fma_f32 v72, -v12, v100, v72
	v_fma_f32 v73, -v13, v101, v73
	v_fma_f32 v74, -v14, v102, v74
	v_fma_f32 v75, -v15, v103, v75
	ds_read_b128 v[12:15], v17 offset:3888
	v_add_f32_e32 v72, v72, v73
	v_add_f32_e32 v74, v74, v75
	v_add_f32_e32 v104, v104, v72
	v_add_f32_e32 v104, v104, v74
	s_waitcnt lgkmcnt(11)
	v_mul_f32_e64 v72, -v24, v92
	v_mul_f32_e64 v73, -v25, v93
	v_mul_f32_e64 v74, -v26, v94
	v_mul_f32_e64 v75, -v27, v95
	ds_read_b128 v[24:27], v17 offset:4096
	s_waitcnt lgkmcnt(11)
	v_fma_f32 v72, -v28, v96, v72
	v_fma_f32 v73, -v29, v97, v73
	v_fma_f32 v74, -v30, v98, v74
	v_fma_f32 v75, -v31, v99, v75
	ds_read_b128 v[28:31], v17 offset:4112
	s_waitcnt lgkmcnt(11)
	v_fma_f32 v72, -v32, v100, v72
	v_fma_f32 v73, -v33, v101, v73
	v_fma_f32 v74, -v34, v102, v74
	v_fma_f32 v75, -v35, v103, v75
	ds_read_b128 v[32:35], v17 offset:4128
	s_waitcnt lgkmcnt(11)
	v_fma_f32 v72, -v36, v104, v72
	ds_read_b128 v[36:39], v17 offset:4144
	v_add_f32_e32 v72, v72, v73
	v_add_f32_e32 v74, v74, v75
	v_add_f32_e32 v105, v105, v72
	v_add_f32_e32 v105, v105, v74
	s_waitcnt lgkmcnt(11)
	v_mul_f32_e64 v72, -v40, v92
	v_mul_f32_e64 v73, -v41, v93
	v_mul_f32_e64 v74, -v42, v94
	v_mul_f32_e64 v75, -v43, v95
	ds_read_b128 v[40:43], v17 offset:4352
	s_waitcnt lgkmcnt(11)
	v_fma_f32 v72, -v44, v96, v72
	v_fma_f32 v73, -v45, v97, v73
	v_fma_f32 v74, -v46, v98, v74
	v_fma_f32 v75, -v47, v99, v75
	ds_read_b128 v[44:47], v17 offset:4368
	s_waitcnt lgkmcnt(11)
	v_fma_f32 v72, -v48, v100, v72
	v_fma_f32 v73, -v49, v101, v73
	v_fma_f32 v74, -v50, v102, v74
	v_fma_f32 v75, -v51, v103, v75
	ds_read_b128 v[48:51], v17 offset:4384
	s_waitcnt lgkmcnt(11)
	v_fma_f32 v72, -v52, v104, v72
	v_fma_f32 v73, -v53, v105, v73
	ds_read_b128 v[52:55], v17 offset:4400
	v_add_f32_e32 v72, v72, v73
	v_add_f32_e32 v74, v74, v75
	v_add_f32_e32 v106, v106, v72
	v_add_f32_e32 v106, v106, v74
	s_waitcnt lgkmcnt(11)
	v_mul_f32_e64 v72, -v56, v92
	v_mul_f32_e64 v73, -v57, v93
	v_mul_f32_e64 v74, -v58, v94
	v_mul_f32_e64 v75, -v59, v95
	ds_read_b128 v[56:59], v17 offset:4416
	s_waitcnt lgkmcnt(11)
	v_fma_f32 v72, -v4, v96, v72
	v_fma_f32 v73, -v5, v97, v73
	v_fma_f32 v74, -v6, v98, v74
	v_fma_f32 v75, -v7, v99, v75
	ds_read_b128 v[4:7], v17 offset:4608
	s_waitcnt lgkmcnt(11)
	v_fma_f32 v72, -v8, v100, v72
	v_fma_f32 v73, -v9, v101, v73
	v_fma_f32 v74, -v10, v102, v74
	v_fma_f32 v75, -v11, v103, v75
	ds_read_b128 v[8:11], v17 offset:4624
	s_waitcnt lgkmcnt(11)
	v_fma_f32 v72, -v12, v104, v72
	v_fma_f32 v73, -v13, v105, v73
	v_fma_f32 v74, -v14, v106, v74
	ds_read_b128 v[12:15], v17 offset:4640
	v_add_f32_e32 v72, v72, v73
	v_add_f32_e32 v74, v74, v75
	v_add_f32_e32 v107, v107, v72
	v_add_f32_e32 v107, v107, v74
	s_waitcnt lgkmcnt(11)
	v_mul_f32_e64 v72, -v24, v92
	v_mul_f32_e64 v73, -v25, v93
	v_mul_f32_e64 v74, -v26, v94
	v_mul_f32_e64 v75, -v27, v95
	ds_read_b128 v[24:27], v17 offset:4656
	s_waitcnt lgkmcnt(11)
	v_fma_f32 v72, -v28, v96, v72
	v_fma_f32 v73, -v29, v97, v73
	v_fma_f32 v74, -v30, v98, v74
	v_fma_f32 v75, -v31, v99, v75
	ds_read_b128 v[28:31], v17 offset:4672
	s_waitcnt lgkmcnt(11)
	v_fma_f32 v72, -v32, v100, v72
	v_fma_f32 v73, -v33, v101, v73
	v_fma_f32 v74, -v34, v102, v74
	v_fma_f32 v75, -v35, v103, v75
	ds_read_b128 v[32:35], v17 offset:4864
	s_waitcnt lgkmcnt(11)
	v_fma_f32 v72, -v36, v104, v72
	v_fma_f32 v73, -v37, v105, v73
	v_fma_f32 v74, -v38, v106, v74
	v_fma_f32 v75, -v39, v107, v75
	ds_read_b128 v[36:39], v17 offset:4880
	v_add_f32_e32 v72, v72, v73
	v_add_f32_e32 v74, v74, v75
	v_add_f32_e32 v108, v108, v72
	v_add_f32_e32 v108, v108, v74
	s_waitcnt lgkmcnt(11)
	v_mul_f32_e64 v72, -v40, v92
	v_mul_f32_e64 v73, -v41, v93
	v_mul_f32_e64 v74, -v42, v94
	v_mul_f32_e64 v75, -v43, v95
	ds_read_b128 v[40:43], v17 offset:4896
	s_waitcnt lgkmcnt(11)
; #define LAS __attribute__((address_space(3)))
; __device__ __forceinline__ void even_prep(const Ctx& c, const Params& p, int e) {
;     ...
; #pragma unroll
;             for (int i = 1; i < 64; ++i) { const LAS f32x4* Lr = (const LAS f32x4*)(Lv + i * 64); float a0 = x[i], a1 = 0.f;
; #pragma unroll
;                 for (int j4 = 0; j4 < (i + 3) / 4; ++j4) { const f32x4 l = Lr[j4];
;                     if (4 * j4 + 0 < i) a0 -= l[0] * x[4 * j4 + 0];
;                     if (4 * j4 + 1 < i) a1 -= l[1] * x[4 * j4 + 1];
;                     if (4 * j4 + 2 < i) a0 -= l[2] * x[4 * j4 + 2];
;                     if (4 * j4 + 3 < i) a1 -= l[3] * x[4 * j4 + 3]; }
;                 x[i] = a0 + a1; }
	v_fma_f32 v72, -v44, v96, v72
	v_fma_f32 v73, -v45, v97, v73
	v_fma_f32 v74, -v46, v98, v74
	v_fma_f32 v75, -v47, v99, v75
	ds_read_b128 v[44:47], v17 offset:4912
	s_waitcnt lgkmcnt(11)
	v_fma_f32 v72, -v48, v100, v72
	v_fma_f32 v73, -v49, v101, v73
	v_fma_f32 v74, -v50, v102, v74
	v_fma_f32 v75, -v51, v103, v75
	ds_read_b128 v[48:51], v17 offset:4928
	s_waitcnt lgkmcnt(11)
	v_fma_f32 v72, -v52, v104, v72
	v_fma_f32 v73, -v53, v105, v73
	v_fma_f32 v74, -v54, v106, v74
	v_fma_f32 v75, -v55, v107, v75
	ds_read_b128 v[52:55], v17 offset:5120
	s_waitcnt lgkmcnt(11)
	v_fma_f32 v72, -v56, v108, v72
	ds_read_b128 v[56:59], v17 offset:5136
	v_add_f32_e32 v72, v72, v73
	v_add_f32_e32 v74, v74, v75
	v_add_f32_e32 v109, v109, v72
	v_add_f32_e32 v109, v109, v74
	s_waitcnt lgkmcnt(11)
	v_mul_f32_e64 v72, -v4, v92
	v_mul_f32_e64 v73, -v5, v93
	v_mul_f32_e64 v74, -v6, v94
	v_mul_f32_e64 v75, -v7, v95
	ds_read_b128 v[4:7], v17 offset:5152
	s_waitcnt lgkmcnt(11)
	v_fma_f32 v72, -v8, v96, v72
	v_fma_f32 v73, -v9, v97, v73
	v_fma_f32 v74, -v10, v98, v74
	v_fma_f32 v75, -v11, v99, v75
	ds_read_b128 v[8:11], v17 offset:5168
	s_waitcnt lgkmcnt(11)
	v_fma_f32 v72, -v12, v100, v72
	v_fma_f32 v73, -v13, v101, v73
	v_fma_f32 v74, -v14, v102, v74
	v_fma_f32 v75, -v15, v103, v75
	ds_read_b128 v[12:15], v17 offset:5184
	s_waitcnt lgkmcnt(11)
	v_fma_f32 v72, -v24, v104, v72
	v_fma_f32 v73, -v25, v105, v73
	v_fma_f32 v74, -v26, v106, v74
	v_fma_f32 v75, -v27, v107, v75
	ds_read_b128 v[24:27], v17 offset:5376
	s_waitcnt lgkmcnt(11)
	v_fma_f32 v72, -v28, v108, v72
	v_fma_f32 v73, -v29, v109, v73
	ds_read_b128 v[28:31], v17 offset:5392
	v_add_f32_e32 v72, v72, v73
	v_add_f32_e32 v74, v74, v75
	v_add_f32_e32 v110, v110, v72
	v_add_f32_e32 v110, v110, v74
	s_waitcnt lgkmcnt(11)
	v_mul_f32_e64 v72, -v32, v92
	v_mul_f32_e64 v73, -v33, v93
	v_mul_f32_e64 v74, -v34, v94
	v_mul_f32_e64 v75, -v35, v95
	ds_read_b128 v[32:35], v17 offset:5408
	s_waitcnt lgkmcnt(11)
	v_fma_f32 v72, -v36, v96, v72
	v_fma_f32 v73, -v37, v97, v73
	v_fma_f32 v74, -v38, v98, v74
	v_fma_f32 v75, -v39, v99, v75
	ds_read_b128 v[36:39], v17 offset:5424
	s_waitcnt lgkmcnt(11)
	v_fma_f32 v72, -v40, v100, v72
	v_fma_f32 v73, -v41, v101, v73
	v_fma_f32 v74, -v42, v102, v74
	v_fma_f32 v75, -v43, v103, v75
	ds_read_b128 v[40:43], v17 offset:5440
	s_waitcnt lgkmcnt(11)
	v_fma_f32 v72, -v44, v104, v72
	v_fma_f32 v73, -v45, v105, v73
	v_fma_f32 v74, -v46, v106, v74
	v_fma_f32 v75, -v47, v107, v75
	ds_read_b128 v[44:47], v17 offset:5456
	s_waitcnt lgkmcnt(11)
	v_fma_f32 v72, -v48, v108, v72
	v_fma_f32 v73, -v49, v109, v73
	v_fma_f32 v74, -v50, v110, v74
	ds_read_b128 v[48:51], v17 offset:5632
	v_add_f32_e32 v72, v72, v73
	v_add_f32_e32 v74, v74, v75
	v_add_f32_e32 v111, v111, v72
	v_add_f32_e32 v111, v111, v74
	s_waitcnt lgkmcnt(11)
	v_mul_f32_e64 v72, -v52, v92
	v_mul_f32_e64 v73, -v53, v93
	v_mul_f32_e64 v74, -v54, v94
	v_mul_f32_e64 v75, -v55, v95
	ds_read_b128 v[52:55], v17 offset:5648
	s_waitcnt lgkmcnt(11)
	v_fma_f32 v72, -v56, v96, v72
	v_fma_f32 v73, -v57, v97, v73
	v_fma_f32 v74, -v58, v98, v74
	v_fma_f32 v75, -v59, v99, v75
	ds_read_b128 v[56:59], v17 offset:5664
	s_waitcnt lgkmcnt(11)
	v_fma_f32 v72, -v4, v100, v72
	v_fma_f32 v73, -v5, v101, v73
	v_fma_f32 v74, -v6, v102, v74
	v_fma_f32 v75, -v7, v103, v75
	ds_read_b128 v[4:7], v17 offset:5680
	s_waitcnt lgkmcnt(11)
	v_fma_f32 v72, -v8, v104, v72
	v_fma_f32 v73, -v9, v105, v73
	v_fma_f32 v74, -v10, v106, v74
	v_fma_f32 v75, -v11, v107, v75
	ds_read_b128 v[8:11], v17 offset:5696
	s_waitcnt lgkmcnt(11)
	v_fma_f32 v72, -v12, v108, v72
	v_fma_f32 v73, -v13, v109, v73
	v_fma_f32 v74, -v14, v110, v74
	v_fma_f32 v75, -v15, v111, v75
	ds_read_b128 v[12:15], v17 offset:5712
	v_add_f32_e32 v72, v72, v73
	v_add_f32_e32 v74, v74, v75
	v_add_f32_e32 v112, v112, v72
	v_add_f32_e32 v112, v112, v74
	s_waitcnt lgkmcnt(11)
	v_mul_f32_e64 v72, -v24, v92
	v_mul_f32_e64 v73, -v25, v93
	v_mul_f32_e64 v74, -v26, v94
	v_mul_f32_e64 v75, -v27, v95
	ds_read_b128 v[24:27], v17 offset:5888
	s_waitcnt lgkmcnt(11)
	v_fma_f32 v72, -v28, v96, v72
	v_fma_f32 v73, -v29, v97, v73
	v_fma_f32 v74, -v30, v98, v74
	v_fma_f32 v75, -v31, v99, v75
	ds_read_b128 v[28:31], v17 offset:5904
	s_waitcnt lgkmcnt(11)
	v_fma_f32 v72, -v32, v100, v72
	v_fma_f32 v73, -v33, v101, v73
	v_fma_f32 v74, -v34, v102, v74
	v_fma_f32 v75, -v35, v103, v75
	ds_read_b128 v[32:35], v17 offset:5920
	s_waitcnt lgkmcnt(11)
	v_fma_f32 v72, -v36, v104, v72
	v_fma_f32 v73, -v37, v105, v73
	v_fma_f32 v74, -v38, v106, v74
	v_fma_f32 v75, -v39, v107, v75
	ds_read_b128 v[36:39], v17 offset:5936
	s_waitcnt lgkmcnt(11)
	v_fma_f32 v72, -v40, v108, v72
	v_fma_f32 v73, -v41, v109, v73
	v_fma_f32 v74, -v42, v110, v74
	v_fma_f32 v75, -v43, v111, v75
	ds_read_b128 v[40:43], v17 offset:5952
	s_waitcnt lgkmcnt(11)
	v_fma_f32 v72, -v44, v112, v72
	ds_read_b128 v[44:47], v17 offset:5968
	v_add_f32_e32 v72, v72, v73
	v_add_f32_e32 v74, v74, v75
	v_add_f32_e32 v113, v113, v72
	v_add_f32_e32 v113, v113, v74
	s_waitcnt lgkmcnt(11)
	v_mul_f32_e64 v72, -v48, v92
	v_mul_f32_e64 v73, -v49, v93
	v_mul_f32_e64 v74, -v50, v94
	v_mul_f32_e64 v75, -v51, v95
	ds_read_b128 v[48:51], v17 offset:6144
	s_waitcnt lgkmcnt(11)
	v_fma_f32 v72, -v52, v96, v72
	v_fma_f32 v73, -v53, v97, v73
	v_fma_f32 v74, -v54, v98, v74
	v_fma_f32 v75, -v55, v99, v75
	ds_read_b128 v[52:55], v17 offset:6160
	s_waitcnt lgkmcnt(11)
	v_fma_f32 v72, -v56, v100, v72
	v_fma_f32 v73, -v57, v101, v73
	v_fma_f32 v74, -v58, v102, v74
	v_fma_f32 v75, -v59, v103, v75
	ds_read_b128 v[56:59], v17 offset:6176
	s_waitcnt lgkmcnt(11)
; #define LAS __attribute__((address_space(3)))
; __device__ __forceinline__ void even_prep(const Ctx& c, const Params& p, int e) {
;     ...
; #pragma unroll
;             for (int i = 1; i < 64; ++i) { const LAS f32x4* Lr = (const LAS f32x4*)(Lv + i * 64); float a0 = x[i], a1 = 0.f;
; #pragma unroll
;                 for (int j4 = 0; j4 < (i + 3) / 4; ++j4) { const f32x4 l = Lr[j4];
;                     if (4 * j4 + 0 < i) a0 -= l[0] * x[4 * j4 + 0];
;                     if (4 * j4 + 1 < i) a1 -= l[1] * x[4 * j4 + 1];
;                     if (4 * j4 + 2 < i) a0 -= l[2] * x[4 * j4 + 2];
;                     if (4 * j4 + 3 < i) a1 -= l[3] * x[4 * j4 + 3]; }
;                 x[i] = a0 + a1; }
	v_fma_f32 v72, -v4, v104, v72
	v_fma_f32 v73, -v5, v105, v73
	v_fma_f32 v74, -v6, v106, v74
	v_fma_f32 v75, -v7, v107, v75
	ds_read_b128 v[4:7], v17 offset:6192
	s_waitcnt lgkmcnt(11)
	v_fma_f32 v72, -v8, v108, v72
	v_fma_f32 v73, -v9, v109, v73
	v_fma_f32 v74, -v10, v110, v74
	v_fma_f32 v75, -v11, v111, v75
	ds_read_b128 v[8:11], v17 offset:6208
	s_waitcnt lgkmcnt(11)
	v_fma_f32 v72, -v12, v112, v72
	v_fma_f32 v73, -v13, v113, v73
	ds_read_b128 v[12:15], v17 offset:6224
	v_add_f32_e32 v72, v72, v73
	v_add_f32_e32 v74, v74, v75
	v_add_f32_e32 v114, v114, v72
	v_add_f32_e32 v114, v114, v74
	s_waitcnt lgkmcnt(11)
	v_mul_f32_e64 v72, -v24, v92
	v_mul_f32_e64 v73, -v25, v93
	v_mul_f32_e64 v74, -v26, v94
	v_mul_f32_e64 v75, -v27, v95
	ds_read_b128 v[24:27], v17 offset:6400
	s_waitcnt lgkmcnt(11)
	v_fma_f32 v72, -v28, v96, v72
	v_fma_f32 v73, -v29, v97, v73
	v_fma_f32 v74, -v30, v98, v74
	v_fma_f32 v75, -v31, v99, v75
	ds_read_b128 v[28:31], v17 offset:6416
	s_waitcnt lgkmcnt(11)
	v_fma_f32 v72, -v32, v100, v72
	v_fma_f32 v73, -v33, v101, v73
	v_fma_f32 v74, -v34, v102, v74
	v_fma_f32 v75, -v35, v103, v75
	ds_read_b128 v[32:35], v17 offset:6432
	s_waitcnt lgkmcnt(11)
	v_fma_f32 v72, -v36, v104, v72
	v_fma_f32 v73, -v37, v105, v73
	v_fma_f32 v74, -v38, v106, v74
	v_fma_f32 v75, -v39, v107, v75
	ds_read_b128 v[36:39], v17 offset:6448
	s_waitcnt lgkmcnt(11)
	v_fma_f32 v72, -v40, v108, v72
	v_fma_f32 v73, -v41, v109, v73
	v_fma_f32 v74, -v42, v110, v74
	v_fma_f32 v75, -v43, v111, v75
	ds_read_b128 v[40:43], v17 offset:6464
	s_waitcnt lgkmcnt(11)
	v_fma_f32 v72, -v44, v112, v72
	v_fma_f32 v73, -v45, v113, v73
	v_fma_f32 v74, -v46, v114, v74
	ds_read_b128 v[44:47], v17 offset:6480
	v_add_f32_e32 v72, v72, v73
	v_add_f32_e32 v74, v74, v75
	v_add_f32_e32 v115, v115, v72
	v_add_f32_e32 v115, v115, v74
	s_waitcnt lgkmcnt(11)
	v_mul_f32_e64 v72, -v48, v92
	v_mul_f32_e64 v73, -v49, v93
	v_mul_f32_e64 v74, -v50, v94
	v_mul_f32_e64 v75, -v51, v95
	ds_read_b128 v[48:51], v17 offset:6496
	s_waitcnt lgkmcnt(11)
	v_fma_f32 v72, -v52, v96, v72
	v_fma_f32 v73, -v53, v97, v73
	v_fma_f32 v74, -v54, v98, v74
	v_fma_f32 v75, -v55, v99, v75
	ds_read_b128 v[52:55], v17 offset:6656
	s_waitcnt lgkmcnt(11)
	v_fma_f32 v72, -v56, v100, v72
	v_fma_f32 v73, -v57, v101, v73
	v_fma_f32 v74, -v58, v102, v74
	v_fma_f32 v75, -v59, v103, v75
	ds_read_b128 v[56:59], v17 offset:6672
	s_waitcnt lgkmcnt(11)
	v_fma_f32 v72, -v4, v104, v72
	v_fma_f32 v73, -v5, v105, v73
	v_fma_f32 v74, -v6, v106, v74
	v_fma_f32 v75, -v7, v107, v75
	ds_read_b128 v[4:7], v17 offset:6688
	s_waitcnt lgkmcnt(11)
	v_fma_f32 v72, -v8, v108, v72
	v_fma_f32 v73, -v9, v109, v73
	v_fma_f32 v74, -v10, v110, v74
	v_fma_f32 v75, -v11, v111, v75
	ds_read_b128 v[8:11], v17 offset:6704
	s_waitcnt lgkmcnt(11)
	v_fma_f32 v72, -v12, v112, v72
	v_fma_f32 v73, -v13, v113, v73
	v_fma_f32 v74, -v14, v114, v74
	v_fma_f32 v75, -v15, v115, v75
	ds_read_b128 v[12:15], v17 offset:6720
	v_add_f32_e32 v72, v72, v73
	v_add_f32_e32 v74, v74, v75
	v_add_f32_e32 v116, v116, v72
	v_add_f32_e32 v116, v116, v74
	s_waitcnt lgkmcnt(11)
	v_mul_f32_e64 v72, -v24, v92
	v_mul_f32_e64 v73, -v25, v93
	v_mul_f32_e64 v74, -v26, v94
	v_mul_f32_e64 v75, -v27, v95
	ds_read_b128 v[24:27], v17 offset:6736
	s_waitcnt lgkmcnt(11)
	v_fma_f32 v72, -v28, v96, v72
	v_fma_f32 v73, -v29, v97, v73
	v_fma_f32 v74, -v30, v98, v74
	v_fma_f32 v75, -v31, v99, v75
	ds_read_b128 v[28:31], v17 offset:6752
	s_waitcnt lgkmcnt(11)
	v_fma_f32 v72, -v32, v100, v72
	v_fma_f32 v73, -v33, v101, v73
	v_fma_f32 v74, -v34, v102, v74
	v_fma_f32 v75, -v35, v103, v75
	ds_read_b128 v[32:35], v17 offset:6912
	s_waitcnt lgkmcnt(11)
	v_fma_f32 v72, -v36, v104, v72
	v_fma_f32 v73, -v37, v105, v73
	v_fma_f32 v74, -v38, v106, v74
	v_fma_f32 v75, -v39, v107, v75
	ds_read_b128 v[36:39], v17 offset:6928
	s_waitcnt lgkmcnt(11)
	v_fma_f32 v72, -v40, v108, v72
	v_fma_f32 v73, -v41, v109, v73
	v_fma_f32 v74, -v42, v110, v74
	v_fma_f32 v75, -v43, v111, v75
	ds_read_b128 v[40:43], v17 offset:6944
	s_waitcnt lgkmcnt(11)
	v_fma_f32 v72, -v44, v112, v72
	v_fma_f32 v73, -v45, v113, v73
	v_fma_f32 v74, -v46, v114, v74
	v_fma_f32 v75, -v47, v115, v75
	ds_read_b128 v[44:47], v17 offset:6960
	s_waitcnt lgkmcnt(11)
	v_fma_f32 v72, -v48, v116, v72
	ds_read_b128 v[48:51], v17 offset:6976
	v_add_f32_e32 v72, v72, v73
	v_add_f32_e32 v74, v74, v75
	v_add_f32_e32 v117, v117, v72
	v_add_f32_e32 v117, v117, v74
	s_waitcnt lgkmcnt(11)
	v_mul_f32_e64 v72, -v52, v92
	v_mul_f32_e64 v73, -v53, v93
	v_mul_f32_e64 v74, -v54, v94
	v_mul_f32_e64 v75, -v55, v95
	ds_read_b128 v[52:55], v17 offset:6992
	s_waitcnt lgkmcnt(11)
	v_fma_f32 v72, -v56, v96, v72
	v_fma_f32 v73, -v57, v97, v73
	v_fma_f32 v74, -v58, v98, v74
	v_fma_f32 v75, -v59, v99, v75
	ds_read_b128 v[56:59], v17 offset:7008
	s_waitcnt lgkmcnt(11)
	v_fma_f32 v72, -v4, v100, v72
	v_fma_f32 v73, -v5, v101, v73
	v_fma_f32 v74, -v6, v102, v74
	v_fma_f32 v75, -v7, v103, v75
	ds_read_b128 v[4:7], v17 offset:7168
	s_waitcnt lgkmcnt(11)
	v_fma_f32 v72, -v8, v104, v72
	v_fma_f32 v73, -v9, v105, v73
	v_fma_f32 v74, -v10, v106, v74
	v_fma_f32 v75, -v11, v107, v75
	ds_read_b128 v[8:11], v17 offset:7184
	s_waitcnt lgkmcnt(11)
	v_fma_f32 v72, -v12, v108, v72
	v_fma_f32 v73, -v13, v109, v73
	v_fma_f32 v74, -v14, v110, v74
	v_fma_f32 v75, -v15, v111, v75
	ds_read_b128 v[12:15], v17 offset:7200
	s_waitcnt lgkmcnt(11)
	v_fma_f32 v72, -v24, v112, v72
	v_fma_f32 v73, -v25, v113, v73
	v_fma_f32 v74, -v26, v114, v74
	v_fma_f32 v75, -v27, v115, v75
	ds_read_b128 v[24:27], v17 offset:7216
	s_waitcnt lgkmcnt(11)
; #define LAS __attribute__((address_space(3)))
; __device__ __forceinline__ void even_prep(const Ctx& c, const Params& p, int e) {
;     ...
; #pragma unroll
;             for (int i = 1; i < 64; ++i) { const LAS f32x4* Lr = (const LAS f32x4*)(Lv + i * 64); float a0 = x[i], a1 = 0.f;
; #pragma unroll
;                 for (int j4 = 0; j4 < (i + 3) / 4; ++j4) { const f32x4 l = Lr[j4];
;                     if (4 * j4 + 0 < i) a0 -= l[0] * x[4 * j4 + 0];
;                     if (4 * j4 + 1 < i) a1 -= l[1] * x[4 * j4 + 1];
;                     if (4 * j4 + 2 < i) a0 -= l[2] * x[4 * j4 + 2];
;                     if (4 * j4 + 3 < i) a1 -= l[3] * x[4 * j4 + 3]; }
;                 x[i] = a0 + a1; }
	v_fma_f32 v72, -v28, v116, v72
	v_fma_f32 v73, -v29, v117, v73
	ds_read_b128 v[28:31], v17 offset:7232
	v_add_f32_e32 v72, v72, v73
	v_add_f32_e32 v74, v74, v75
	v_add_f32_e32 v118, v118, v72
	v_add_f32_e32 v118, v118, v74
	s_waitcnt lgkmcnt(11)
	v_mul_f32_e64 v72, -v32, v92
	v_mul_f32_e64 v73, -v33, v93
	v_mul_f32_e64 v74, -v34, v94
	v_mul_f32_e64 v75, -v35, v95
	ds_read_b128 v[32:35], v17 offset:7248
	s_waitcnt lgkmcnt(11)
	v_fma_f32 v72, -v36, v96, v72
	v_fma_f32 v73, -v37, v97, v73
	v_fma_f32 v74, -v38, v98, v74
	v_fma_f32 v75, -v39, v99, v75
	ds_read_b128 v[36:39], v17 offset:7264
	s_waitcnt lgkmcnt(11)
	v_fma_f32 v72, -v40, v100, v72
	v_fma_f32 v73, -v41, v101, v73
	v_fma_f32 v74, -v42, v102, v74
	v_fma_f32 v75, -v43, v103, v75
	ds_read_b128 v[40:43], v17 offset:7424
	s_waitcnt lgkmcnt(11)
	v_fma_f32 v72, -v44, v104, v72
	v_fma_f32 v73, -v45, v105, v73
	v_fma_f32 v74, -v46, v106, v74
	v_fma_f32 v75, -v47, v107, v75
	ds_read_b128 v[44:47], v17 offset:7440
	s_waitcnt lgkmcnt(11)
	v_fma_f32 v72, -v48, v108, v72
	v_fma_f32 v73, -v49, v109, v73
	v_fma_f32 v74, -v50, v110, v74
	v_fma_f32 v75, -v51, v111, v75
	ds_read_b128 v[48:51], v17 offset:7456
	s_waitcnt lgkmcnt(11)
	v_fma_f32 v72, -v52, v112, v72
	v_fma_f32 v73, -v53, v113, v73
	v_fma_f32 v74, -v54, v114, v74
	v_fma_f32 v75, -v55, v115, v75
	ds_read_b128 v[52:55], v17 offset:7472
	s_waitcnt lgkmcnt(11)
	v_fma_f32 v72, -v56, v116, v72
	v_fma_f32 v73, -v57, v117, v73
	v_fma_f32 v74, -v58, v118, v74
	ds_read_b128 v[56:59], v17 offset:7488
	v_add_f32_e32 v72, v72, v73
	v_add_f32_e32 v74, v74, v75
	v_add_f32_e32 v119, v119, v72
	v_add_f32_e32 v119, v119, v74
	s_waitcnt lgkmcnt(11)
	v_mul_f32_e64 v72, -v4, v92
	v_mul_f32_e64 v73, -v5, v93
	v_mul_f32_e64 v74, -v6, v94
	v_mul_f32_e64 v75, -v7, v95
	ds_read_b128 v[4:7], v17 offset:7504
	s_waitcnt lgkmcnt(11)
	v_fma_f32 v72, -v8, v96, v72
	v_fma_f32 v73, -v9, v97, v73
	v_fma_f32 v74, -v10, v98, v74
	v_fma_f32 v75, -v11, v99, v75
	ds_read_b128 v[8:11], v17 offset:7520
	s_waitcnt lgkmcnt(11)
	v_fma_f32 v72, -v12, v100, v72
	v_fma_f32 v73, -v13, v101, v73
	v_fma_f32 v74, -v14, v102, v74
	v_fma_f32 v75, -v15, v103, v75
	ds_read_b128 v[12:15], v17 offset:7536
	s_waitcnt lgkmcnt(11)
	v_fma_f32 v72, -v24, v104, v72
	v_fma_f32 v73, -v25, v105, v73
	v_fma_f32 v74, -v26, v106, v74
	v_fma_f32 v75, -v27, v107, v75
	ds_read_b128 v[24:27], v17 offset:7680
	s_waitcnt lgkmcnt(11)
	v_fma_f32 v72, -v28, v108, v72
	v_fma_f32 v73, -v29, v109, v73
	v_fma_f32 v74, -v30, v110, v74
	v_fma_f32 v75, -v31, v111, v75
	ds_read_b128 v[28:31], v17 offset:7696
	s_waitcnt lgkmcnt(11)
	v_fma_f32 v72, -v32, v112, v72
	v_fma_f32 v73, -v33, v113, v73
	v_fma_f32 v74, -v34, v114, v74
	v_fma_f32 v75, -v35, v115, v75
	ds_read_b128 v[32:35], v17 offset:7712
	s_waitcnt lgkmcnt(11)
	v_fma_f32 v72, -v36, v116, v72
	v_fma_f32 v73, -v37, v117, v73
	v_fma_f32 v74, -v38, v118, v74
	v_fma_f32 v75, -v39, v119, v75
	ds_read_b128 v[36:39], v17 offset:7728
	v_add_f32_e32 v72, v72, v73
	v_add_f32_e32 v74, v74, v75
	v_add_f32_e32 v120, v120, v72
	v_add_f32_e32 v120, v120, v74
	s_waitcnt lgkmcnt(11)
	v_mul_f32_e64 v72, -v40, v92
	v_mul_f32_e64 v73, -v41, v93
	v_mul_f32_e64 v74, -v42, v94
	v_mul_f32_e64 v75, -v43, v95
	ds_read_b128 v[40:43], v17 offset:7744
	s_waitcnt lgkmcnt(11)
	v_fma_f32 v72, -v44, v96, v72
	v_fma_f32 v73, -v45, v97, v73
	v_fma_f32 v74, -v46, v98, v74
	v_fma_f32 v75, -v47, v99, v75
	ds_read_b128 v[44:47], v17 offset:7760
	s_waitcnt lgkmcnt(11)
	v_fma_f32 v72, -v48, v100, v72
	v_fma_f32 v73, -v49, v101, v73
	v_fma_f32 v74, -v50, v102, v74
	v_fma_f32 v75, -v51, v103, v75
	ds_read_b128 v[48:51], v17 offset:7776
	s_waitcnt lgkmcnt(11)
	v_fma_f32 v72, -v52, v104, v72
	v_fma_f32 v73, -v53, v105, v73
	v_fma_f32 v74, -v54, v106, v74
	v_fma_f32 v75, -v55, v107, v75
	ds_read_b128 v[52:55], v17 offset:7792
	s_waitcnt lgkmcnt(11)
	v_fma_f32 v72, -v56, v108, v72
	v_fma_f32 v73, -v57, v109, v73
	v_fma_f32 v74, -v58, v110, v74
	v_fma_f32 v75, -v59, v111, v75
	ds_read_b128 v[56:59], v17 offset:7936
	s_waitcnt lgkmcnt(11)
	v_fma_f32 v72, -v4, v112, v72
	v_fma_f32 v73, -v5, v113, v73
	v_fma_f32 v74, -v6, v114, v74
	v_fma_f32 v75, -v7, v115, v75
	ds_read_b128 v[4:7], v17 offset:7952
	s_waitcnt lgkmcnt(11)
	v_fma_f32 v72, -v8, v116, v72
	v_fma_f32 v73, -v9, v117, v73
	v_fma_f32 v74, -v10, v118, v74
	v_fma_f32 v75, -v11, v119, v75
	ds_read_b128 v[8:11], v17 offset:7968
	s_waitcnt lgkmcnt(11)
	v_fma_f32 v72, -v12, v120, v72
	ds_read_b128 v[12:15], v17 offset:7984
	v_add_f32_e32 v72, v72, v73
	v_add_f32_e32 v74, v74, v75
	v_add_f32_e32 v121, v121, v72
	v_add_f32_e32 v121, v121, v74
	s_waitcnt lgkmcnt(11)
	v_mul_f32_e64 v72, -v24, v92
	v_mul_f32_e64 v73, -v25, v93
	v_mul_f32_e64 v74, -v26, v94
	v_mul_f32_e64 v75, -v27, v95
	ds_read_b128 v[24:27], v17 offset:8000
	s_waitcnt lgkmcnt(11)
	v_fma_f32 v72, -v28, v96, v72
	v_fma_f32 v73, -v29, v97, v73
	v_fma_f32 v74, -v30, v98, v74
	v_fma_f32 v75, -v31, v99, v75
	ds_read_b128 v[28:31], v17 offset:8016
	s_waitcnt lgkmcnt(11)
	v_fma_f32 v72, -v32, v100, v72
	v_fma_f32 v73, -v33, v101, v73
	v_fma_f32 v74, -v34, v102, v74
	v_fma_f32 v75, -v35, v103, v75
	ds_read_b128 v[32:35], v17 offset:8032
	s_waitcnt lgkmcnt(11)
	v_fma_f32 v72, -v36, v104, v72
	v_fma_f32 v73, -v37, v105, v73
	v_fma_f32 v74, -v38, v106, v74
	v_fma_f32 v75, -v39, v107, v75
	ds_read_b128 v[36:39], v17 offset:8048
	s_waitcnt lgkmcnt(11)
	v_fma_f32 v72, -v40, v108, v72
	v_fma_f32 v73, -v41, v109, v73
	v_fma_f32 v74, -v42, v110, v74
	v_fma_f32 v75, -v43, v111, v75
	ds_read_b128 v[40:43], v17 offset:8192
	s_waitcnt lgkmcnt(11)
; #define LAS __attribute__((address_space(3)))
; __device__ __forceinline__ void even_prep(const Ctx& c, const Params& p, int e) {
;     ...
; #pragma unroll
;             for (int i = 1; i < 64; ++i) { const LAS f32x4* Lr = (const LAS f32x4*)(Lv + i * 64); float a0 = x[i], a1 = 0.f;
; #pragma unroll
;                 for (int j4 = 0; j4 < (i + 3) / 4; ++j4) { const f32x4 l = Lr[j4];
;                     if (4 * j4 + 0 < i) a0 -= l[0] * x[4 * j4 + 0];
;                     if (4 * j4 + 1 < i) a1 -= l[1] * x[4 * j4 + 1];
;                     if (4 * j4 + 2 < i) a0 -= l[2] * x[4 * j4 + 2];
;                     if (4 * j4 + 3 < i) a1 -= l[3] * x[4 * j4 + 3]; }
;                 x[i] = a0 + a1; }
	v_fma_f32 v72, -v44, v112, v72
	v_fma_f32 v73, -v45, v113, v73
	v_fma_f32 v74, -v46, v114, v74
	v_fma_f32 v75, -v47, v115, v75
	ds_read_b128 v[44:47], v17 offset:8208
	s_waitcnt lgkmcnt(11)
	v_fma_f32 v72, -v48, v116, v72
	v_fma_f32 v73, -v49, v117, v73
	v_fma_f32 v74, -v50, v118, v74
	v_fma_f32 v75, -v51, v119, v75
	ds_read_b128 v[48:51], v17 offset:8224
	s_waitcnt lgkmcnt(11)
	v_fma_f32 v72, -v52, v120, v72
	v_fma_f32 v73, -v53, v121, v73
	ds_read_b128 v[52:55], v17 offset:8240
	v_add_f32_e32 v72, v72, v73
	v_add_f32_e32 v74, v74, v75
	v_add_f32_e32 v122, v122, v72
	v_add_f32_e32 v122, v122, v74
	s_waitcnt lgkmcnt(11)
	v_mul_f32_e64 v72, -v56, v92
	v_mul_f32_e64 v73, -v57, v93
	v_mul_f32_e64 v74, -v58, v94
	v_mul_f32_e64 v75, -v59, v95
	ds_read_b128 v[56:59], v17 offset:8256
	s_waitcnt lgkmcnt(11)
	v_fma_f32 v72, -v4, v96, v72
	v_fma_f32 v73, -v5, v97, v73
	v_fma_f32 v74, -v6, v98, v74
	v_fma_f32 v75, -v7, v99, v75
	ds_read_b128 v[4:7], v17 offset:8272
	s_waitcnt lgkmcnt(11)
	v_fma_f32 v72, -v8, v100, v72
	v_fma_f32 v73, -v9, v101, v73
	v_fma_f32 v74, -v10, v102, v74
	v_fma_f32 v75, -v11, v103, v75
	ds_read_b128 v[8:11], v17 offset:8288
	s_waitcnt lgkmcnt(11)
	v_fma_f32 v72, -v12, v104, v72
	v_fma_f32 v73, -v13, v105, v73
	v_fma_f32 v74, -v14, v106, v74
	v_fma_f32 v75, -v15, v107, v75
	ds_read_b128 v[12:15], v17 offset:8304
	s_waitcnt lgkmcnt(11)
	v_fma_f32 v72, -v24, v108, v72
	v_fma_f32 v73, -v25, v109, v73
	v_fma_f32 v74, -v26, v110, v74
	v_fma_f32 v75, -v27, v111, v75
	ds_read_b128 v[24:27], v17 offset:8448
	s_waitcnt lgkmcnt(11)
	v_fma_f32 v72, -v28, v112, v72
	v_fma_f32 v73, -v29, v113, v73
	v_fma_f32 v74, -v30, v114, v74
	v_fma_f32 v75, -v31, v115, v75
	ds_read_b128 v[28:31], v17 offset:8464
	s_waitcnt lgkmcnt(11)
	v_fma_f32 v72, -v32, v116, v72
	v_fma_f32 v73, -v33, v117, v73
	v_fma_f32 v74, -v34, v118, v74
	v_fma_f32 v75, -v35, v119, v75
	ds_read_b128 v[32:35], v17 offset:8480
	s_waitcnt lgkmcnt(11)
	v_fma_f32 v72, -v36, v120, v72
	v_fma_f32 v73, -v37, v121, v73
	v_fma_f32 v74, -v38, v122, v74
	ds_read_b128 v[36:39], v17 offset:8496
	v_add_f32_e32 v72, v72, v73
	v_add_f32_e32 v74, v74, v75
	v_add_f32_e32 v123, v123, v72
	v_add_f32_e32 v123, v123, v74
	s_waitcnt lgkmcnt(11)
	v_mul_f32_e64 v72, -v40, v92
	v_mul_f32_e64 v73, -v41, v93
	v_mul_f32_e64 v74, -v42, v94
	v_mul_f32_e64 v75, -v43, v95
	ds_read_b128 v[40:43], v17 offset:8512
	s_waitcnt lgkmcnt(11)
	v_fma_f32 v72, -v44, v96, v72
	v_fma_f32 v73, -v45, v97, v73
	v_fma_f32 v74, -v46, v98, v74
	v_fma_f32 v75, -v47, v99, v75
	ds_read_b128 v[44:47], v17 offset:8528
	s_waitcnt lgkmcnt(11)
	v_fma_f32 v72, -v48, v100, v72
	v_fma_f32 v73, -v49, v101, v73
	v_fma_f32 v74, -v50, v102, v74
	v_fma_f32 v75, -v51, v103, v75
	ds_read_b128 v[48:51], v17 offset:8544
	s_waitcnt lgkmcnt(11)
	v_fma_f32 v72, -v52, v104, v72
	v_fma_f32 v73, -v53, v105, v73
	v_fma_f32 v74, -v54, v106, v74
	v_fma_f32 v75, -v55, v107, v75
	ds_read_b128 v[52:55], v17 offset:8560
	s_waitcnt lgkmcnt(11)
	v_fma_f32 v72, -v56, v108, v72
	v_fma_f32 v73, -v57, v109, v73
	v_fma_f32 v74, -v58, v110, v74
	v_fma_f32 v75, -v59, v111, v75
	ds_read_b128 v[56:59], v17 offset:8576
	s_waitcnt lgkmcnt(11)
	v_fma_f32 v72, -v4, v112, v72
	v_fma_f32 v73, -v5, v113, v73
	v_fma_f32 v74, -v6, v114, v74
	v_fma_f32 v75, -v7, v115, v75
	ds_read_b128 v[4:7], v17 offset:8704
	s_waitcnt lgkmcnt(11)
	v_fma_f32 v72, -v8, v116, v72
	v_fma_f32 v73, -v9, v117, v73
	v_fma_f32 v74, -v10, v118, v74
	v_fma_f32 v75, -v11, v119, v75
	ds_read_b128 v[8:11], v17 offset:8720
	s_waitcnt lgkmcnt(11)
	v_fma_f32 v72, -v12, v120, v72
	v_fma_f32 v73, -v13, v121, v73
	v_fma_f32 v74, -v14, v122, v74
	v_fma_f32 v75, -v15, v123, v75
	ds_read_b128 v[12:15], v17 offset:8736
	v_add_f32_e32 v72, v72, v73
	v_add_f32_e32 v74, v74, v75
	v_add_f32_e32 v124, v124, v72
	v_add_f32_e32 v124, v124, v74
	s_waitcnt lgkmcnt(11)
	v_mul_f32_e64 v72, -v24, v92
	v_mul_f32_e64 v73, -v25, v93
	v_mul_f32_e64 v74, -v26, v94
	v_mul_f32_e64 v75, -v27, v95
	ds_read_b128 v[24:27], v17 offset:8752
	s_waitcnt lgkmcnt(11)
	v_fma_f32 v72, -v28, v96, v72
	v_fma_f32 v73, -v29, v97, v73
	v_fma_f32 v74, -v30, v98, v74
	v_fma_f32 v75, -v31, v99, v75
	ds_read_b128 v[28:31], v17 offset:8768
	s_waitcnt lgkmcnt(11)
	v_fma_f32 v72, -v32, v100, v72
	v_fma_f32 v73, -v33, v101, v73
	v_fma_f32 v74, -v34, v102, v74
	v_fma_f32 v75, -v35, v103, v75
	ds_read_b128 v[32:35], v17 offset:8784
	s_waitcnt lgkmcnt(11)
	v_fma_f32 v72, -v36, v104, v72
	v_fma_f32 v73, -v37, v105, v73
	v_fma_f32 v74, -v38, v106, v74
	v_fma_f32 v75, -v39, v107, v75
	ds_read_b128 v[36:39], v17 offset:8800
	s_waitcnt lgkmcnt(11)
	v_fma_f32 v72, -v40, v108, v72
	v_fma_f32 v73, -v41, v109, v73
	v_fma_f32 v74, -v42, v110, v74
	v_fma_f32 v75, -v43, v111, v75
	ds_read_b128 v[40:43], v17 offset:8816
	s_waitcnt lgkmcnt(11)
	v_fma_f32 v72, -v44, v112, v72
	v_fma_f32 v73, -v45, v113, v73
	v_fma_f32 v74, -v46, v114, v74
	v_fma_f32 v75, -v47, v115, v75
	ds_read_b128 v[44:47], v17 offset:8832
	s_waitcnt lgkmcnt(11)
	v_fma_f32 v72, -v48, v116, v72
	v_fma_f32 v73, -v49, v117, v73
	v_fma_f32 v74, -v50, v118, v74
	v_fma_f32 v75, -v51, v119, v75
	ds_read_b128 v[48:51], v17 offset:8960
	s_waitcnt lgkmcnt(11)
	v_fma_f32 v72, -v52, v120, v72
	v_fma_f32 v73, -v53, v121, v73
	v_fma_f32 v74, -v54, v122, v74
	v_fma_f32 v75, -v55, v123, v75
	ds_read_b128 v[52:55], v17 offset:8976
	s_waitcnt lgkmcnt(11)
	v_fma_f32 v72, -v56, v124, v72
	ds_read_b128 v[56:59], v17 offset:8992
	v_add_f32_e32 v72, v72, v73
	v_add_f32_e32 v74, v74, v75
	v_add_f32_e32 v125, v125, v72
	v_add_f32_e32 v125, v125, v74
	s_waitcnt lgkmcnt(11)
; #define LAS __attribute__((address_space(3)))
; __device__ __forceinline__ void even_prep(const Ctx& c, const Params& p, int e) {
;     ...
; #pragma unroll
;             for (int i = 1; i < 64; ++i) { const LAS f32x4* Lr = (const LAS f32x4*)(Lv + i * 64); float a0 = x[i], a1 = 0.f;
; #pragma unroll
;                 for (int j4 = 0; j4 < (i + 3) / 4; ++j4) { const f32x4 l = Lr[j4];
;                     if (4 * j4 + 0 < i) a0 -= l[0] * x[4 * j4 + 0];
;                     if (4 * j4 + 1 < i) a1 -= l[1] * x[4 * j4 + 1];
;                     if (4 * j4 + 2 < i) a0 -= l[2] * x[4 * j4 + 2];
;                     if (4 * j4 + 3 < i) a1 -= l[3] * x[4 * j4 + 3]; }
;                 x[i] = a0 + a1; }
	v_mul_f32_e64 v72, -v4, v92
	v_mul_f32_e64 v73, -v5, v93
	v_mul_f32_e64 v74, -v6, v94
	v_mul_f32_e64 v75, -v7, v95
	ds_read_b128 v[4:7], v17 offset:9008
	s_waitcnt lgkmcnt(11)
	v_fma_f32 v72, -v8, v96, v72
	v_fma_f32 v73, -v9, v97, v73
	v_fma_f32 v74, -v10, v98, v74
	v_fma_f32 v75, -v11, v99, v75
	ds_read_b128 v[8:11], v17 offset:9024
	s_waitcnt lgkmcnt(11)
	v_fma_f32 v72, -v12, v100, v72
	v_fma_f32 v73, -v13, v101, v73
	v_fma_f32 v74, -v14, v102, v74
	v_fma_f32 v75, -v15, v103, v75
	ds_read_b128 v[12:15], v17 offset:9040
	s_waitcnt lgkmcnt(11)
	v_fma_f32 v72, -v24, v104, v72
	v_fma_f32 v73, -v25, v105, v73
	v_fma_f32 v74, -v26, v106, v74
	v_fma_f32 v75, -v27, v107, v75
	ds_read_b128 v[24:27], v17 offset:9056
	s_waitcnt lgkmcnt(11)
	v_fma_f32 v72, -v28, v108, v72
	v_fma_f32 v73, -v29, v109, v73
	v_fma_f32 v74, -v30, v110, v74
	v_fma_f32 v75, -v31, v111, v75
	ds_read_b128 v[28:31], v17 offset:9072
	s_waitcnt lgkmcnt(11)
	v_fma_f32 v72, -v32, v112, v72
	v_fma_f32 v73, -v33, v113, v73
	v_fma_f32 v74, -v34, v114, v74
	v_fma_f32 v75, -v35, v115, v75
	ds_read_b128 v[32:35], v17 offset:9088
	s_waitcnt lgkmcnt(11)
	v_fma_f32 v72, -v36, v116, v72
	v_fma_f32 v73, -v37, v117, v73
	v_fma_f32 v74, -v38, v118, v74
	v_fma_f32 v75, -v39, v119, v75
	ds_read_b128 v[36:39], v17 offset:9216
	s_waitcnt lgkmcnt(11)
	v_fma_f32 v72, -v40, v120, v72
	v_fma_f32 v73, -v41, v121, v73
	v_fma_f32 v74, -v42, v122, v74
	v_fma_f32 v75, -v43, v123, v75
	ds_read_b128 v[40:43], v17 offset:9232
	s_waitcnt lgkmcnt(11)
	v_fma_f32 v72, -v44, v124, v72
	v_fma_f32 v73, -v45, v125, v73
	ds_read_b128 v[44:47], v17 offset:9248
	v_add_f32_e32 v72, v72, v73
	v_add_f32_e32 v74, v74, v75
	v_add_f32_e32 v126, v126, v72
	v_add_f32_e32 v126, v126, v74
	s_waitcnt lgkmcnt(11)
	v_mul_f32_e64 v72, -v48, v92
	v_mul_f32_e64 v73, -v49, v93
	v_mul_f32_e64 v74, -v50, v94
	v_mul_f32_e64 v75, -v51, v95
	ds_read_b128 v[48:51], v17 offset:9264
	s_waitcnt lgkmcnt(11)
	v_fma_f32 v72, -v52, v96, v72
	v_fma_f32 v73, -v53, v97, v73
	v_fma_f32 v74, -v54, v98, v74
	v_fma_f32 v75, -v55, v99, v75
	ds_read_b128 v[52:55], v17 offset:9280
	s_waitcnt lgkmcnt(11)
	v_fma_f32 v72, -v56, v100, v72
	v_fma_f32 v73, -v57, v101, v73
	v_fma_f32 v74, -v58, v102, v74
	v_fma_f32 v75, -v59, v103, v75
	ds_read_b128 v[56:59], v17 offset:9296
	s_waitcnt lgkmcnt(11)
	v_fma_f32 v72, -v4, v104, v72
	v_fma_f32 v73, -v5, v105, v73
	v_fma_f32 v74, -v6, v106, v74
	v_fma_f32 v75, -v7, v107, v75
	ds_read_b128 v[4:7], v17 offset:9312
	s_waitcnt lgkmcnt(11)
	v_fma_f32 v72, -v8, v108, v72
	v_fma_f32 v73, -v9, v109, v73
	v_fma_f32 v74, -v10, v110, v74
	v_fma_f32 v75, -v11, v111, v75
	ds_read_b128 v[8:11], v17 offset:9328
	s_waitcnt lgkmcnt(11)
	v_fma_f32 v72, -v12, v112, v72
	v_fma_f32 v73, -v13, v113, v73
	v_fma_f32 v74, -v14, v114, v74
	v_fma_f32 v75, -v15, v115, v75
	ds_read_b128 v[12:15], v17 offset:9344
	s_waitcnt lgkmcnt(11)
	v_fma_f32 v72, -v24, v116, v72
	v_fma_f32 v73, -v25, v117, v73
	v_fma_f32 v74, -v26, v118, v74
	v_fma_f32 v75, -v27, v119, v75
	ds_read_b128 v[24:27], v17 offset:9472
	s_waitcnt lgkmcnt(11)
	v_fma_f32 v72, -v28, v120, v72
	v_fma_f32 v73, -v29, v121, v73
	v_fma_f32 v74, -v30, v122, v74
	v_fma_f32 v75, -v31, v123, v75
	ds_read_b128 v[28:31], v17 offset:9488
	s_waitcnt lgkmcnt(11)
	v_fma_f32 v72, -v32, v124, v72
	v_fma_f32 v73, -v33, v125, v73
	v_fma_f32 v74, -v34, v126, v74
	ds_read_b128 v[32:35], v17 offset:9504
	v_add_f32_e32 v72, v72, v73
	v_add_f32_e32 v74, v74, v75
	v_add_f32_e32 v127, v127, v72
	v_add_f32_e32 v127, v127, v74
	s_waitcnt lgkmcnt(11)
	v_mul_f32_e64 v72, -v36, v92
	v_mul_f32_e64 v73, -v37, v93
	v_mul_f32_e64 v74, -v38, v94
	v_mul_f32_e64 v75, -v39, v95
	ds_read_b128 v[36:39], v17 offset:9520
	s_waitcnt lgkmcnt(11)
	v_fma_f32 v72, -v40, v96, v72
	v_fma_f32 v73, -v41, v97, v73
	v_fma_f32 v74, -v42, v98, v74
	v_fma_f32 v75, -v43, v99, v75
	ds_read_b128 v[40:43], v17 offset:9536
	s_waitcnt lgkmcnt(11)
	v_fma_f32 v72, -v44, v100, v72
	v_fma_f32 v73, -v45, v101, v73
	v_fma_f32 v74, -v46, v102, v74
	v_fma_f32 v75, -v47, v103, v75
	ds_read_b128 v[44:47], v17 offset:9552
	s_waitcnt lgkmcnt(11)
	v_fma_f32 v72, -v48, v104, v72
	v_fma_f32 v73, -v49, v105, v73
	v_fma_f32 v74, -v50, v106, v74
	v_fma_f32 v75, -v51, v107, v75
	ds_read_b128 v[48:51], v17 offset:9568
	s_waitcnt lgkmcnt(11)
	v_fma_f32 v72, -v52, v108, v72
	v_fma_f32 v73, -v53, v109, v73
	v_fma_f32 v74, -v54, v110, v74
	v_fma_f32 v75, -v55, v111, v75
	ds_read_b128 v[52:55], v17 offset:9584
	s_waitcnt lgkmcnt(11)
	v_fma_f32 v72, -v56, v112, v72
	v_fma_f32 v73, -v57, v113, v73
	v_fma_f32 v74, -v58, v114, v74
	v_fma_f32 v75, -v59, v115, v75
	ds_read_b128 v[56:59], v17 offset:9600
	s_waitcnt lgkmcnt(11)
	v_fma_f32 v72, -v4, v116, v72
	v_fma_f32 v73, -v5, v117, v73
	v_fma_f32 v74, -v6, v118, v74
	v_fma_f32 v75, -v7, v119, v75
	ds_read_b128 v[4:7], v17 offset:9616
	s_waitcnt lgkmcnt(11)
	v_fma_f32 v72, -v8, v120, v72
	v_fma_f32 v73, -v9, v121, v73
	v_fma_f32 v74, -v10, v122, v74
	v_fma_f32 v75, -v11, v123, v75
	ds_read_b128 v[8:11], v17 offset:9728
	s_waitcnt lgkmcnt(11)
	v_fma_f32 v72, -v12, v124, v72
	v_fma_f32 v73, -v13, v125, v73
	v_fma_f32 v74, -v14, v126, v74
	v_fma_f32 v75, -v15, v127, v75
	ds_read_b128 v[12:15], v17 offset:9744
	v_add_f32_e32 v72, v72, v73
	v_add_f32_e32 v74, v74, v75
	v_add_f32_e32 v128, v128, v72
	v_add_f32_e32 v128, v128, v74
	s_waitcnt lgkmcnt(11)
	v_mul_f32_e64 v72, -v24, v92
	v_mul_f32_e64 v73, -v25, v93
	v_mul_f32_e64 v74, -v26, v94
	v_mul_f32_e64 v75, -v27, v95
	ds_read_b128 v[24:27], v17 offset:9760
	s_waitcnt lgkmcnt(11)
	v_fma_f32 v72, -v28, v96, v72
	v_fma_f32 v73, -v29, v97, v73
	v_fma_f32 v74, -v30, v98, v74
	v_fma_f32 v75, -v31, v99, v75
	ds_read_b128 v[28:31], v17 offset:9776
	s_waitcnt lgkmcnt(11)
; #define LAS __attribute__((address_space(3)))
; __device__ __forceinline__ void even_prep(const Ctx& c, const Params& p, int e) {
;     ...
; #pragma unroll
;             for (int i = 1; i < 64; ++i) { const LAS f32x4* Lr = (const LAS f32x4*)(Lv + i * 64); float a0 = x[i], a1 = 0.f;
; #pragma unroll
;                 for (int j4 = 0; j4 < (i + 3) / 4; ++j4) { const f32x4 l = Lr[j4];
;                     if (4 * j4 + 0 < i) a0 -= l[0] * x[4 * j4 + 0];
;                     if (4 * j4 + 1 < i) a1 -= l[1] * x[4 * j4 + 1];
;                     if (4 * j4 + 2 < i) a0 -= l[2] * x[4 * j4 + 2];
;                     if (4 * j4 + 3 < i) a1 -= l[3] * x[4 * j4 + 3]; }
;                 x[i] = a0 + a1; }
	v_fma_f32 v72, -v32, v100, v72
	v_fma_f32 v73, -v33, v101, v73
	v_fma_f32 v74, -v34, v102, v74
	v_fma_f32 v75, -v35, v103, v75
	ds_read_b128 v[32:35], v17 offset:9792
	s_waitcnt lgkmcnt(11)
	v_fma_f32 v72, -v36, v104, v72
	v_fma_f32 v73, -v37, v105, v73
	v_fma_f32 v74, -v38, v106, v74
	v_fma_f32 v75, -v39, v107, v75
	ds_read_b128 v[36:39], v17 offset:9808
	s_waitcnt lgkmcnt(11)
	v_fma_f32 v72, -v40, v108, v72
	v_fma_f32 v73, -v41, v109, v73
	v_fma_f32 v74, -v42, v110, v74
	v_fma_f32 v75, -v43, v111, v75
	ds_read_b128 v[40:43], v17 offset:9824
	s_waitcnt lgkmcnt(11)
	v_fma_f32 v72, -v44, v112, v72
	v_fma_f32 v73, -v45, v113, v73
	v_fma_f32 v74, -v46, v114, v74
	v_fma_f32 v75, -v47, v115, v75
	ds_read_b128 v[44:47], v17 offset:9840
	s_waitcnt lgkmcnt(11)
	v_fma_f32 v72, -v48, v116, v72
	v_fma_f32 v73, -v49, v117, v73
	v_fma_f32 v74, -v50, v118, v74
	v_fma_f32 v75, -v51, v119, v75
	ds_read_b128 v[48:51], v17 offset:9856
	s_waitcnt lgkmcnt(11)
	v_fma_f32 v72, -v52, v120, v72
	v_fma_f32 v73, -v53, v121, v73
	v_fma_f32 v74, -v54, v122, v74
	v_fma_f32 v75, -v55, v123, v75
	ds_read_b128 v[52:55], v17 offset:9872
	s_waitcnt lgkmcnt(11)
	v_fma_f32 v72, -v56, v124, v72
	v_fma_f32 v73, -v57, v125, v73
	v_fma_f32 v74, -v58, v126, v74
	v_fma_f32 v75, -v59, v127, v75
	ds_read_b128 v[56:59], v17 offset:9984
	s_waitcnt lgkmcnt(11)
	v_fma_f32 v72, -v4, v128, v72
	ds_read_b128 v[4:7], v17 offset:10000
	v_add_f32_e32 v72, v72, v73
	v_add_f32_e32 v74, v74, v75
	v_add_f32_e32 v129, v129, v72
	v_add_f32_e32 v129, v129, v74
	s_waitcnt lgkmcnt(11)
	v_mul_f32_e64 v72, -v8, v92
	v_mul_f32_e64 v73, -v9, v93
	v_mul_f32_e64 v74, -v10, v94
	v_mul_f32_e64 v75, -v11, v95
	ds_read_b128 v[8:11], v17 offset:10016
	s_waitcnt lgkmcnt(11)
	v_fma_f32 v72, -v12, v96, v72
	v_fma_f32 v73, -v13, v97, v73
	v_fma_f32 v74, -v14, v98, v74
	v_fma_f32 v75, -v15, v99, v75
	ds_read_b128 v[12:15], v17 offset:10032
	s_waitcnt lgkmcnt(11)
	v_fma_f32 v72, -v24, v100, v72
	v_fma_f32 v73, -v25, v101, v73
	v_fma_f32 v74, -v26, v102, v74
	v_fma_f32 v75, -v27, v103, v75
	ds_read_b128 v[24:27], v17 offset:10048
	s_waitcnt lgkmcnt(11)
	v_fma_f32 v72, -v28, v104, v72
	v_fma_f32 v73, -v29, v105, v73
	v_fma_f32 v74, -v30, v106, v74
	v_fma_f32 v75, -v31, v107, v75
	ds_read_b128 v[28:31], v17 offset:10064
	s_waitcnt lgkmcnt(11)
	v_fma_f32 v72, -v32, v108, v72
	v_fma_f32 v73, -v33, v109, v73
	v_fma_f32 v74, -v34, v110, v74
	v_fma_f32 v75, -v35, v111, v75
	ds_read_b128 v[32:35], v17 offset:10080
	s_waitcnt lgkmcnt(11)
	v_fma_f32 v72, -v36, v112, v72
	v_fma_f32 v73, -v37, v113, v73
	v_fma_f32 v74, -v38, v114, v74
	v_fma_f32 v75, -v39, v115, v75
	ds_read_b128 v[36:39], v17 offset:10096
	s_waitcnt lgkmcnt(11)
	v_fma_f32 v72, -v40, v116, v72
	v_fma_f32 v73, -v41, v117, v73
	v_fma_f32 v74, -v42, v118, v74
	v_fma_f32 v75, -v43, v119, v75
	ds_read_b128 v[40:43], v17 offset:10112
	s_waitcnt lgkmcnt(11)
	v_fma_f32 v72, -v44, v120, v72
	v_fma_f32 v73, -v45, v121, v73
	v_fma_f32 v74, -v46, v122, v74
	v_fma_f32 v75, -v47, v123, v75
	ds_read_b128 v[44:47], v17 offset:10128
	s_waitcnt lgkmcnt(11)
	v_fma_f32 v72, -v48, v124, v72
	v_fma_f32 v73, -v49, v125, v73
	v_fma_f32 v74, -v50, v126, v74
	v_fma_f32 v75, -v51, v127, v75
	ds_read_b128 v[48:51], v17 offset:10240
	s_waitcnt lgkmcnt(11)
	v_fma_f32 v72, -v52, v128, v72
	v_fma_f32 v73, -v53, v129, v73
	ds_read_b128 v[52:55], v17 offset:10256
	v_add_f32_e32 v72, v72, v73
	v_add_f32_e32 v74, v74, v75
	v_add_f32_e32 v130, v130, v72
	v_add_f32_e32 v130, v130, v74
	s_waitcnt lgkmcnt(11)
	v_mul_f32_e64 v72, -v56, v92
	v_mul_f32_e64 v73, -v57, v93
	v_mul_f32_e64 v74, -v58, v94
	v_mul_f32_e64 v75, -v59, v95
	ds_read_b128 v[56:59], v17 offset:10272
	s_waitcnt lgkmcnt(11)
	v_fma_f32 v72, -v4, v96, v72
	v_fma_f32 v73, -v5, v97, v73
	v_fma_f32 v74, -v6, v98, v74
	v_fma_f32 v75, -v7, v99, v75
	ds_read_b128 v[4:7], v17 offset:10288
	s_waitcnt lgkmcnt(11)
	v_fma_f32 v72, -v8, v100, v72
	v_fma_f32 v73, -v9, v101, v73
	v_fma_f32 v74, -v10, v102, v74
	v_fma_f32 v75, -v11, v103, v75
	ds_read_b128 v[8:11], v17 offset:10304
	s_waitcnt lgkmcnt(11)
	v_fma_f32 v72, -v12, v104, v72
	v_fma_f32 v73, -v13, v105, v73
	v_fma_f32 v74, -v14, v106, v74
	v_fma_f32 v75, -v15, v107, v75
	ds_read_b128 v[12:15], v17 offset:10320
	s_waitcnt lgkmcnt(11)
	v_fma_f32 v72, -v24, v108, v72
	v_fma_f32 v73, -v25, v109, v73
	v_fma_f32 v74, -v26, v110, v74
	v_fma_f32 v75, -v27, v111, v75
	ds_read_b128 v[24:27], v17 offset:10336
	s_waitcnt lgkmcnt(11)
	v_fma_f32 v72, -v28, v112, v72
	v_fma_f32 v73, -v29, v113, v73
	v_fma_f32 v74, -v30, v114, v74
	v_fma_f32 v75, -v31, v115, v75
	ds_read_b128 v[28:31], v17 offset:10352
	s_waitcnt lgkmcnt(11)
	v_fma_f32 v72, -v32, v116, v72
	v_fma_f32 v73, -v33, v117, v73
	v_fma_f32 v74, -v34, v118, v74
	v_fma_f32 v75, -v35, v119, v75
	ds_read_b128 v[32:35], v17 offset:10368
	s_waitcnt lgkmcnt(11)
	v_fma_f32 v72, -v36, v120, v72
	v_fma_f32 v73, -v37, v121, v73
	v_fma_f32 v74, -v38, v122, v74
	v_fma_f32 v75, -v39, v123, v75
	ds_read_b128 v[36:39], v17 offset:10384
	s_waitcnt lgkmcnt(11)
	v_fma_f32 v72, -v40, v124, v72
	v_fma_f32 v73, -v41, v125, v73
	v_fma_f32 v74, -v42, v126, v74
	v_fma_f32 v75, -v43, v127, v75
	ds_read_b128 v[40:43], v17 offset:10496
	s_waitcnt lgkmcnt(11)
	v_fma_f32 v72, -v44, v128, v72
	v_fma_f32 v73, -v45, v129, v73
	v_fma_f32 v74, -v46, v130, v74
	ds_read_b128 v[44:47], v17 offset:10512
	v_add_f32_e32 v72, v72, v73
	v_add_f32_e32 v74, v74, v75
	v_add_f32_e32 v131, v131, v72
	v_add_f32_e32 v131, v131, v74
	s_waitcnt lgkmcnt(11)
	v_mul_f32_e64 v72, -v48, v92
	v_mul_f32_e64 v73, -v49, v93
	v_mul_f32_e64 v74, -v50, v94
	v_mul_f32_e64 v75, -v51, v95
	ds_read_b128 v[48:51], v17 offset:10528
	s_waitcnt lgkmcnt(11)
; #define LAS __attribute__((address_space(3)))
; __device__ __forceinline__ void even_prep(const Ctx& c, const Params& p, int e) {
;     ...
; #pragma unroll
;             for (int i = 1; i < 64; ++i) { const LAS f32x4* Lr = (const LAS f32x4*)(Lv + i * 64); float a0 = x[i], a1 = 0.f;
; #pragma unroll
;                 for (int j4 = 0; j4 < (i + 3) / 4; ++j4) { const f32x4 l = Lr[j4];
;                     if (4 * j4 + 0 < i) a0 -= l[0] * x[4 * j4 + 0];
;                     if (4 * j4 + 1 < i) a1 -= l[1] * x[4 * j4 + 1];
;                     if (4 * j4 + 2 < i) a0 -= l[2] * x[4 * j4 + 2];
;                     if (4 * j4 + 3 < i) a1 -= l[3] * x[4 * j4 + 3]; }
;                 x[i] = a0 + a1; }
	v_fma_f32 v72, -v52, v96, v72
	v_fma_f32 v73, -v53, v97, v73
	v_fma_f32 v74, -v54, v98, v74
	v_fma_f32 v75, -v55, v99, v75
	ds_read_b128 v[52:55], v17 offset:10544
	s_waitcnt lgkmcnt(11)
	v_fma_f32 v72, -v56, v100, v72
	v_fma_f32 v73, -v57, v101, v73
	v_fma_f32 v74, -v58, v102, v74
	v_fma_f32 v75, -v59, v103, v75
	ds_read_b128 v[56:59], v17 offset:10560
	s_waitcnt lgkmcnt(11)
	v_fma_f32 v72, -v4, v104, v72
	v_fma_f32 v73, -v5, v105, v73
	v_fma_f32 v74, -v6, v106, v74
	v_fma_f32 v75, -v7, v107, v75
	ds_read_b128 v[4:7], v17 offset:10576
	s_waitcnt lgkmcnt(11)
	v_fma_f32 v72, -v8, v108, v72
	v_fma_f32 v73, -v9, v109, v73
	v_fma_f32 v74, -v10, v110, v74
	v_fma_f32 v75, -v11, v111, v75
	ds_read_b128 v[8:11], v17 offset:10592
	s_waitcnt lgkmcnt(11)
	v_fma_f32 v72, -v12, v112, v72
	v_fma_f32 v73, -v13, v113, v73
	v_fma_f32 v74, -v14, v114, v74
	v_fma_f32 v75, -v15, v115, v75
	ds_read_b128 v[12:15], v17 offset:10608
	s_waitcnt lgkmcnt(11)
	v_fma_f32 v72, -v24, v116, v72
	v_fma_f32 v73, -v25, v117, v73
	v_fma_f32 v74, -v26, v118, v74
	v_fma_f32 v75, -v27, v119, v75
	ds_read_b128 v[24:27], v17 offset:10624
	s_waitcnt lgkmcnt(11)
	v_fma_f32 v72, -v28, v120, v72
	v_fma_f32 v73, -v29, v121, v73
	v_fma_f32 v74, -v30, v122, v74
	v_fma_f32 v75, -v31, v123, v75
	ds_read_b128 v[28:31], v17 offset:10640
	s_waitcnt lgkmcnt(11)
	v_fma_f32 v72, -v32, v124, v72
	v_fma_f32 v73, -v33, v125, v73
	v_fma_f32 v74, -v34, v126, v74
	v_fma_f32 v75, -v35, v127, v75
	ds_read_b128 v[32:35], v17 offset:10656
	s_waitcnt lgkmcnt(11)
	v_fma_f32 v72, -v36, v128, v72
	v_fma_f32 v73, -v37, v129, v73
	v_fma_f32 v74, -v38, v130, v74
	v_fma_f32 v75, -v39, v131, v75
	ds_read_b128 v[36:39], v17 offset:10752
	v_add_f32_e32 v72, v72, v73
	v_add_f32_e32 v74, v74, v75
	v_add_f32_e32 v132, v132, v72
	v_add_f32_e32 v132, v132, v74
	s_waitcnt lgkmcnt(11)
	v_mul_f32_e64 v72, -v40, v92
	v_mul_f32_e64 v73, -v41, v93
	v_mul_f32_e64 v74, -v42, v94
	v_mul_f32_e64 v75, -v43, v95
	ds_read_b128 v[40:43], v17 offset:10768
	s_waitcnt lgkmcnt(11)
	v_fma_f32 v72, -v44, v96, v72
	v_fma_f32 v73, -v45, v97, v73
	v_fma_f32 v74, -v46, v98, v74
	v_fma_f32 v75, -v47, v99, v75
	ds_read_b128 v[44:47], v17 offset:10784
	s_waitcnt lgkmcnt(11)
	v_fma_f32 v72, -v48, v100, v72
	v_fma_f32 v73, -v49, v101, v73
	v_fma_f32 v74, -v50, v102, v74
	v_fma_f32 v75, -v51, v103, v75
	ds_read_b128 v[48:51], v17 offset:10800
	s_waitcnt lgkmcnt(11)
	v_fma_f32 v72, -v52, v104, v72
	v_fma_f32 v73, -v53, v105, v73
	v_fma_f32 v74, -v54, v106, v74
	v_fma_f32 v75, -v55, v107, v75
	ds_read_b128 v[52:55], v17 offset:10816
	s_waitcnt lgkmcnt(11)
	v_fma_f32 v72, -v56, v108, v72
	v_fma_f32 v73, -v57, v109, v73
	v_fma_f32 v74, -v58, v110, v74
	v_fma_f32 v75, -v59, v111, v75
	ds_read_b128 v[56:59], v17 offset:10832
	s_waitcnt lgkmcnt(11)
	v_fma_f32 v72, -v4, v112, v72
	v_fma_f32 v73, -v5, v113, v73
	v_fma_f32 v74, -v6, v114, v74
	v_fma_f32 v75, -v7, v115, v75
	ds_read_b128 v[4:7], v17 offset:10848
	s_waitcnt lgkmcnt(11)
	v_fma_f32 v72, -v8, v116, v72
	v_fma_f32 v73, -v9, v117, v73
	v_fma_f32 v74, -v10, v118, v74
	v_fma_f32 v75, -v11, v119, v75
	ds_read_b128 v[8:11], v17 offset:10864
	s_waitcnt lgkmcnt(11)
	v_fma_f32 v72, -v12, v120, v72
	v_fma_f32 v73, -v13, v121, v73
	v_fma_f32 v74, -v14, v122, v74
	v_fma_f32 v75, -v15, v123, v75
	ds_read_b128 v[12:15], v17 offset:10880
	s_waitcnt lgkmcnt(11)
	v_fma_f32 v72, -v24, v124, v72
	v_fma_f32 v73, -v25, v125, v73
	v_fma_f32 v74, -v26, v126, v74
	v_fma_f32 v75, -v27, v127, v75
	ds_read_b128 v[24:27], v17 offset:10896
	s_waitcnt lgkmcnt(11)
	v_fma_f32 v72, -v28, v128, v72
	v_fma_f32 v73, -v29, v129, v73
	v_fma_f32 v74, -v30, v130, v74
	v_fma_f32 v75, -v31, v131, v75
	ds_read_b128 v[28:31], v17 offset:10912
	s_waitcnt lgkmcnt(11)
	v_fma_f32 v72, -v32, v132, v72
	ds_read_b128 v[32:35], v17 offset:11008
	v_add_f32_e32 v72, v72, v73
	v_add_f32_e32 v74, v74, v75
	v_add_f32_e32 v133, v133, v72
	v_add_f32_e32 v133, v133, v74
	s_waitcnt lgkmcnt(11)
	v_mul_f32_e64 v72, -v36, v92
	v_mul_f32_e64 v73, -v37, v93
	v_mul_f32_e64 v74, -v38, v94
	v_mul_f32_e64 v75, -v39, v95
	ds_read_b128 v[36:39], v17 offset:11024
	s_waitcnt lgkmcnt(11)
	v_fma_f32 v72, -v40, v96, v72
	v_fma_f32 v73, -v41, v97, v73
	v_fma_f32 v74, -v42, v98, v74
	v_fma_f32 v75, -v43, v99, v75
	ds_read_b128 v[40:43], v17 offset:11040
	s_waitcnt lgkmcnt(11)
	v_fma_f32 v72, -v44, v100, v72
	v_fma_f32 v73, -v45, v101, v73
	v_fma_f32 v74, -v46, v102, v74
	v_fma_f32 v75, -v47, v103, v75
	ds_read_b128 v[44:47], v17 offset:11056
	s_waitcnt lgkmcnt(11)
	v_fma_f32 v72, -v48, v104, v72
	v_fma_f32 v73, -v49, v105, v73
	v_fma_f32 v74, -v50, v106, v74
	v_fma_f32 v75, -v51, v107, v75
	ds_read_b128 v[48:51], v17 offset:11072
	s_waitcnt lgkmcnt(11)
	v_fma_f32 v72, -v52, v108, v72
	v_fma_f32 v73, -v53, v109, v73
	v_fma_f32 v74, -v54, v110, v74
	v_fma_f32 v75, -v55, v111, v75
	ds_read_b128 v[52:55], v17 offset:11088
	s_waitcnt lgkmcnt(11)
	v_fma_f32 v72, -v56, v112, v72
	v_fma_f32 v73, -v57, v113, v73
	v_fma_f32 v74, -v58, v114, v74
	v_fma_f32 v75, -v59, v115, v75
	ds_read_b128 v[56:59], v17 offset:11104
	s_waitcnt lgkmcnt(11)
	v_fma_f32 v72, -v4, v116, v72
	v_fma_f32 v73, -v5, v117, v73
	v_fma_f32 v74, -v6, v118, v74
	v_fma_f32 v75, -v7, v119, v75
	ds_read_b128 v[4:7], v17 offset:11120
	s_waitcnt lgkmcnt(11)
	v_fma_f32 v72, -v8, v120, v72
	v_fma_f32 v73, -v9, v121, v73
	v_fma_f32 v74, -v10, v122, v74
	v_fma_f32 v75, -v11, v123, v75
	ds_read_b128 v[8:11], v17 offset:11136
	s_waitcnt lgkmcnt(11)
	v_fma_f32 v72, -v12, v124, v72
	v_fma_f32 v73, -v13, v125, v73
	v_fma_f32 v74, -v14, v126, v74
	v_fma_f32 v75, -v15, v127, v75
	ds_read_b128 v[12:15], v17 offset:11152
	s_waitcnt lgkmcnt(11)
; #define LAS __attribute__((address_space(3)))
; __device__ __forceinline__ void even_prep(const Ctx& c, const Params& p, int e) {
;     ...
; #pragma unroll
;             for (int i = 1; i < 64; ++i) { const LAS f32x4* Lr = (const LAS f32x4*)(Lv + i * 64); float a0 = x[i], a1 = 0.f;
; #pragma unroll
;                 for (int j4 = 0; j4 < (i + 3) / 4; ++j4) { const f32x4 l = Lr[j4];
;                     if (4 * j4 + 0 < i) a0 -= l[0] * x[4 * j4 + 0];
;                     if (4 * j4 + 1 < i) a1 -= l[1] * x[4 * j4 + 1];
;                     if (4 * j4 + 2 < i) a0 -= l[2] * x[4 * j4 + 2];
;                     if (4 * j4 + 3 < i) a1 -= l[3] * x[4 * j4 + 3]; }
;                 x[i] = a0 + a1; }
	v_fma_f32 v72, -v24, v128, v72
	v_fma_f32 v73, -v25, v129, v73
	v_fma_f32 v74, -v26, v130, v74
	v_fma_f32 v75, -v27, v131, v75
	ds_read_b128 v[24:27], v17 offset:11168
	s_waitcnt lgkmcnt(11)
	v_fma_f32 v72, -v28, v132, v72
	v_fma_f32 v73, -v29, v133, v73
	ds_read_b128 v[28:31], v17 offset:11264
	v_add_f32_e32 v72, v72, v73
	v_add_f32_e32 v74, v74, v75
	v_add_f32_e32 v134, v134, v72
	v_add_f32_e32 v134, v134, v74
	s_waitcnt lgkmcnt(11)
	v_mul_f32_e64 v72, -v32, v92
	v_mul_f32_e64 v73, -v33, v93
	v_mul_f32_e64 v74, -v34, v94
	v_mul_f32_e64 v75, -v35, v95
	ds_read_b128 v[32:35], v17 offset:11280
	s_waitcnt lgkmcnt(11)
	v_fma_f32 v72, -v36, v96, v72
	v_fma_f32 v73, -v37, v97, v73
	v_fma_f32 v74, -v38, v98, v74
	v_fma_f32 v75, -v39, v99, v75
	ds_read_b128 v[36:39], v17 offset:11296
	s_waitcnt lgkmcnt(11)
	v_fma_f32 v72, -v40, v100, v72
	v_fma_f32 v73, -v41, v101, v73
	v_fma_f32 v74, -v42, v102, v74
	v_fma_f32 v75, -v43, v103, v75
	ds_read_b128 v[40:43], v17 offset:11312
	s_waitcnt lgkmcnt(11)
	v_fma_f32 v72, -v44, v104, v72
	v_fma_f32 v73, -v45, v105, v73
	v_fma_f32 v74, -v46, v106, v74
	v_fma_f32 v75, -v47, v107, v75
	ds_read_b128 v[44:47], v17 offset:11328
	s_waitcnt lgkmcnt(11)
	v_fma_f32 v72, -v48, v108, v72
	v_fma_f32 v73, -v49, v109, v73
	v_fma_f32 v74, -v50, v110, v74
	v_fma_f32 v75, -v51, v111, v75
	ds_read_b128 v[48:51], v17 offset:11344
	s_waitcnt lgkmcnt(11)
	v_fma_f32 v72, -v52, v112, v72
	v_fma_f32 v73, -v53, v113, v73
	v_fma_f32 v74, -v54, v114, v74
	v_fma_f32 v75, -v55, v115, v75
	ds_read_b128 v[52:55], v17 offset:11360
	s_waitcnt lgkmcnt(11)
	v_fma_f32 v72, -v56, v116, v72
	v_fma_f32 v73, -v57, v117, v73
	v_fma_f32 v74, -v58, v118, v74
	v_fma_f32 v75, -v59, v119, v75
	ds_read_b128 v[56:59], v17 offset:11376
	s_waitcnt lgkmcnt(11)
	v_fma_f32 v72, -v4, v120, v72
	v_fma_f32 v73, -v5, v121, v73
	v_fma_f32 v74, -v6, v122, v74
	v_fma_f32 v75, -v7, v123, v75
	ds_read_b128 v[4:7], v17 offset:11392
	s_waitcnt lgkmcnt(11)
	v_fma_f32 v72, -v8, v124, v72
	v_fma_f32 v73, -v9, v125, v73
	v_fma_f32 v74, -v10, v126, v74
	v_fma_f32 v75, -v11, v127, v75
	ds_read_b128 v[8:11], v17 offset:11408
	s_waitcnt lgkmcnt(11)
	v_fma_f32 v72, -v12, v128, v72
	v_fma_f32 v73, -v13, v129, v73
	v_fma_f32 v74, -v14, v130, v74
	v_fma_f32 v75, -v15, v131, v75
	ds_read_b128 v[12:15], v17 offset:11424
	s_waitcnt lgkmcnt(11)
	v_fma_f32 v72, -v24, v132, v72
	v_fma_f32 v73, -v25, v133, v73
	v_fma_f32 v74, -v26, v134, v74
	ds_read_b128 v[24:27], v17 offset:11520
	v_add_f32_e32 v72, v72, v73
	v_add_f32_e32 v74, v74, v75
	v_add_f32_e32 v135, v135, v72
	v_add_f32_e32 v135, v135, v74
	s_waitcnt lgkmcnt(11)
	v_mul_f32_e64 v72, -v28, v92
	v_mul_f32_e64 v73, -v29, v93
	v_mul_f32_e64 v74, -v30, v94
	v_mul_f32_e64 v75, -v31, v95
	ds_read_b128 v[28:31], v17 offset:11536
	s_waitcnt lgkmcnt(11)
	v_fma_f32 v72, -v32, v96, v72
	v_fma_f32 v73, -v33, v97, v73
	v_fma_f32 v74, -v34, v98, v74
	v_fma_f32 v75, -v35, v99, v75
	ds_read_b128 v[32:35], v17 offset:11552
	s_waitcnt lgkmcnt(11)
	v_fma_f32 v72, -v36, v100, v72
	v_fma_f32 v73, -v37, v101, v73
	v_fma_f32 v74, -v38, v102, v74
	v_fma_f32 v75, -v39, v103, v75
	ds_read_b128 v[36:39], v17 offset:11568
	s_waitcnt lgkmcnt(11)
	v_fma_f32 v72, -v40, v104, v72
	v_fma_f32 v73, -v41, v105, v73
	v_fma_f32 v74, -v42, v106, v74
	v_fma_f32 v75, -v43, v107, v75
	ds_read_b128 v[40:43], v17 offset:11584
	s_waitcnt lgkmcnt(11)
	v_fma_f32 v72, -v44, v108, v72
	v_fma_f32 v73, -v45, v109, v73
	v_fma_f32 v74, -v46, v110, v74
	v_fma_f32 v75, -v47, v111, v75
	ds_read_b128 v[44:47], v17 offset:11600
	s_waitcnt lgkmcnt(11)
	v_fma_f32 v72, -v48, v112, v72
	v_fma_f32 v73, -v49, v113, v73
	v_fma_f32 v74, -v50, v114, v74
	v_fma_f32 v75, -v51, v115, v75
	ds_read_b128 v[48:51], v17 offset:11616
	s_waitcnt lgkmcnt(11)
	v_fma_f32 v72, -v52, v116, v72
	v_fma_f32 v73, -v53, v117, v73
	v_fma_f32 v74, -v54, v118, v74
	v_fma_f32 v75, -v55, v119, v75
	ds_read_b128 v[52:55], v17 offset:11632
	s_waitcnt lgkmcnt(11)
	v_fma_f32 v72, -v56, v120, v72
	v_fma_f32 v73, -v57, v121, v73
	v_fma_f32 v74, -v58, v122, v74
	v_fma_f32 v75, -v59, v123, v75
	ds_read_b128 v[56:59], v17 offset:11648
	s_waitcnt lgkmcnt(11)
	v_fma_f32 v72, -v4, v124, v72
	v_fma_f32 v73, -v5, v125, v73
	v_fma_f32 v74, -v6, v126, v74
	v_fma_f32 v75, -v7, v127, v75
	ds_read_b128 v[4:7], v17 offset:11664
	s_waitcnt lgkmcnt(11)
	v_fma_f32 v72, -v8, v128, v72
	v_fma_f32 v73, -v9, v129, v73
	v_fma_f32 v74, -v10, v130, v74
	v_fma_f32 v75, -v11, v131, v75
	ds_read_b128 v[8:11], v17 offset:11680
	s_waitcnt lgkmcnt(11)
	v_fma_f32 v72, -v12, v132, v72
	v_fma_f32 v73, -v13, v133, v73
	v_fma_f32 v74, -v14, v134, v74
	v_fma_f32 v75, -v15, v135, v75
	ds_read_b128 v[12:15], v17 offset:11696
	v_add_f32_e32 v72, v72, v73
	v_add_f32_e32 v74, v74, v75
	v_add_f32_e32 v136, v136, v72
	v_add_f32_e32 v136, v136, v74
	s_waitcnt lgkmcnt(11)
	v_mul_f32_e64 v72, -v24, v92
	v_mul_f32_e64 v73, -v25, v93
	v_mul_f32_e64 v74, -v26, v94
	v_mul_f32_e64 v75, -v27, v95
	ds_read_b128 v[24:27], v17 offset:11776
	s_waitcnt lgkmcnt(11)
	v_fma_f32 v72, -v28, v96, v72
	v_fma_f32 v73, -v29, v97, v73
	v_fma_f32 v74, -v30, v98, v74
	v_fma_f32 v75, -v31, v99, v75
	ds_read_b128 v[28:31], v17 offset:11792
	s_waitcnt lgkmcnt(11)
	v_fma_f32 v72, -v32, v100, v72
	v_fma_f32 v73, -v33, v101, v73
	v_fma_f32 v74, -v34, v102, v74
	v_fma_f32 v75, -v35, v103, v75
	ds_read_b128 v[32:35], v17 offset:11808
	s_waitcnt lgkmcnt(11)
	v_fma_f32 v72, -v36, v104, v72
	v_fma_f32 v73, -v37, v105, v73
	v_fma_f32 v74, -v38, v106, v74
	v_fma_f32 v75, -v39, v107, v75
	ds_read_b128 v[36:39], v17 offset:11824
	s_waitcnt lgkmcnt(11)
; #define LAS __attribute__((address_space(3)))
; __device__ __forceinline__ void even_prep(const Ctx& c, const Params& p, int e) {
;     ...
; #pragma unroll
;             for (int i = 1; i < 64; ++i) { const LAS f32x4* Lr = (const LAS f32x4*)(Lv + i * 64); float a0 = x[i], a1 = 0.f;
; #pragma unroll
;                 for (int j4 = 0; j4 < (i + 3) / 4; ++j4) { const f32x4 l = Lr[j4];
;                     if (4 * j4 + 0 < i) a0 -= l[0] * x[4 * j4 + 0];
;                     if (4 * j4 + 1 < i) a1 -= l[1] * x[4 * j4 + 1];
;                     if (4 * j4 + 2 < i) a0 -= l[2] * x[4 * j4 + 2];
;                     if (4 * j4 + 3 < i) a1 -= l[3] * x[4 * j4 + 3]; }
;                 x[i] = a0 + a1; }
	v_fma_f32 v72, -v40, v108, v72
	v_fma_f32 v73, -v41, v109, v73
	v_fma_f32 v74, -v42, v110, v74
	v_fma_f32 v75, -v43, v111, v75
	ds_read_b128 v[40:43], v17 offset:11840
	s_waitcnt lgkmcnt(11)
	v_fma_f32 v72, -v44, v112, v72
	v_fma_f32 v73, -v45, v113, v73
	v_fma_f32 v74, -v46, v114, v74
	v_fma_f32 v75, -v47, v115, v75
	ds_read_b128 v[44:47], v17 offset:11856
	s_waitcnt lgkmcnt(11)
	v_fma_f32 v72, -v48, v116, v72
	v_fma_f32 v73, -v49, v117, v73
	v_fma_f32 v74, -v50, v118, v74
	v_fma_f32 v75, -v51, v119, v75
	ds_read_b128 v[48:51], v17 offset:11872
	s_waitcnt lgkmcnt(11)
	v_fma_f32 v72, -v52, v120, v72
	v_fma_f32 v73, -v53, v121, v73
	v_fma_f32 v74, -v54, v122, v74
	v_fma_f32 v75, -v55, v123, v75
	ds_read_b128 v[52:55], v17 offset:11888
	s_waitcnt lgkmcnt(11)
	v_fma_f32 v72, -v56, v124, v72
	v_fma_f32 v73, -v57, v125, v73
	v_fma_f32 v74, -v58, v126, v74
	v_fma_f32 v75, -v59, v127, v75
	ds_read_b128 v[56:59], v17 offset:11904
	s_waitcnt lgkmcnt(11)
	v_fma_f32 v72, -v4, v128, v72
	v_fma_f32 v73, -v5, v129, v73
	v_fma_f32 v74, -v6, v130, v74
	v_fma_f32 v75, -v7, v131, v75
	ds_read_b128 v[4:7], v17 offset:11920
	s_waitcnt lgkmcnt(11)
	v_fma_f32 v72, -v8, v132, v72
	v_fma_f32 v73, -v9, v133, v73
	v_fma_f32 v74, -v10, v134, v74
	v_fma_f32 v75, -v11, v135, v75
	ds_read_b128 v[8:11], v17 offset:11936
	s_waitcnt lgkmcnt(11)
	v_fma_f32 v72, -v12, v136, v72
	ds_read_b128 v[12:15], v17 offset:11952
	v_add_f32_e32 v72, v72, v73
	v_add_f32_e32 v74, v74, v75
	v_add_f32_e32 v137, v137, v72
	v_add_f32_e32 v137, v137, v74
	s_waitcnt lgkmcnt(11)
	v_mul_f32_e64 v72, -v24, v92
	v_mul_f32_e64 v73, -v25, v93
	v_mul_f32_e64 v74, -v26, v94
	v_mul_f32_e64 v75, -v27, v95
	ds_read_b128 v[24:27], v17 offset:12032
	s_waitcnt lgkmcnt(11)
	v_fma_f32 v72, -v28, v96, v72
	v_fma_f32 v73, -v29, v97, v73
	v_fma_f32 v74, -v30, v98, v74
	v_fma_f32 v75, -v31, v99, v75
	ds_read_b128 v[28:31], v17 offset:12048
	s_waitcnt lgkmcnt(11)
	v_fma_f32 v72, -v32, v100, v72
	v_fma_f32 v73, -v33, v101, v73
	v_fma_f32 v74, -v34, v102, v74
	v_fma_f32 v75, -v35, v103, v75
	ds_read_b128 v[32:35], v17 offset:12064
	s_waitcnt lgkmcnt(11)
	v_fma_f32 v72, -v36, v104, v72
	v_fma_f32 v73, -v37, v105, v73
	v_fma_f32 v74, -v38, v106, v74
	v_fma_f32 v75, -v39, v107, v75
	ds_read_b128 v[36:39], v17 offset:12080
	s_waitcnt lgkmcnt(11)
	v_fma_f32 v72, -v40, v108, v72
	v_fma_f32 v73, -v41, v109, v73
	v_fma_f32 v74, -v42, v110, v74
	v_fma_f32 v75, -v43, v111, v75
	ds_read_b128 v[40:43], v17 offset:12096
	s_waitcnt lgkmcnt(11)
	v_fma_f32 v72, -v44, v112, v72
	v_fma_f32 v73, -v45, v113, v73
	v_fma_f32 v74, -v46, v114, v74
	v_fma_f32 v75, -v47, v115, v75
	ds_read_b128 v[44:47], v17 offset:12112
	s_waitcnt lgkmcnt(11)
	v_fma_f32 v72, -v48, v116, v72
	v_fma_f32 v73, -v49, v117, v73
	v_fma_f32 v74, -v50, v118, v74
	v_fma_f32 v75, -v51, v119, v75
	ds_read_b128 v[48:51], v17 offset:12128
	s_waitcnt lgkmcnt(11)
	v_fma_f32 v72, -v52, v120, v72
	v_fma_f32 v73, -v53, v121, v73
	v_fma_f32 v74, -v54, v122, v74
	v_fma_f32 v75, -v55, v123, v75
	ds_read_b128 v[52:55], v17 offset:12144
	s_waitcnt lgkmcnt(11)
	v_fma_f32 v72, -v56, v124, v72
	v_fma_f32 v73, -v57, v125, v73
	v_fma_f32 v74, -v58, v126, v74
	v_fma_f32 v75, -v59, v127, v75
	ds_read_b128 v[56:59], v17 offset:12160
	s_waitcnt lgkmcnt(11)
	v_fma_f32 v72, -v4, v128, v72
	v_fma_f32 v73, -v5, v129, v73
	v_fma_f32 v74, -v6, v130, v74
	v_fma_f32 v75, -v7, v131, v75
	ds_read_b128 v[4:7], v17 offset:12176
	s_waitcnt lgkmcnt(11)
	v_fma_f32 v72, -v8, v132, v72
	v_fma_f32 v73, -v9, v133, v73
	v_fma_f32 v74, -v10, v134, v74
	v_fma_f32 v75, -v11, v135, v75
	ds_read_b128 v[8:11], v17 offset:12192
	s_waitcnt lgkmcnt(11)
	v_fma_f32 v72, -v12, v136, v72
	v_fma_f32 v73, -v13, v137, v73
	ds_read_b128 v[12:15], v17 offset:12208
	v_add_f32_e32 v72, v72, v73
	v_add_f32_e32 v74, v74, v75
	v_add_f32_e32 v138, v138, v72
	v_add_f32_e32 v138, v138, v74
	s_waitcnt lgkmcnt(11)
	v_mul_f32_e64 v72, -v24, v92
	v_mul_f32_e64 v73, -v25, v93
	v_mul_f32_e64 v74, -v26, v94
	v_mul_f32_e64 v75, -v27, v95
	ds_read_b128 v[24:27], v17 offset:12288
	s_waitcnt lgkmcnt(11)
	v_fma_f32 v72, -v28, v96, v72
	v_fma_f32 v73, -v29, v97, v73
	v_fma_f32 v74, -v30, v98, v74
	v_fma_f32 v75, -v31, v99, v75
	ds_read_b128 v[28:31], v17 offset:12304
	s_waitcnt lgkmcnt(11)
	v_fma_f32 v72, -v32, v100, v72
	v_fma_f32 v73, -v33, v101, v73
	v_fma_f32 v74, -v34, v102, v74
	v_fma_f32 v75, -v35, v103, v75
	ds_read_b128 v[32:35], v17 offset:12320
	s_waitcnt lgkmcnt(11)
	v_fma_f32 v72, -v36, v104, v72
	v_fma_f32 v73, -v37, v105, v73
	v_fma_f32 v74, -v38, v106, v74
	v_fma_f32 v75, -v39, v107, v75
	ds_read_b128 v[36:39], v17 offset:12336
	s_waitcnt lgkmcnt(11)
	v_fma_f32 v72, -v40, v108, v72
	v_fma_f32 v73, -v41, v109, v73
	v_fma_f32 v74, -v42, v110, v74
	v_fma_f32 v75, -v43, v111, v75
	ds_read_b128 v[40:43], v17 offset:12352
	s_waitcnt lgkmcnt(11)
	v_fma_f32 v72, -v44, v112, v72
	v_fma_f32 v73, -v45, v113, v73
	v_fma_f32 v74, -v46, v114, v74
	v_fma_f32 v75, -v47, v115, v75
	ds_read_b128 v[44:47], v17 offset:12368
	s_waitcnt lgkmcnt(11)
	v_fma_f32 v72, -v48, v116, v72
	v_fma_f32 v73, -v49, v117, v73
	v_fma_f32 v74, -v50, v118, v74
	v_fma_f32 v75, -v51, v119, v75
	ds_read_b128 v[48:51], v17 offset:12384
	s_waitcnt lgkmcnt(11)
	v_fma_f32 v72, -v52, v120, v72
	v_fma_f32 v73, -v53, v121, v73
	v_fma_f32 v74, -v54, v122, v74
	v_fma_f32 v75, -v55, v123, v75
	ds_read_b128 v[52:55], v17 offset:12400
	s_waitcnt lgkmcnt(11)
	v_fma_f32 v72, -v56, v124, v72
	v_fma_f32 v73, -v57, v125, v73
	v_fma_f32 v74, -v58, v126, v74
	v_fma_f32 v75, -v59, v127, v75
	ds_read_b128 v[56:59], v17 offset:12416
	s_waitcnt lgkmcnt(11)
; #define LAS __attribute__((address_space(3)))
; __device__ __forceinline__ void even_prep(const Ctx& c, const Params& p, int e) {
;     ...
; #pragma unroll
;             for (int i = 1; i < 64; ++i) { const LAS f32x4* Lr = (const LAS f32x4*)(Lv + i * 64); float a0 = x[i], a1 = 0.f;
; #pragma unroll
;                 for (int j4 = 0; j4 < (i + 3) / 4; ++j4) { const f32x4 l = Lr[j4];
;                     if (4 * j4 + 0 < i) a0 -= l[0] * x[4 * j4 + 0];
;                     if (4 * j4 + 1 < i) a1 -= l[1] * x[4 * j4 + 1];
;                     if (4 * j4 + 2 < i) a0 -= l[2] * x[4 * j4 + 2];
;                     if (4 * j4 + 3 < i) a1 -= l[3] * x[4 * j4 + 3]; }
;                 x[i] = a0 + a1; }
	v_fma_f32 v72, -v4, v128, v72
	v_fma_f32 v73, -v5, v129, v73
	v_fma_f32 v74, -v6, v130, v74
	v_fma_f32 v75, -v7, v131, v75
	ds_read_b128 v[4:7], v17 offset:12432
	s_waitcnt lgkmcnt(11)
	v_fma_f32 v72, -v8, v132, v72
	v_fma_f32 v73, -v9, v133, v73
	v_fma_f32 v74, -v10, v134, v74
	v_fma_f32 v75, -v11, v135, v75
	ds_read_b128 v[8:11], v17 offset:12448
	s_waitcnt lgkmcnt(11)
	v_fma_f32 v72, -v12, v136, v72
	v_fma_f32 v73, -v13, v137, v73
	v_fma_f32 v74, -v14, v138, v74
	ds_read_b128 v[12:15], v17 offset:12464
	v_add_f32_e32 v72, v72, v73
	v_add_f32_e32 v74, v74, v75
	v_add_f32_e32 v139, v139, v72
	v_add_f32_e32 v139, v139, v74
	s_waitcnt lgkmcnt(11)
	v_mul_f32_e64 v72, -v24, v92
	v_mul_f32_e64 v73, -v25, v93
	v_mul_f32_e64 v74, -v26, v94
	v_mul_f32_e64 v75, -v27, v95
	ds_read_b128 v[24:27], v17 offset:12544
	s_waitcnt lgkmcnt(11)
	v_fma_f32 v72, -v28, v96, v72
	v_fma_f32 v73, -v29, v97, v73
	v_fma_f32 v74, -v30, v98, v74
	v_fma_f32 v75, -v31, v99, v75
	ds_read_b128 v[28:31], v17 offset:12560
	s_waitcnt lgkmcnt(11)
	v_fma_f32 v72, -v32, v100, v72
	v_fma_f32 v73, -v33, v101, v73
	v_fma_f32 v74, -v34, v102, v74
	v_fma_f32 v75, -v35, v103, v75
	ds_read_b128 v[32:35], v17 offset:12576
	s_waitcnt lgkmcnt(11)
	v_fma_f32 v72, -v36, v104, v72
	v_fma_f32 v73, -v37, v105, v73
	v_fma_f32 v74, -v38, v106, v74
	v_fma_f32 v75, -v39, v107, v75
	ds_read_b128 v[36:39], v17 offset:12592
	s_waitcnt lgkmcnt(11)
	v_fma_f32 v72, -v40, v108, v72
	v_fma_f32 v73, -v41, v109, v73
	v_fma_f32 v74, -v42, v110, v74
	v_fma_f32 v75, -v43, v111, v75
	ds_read_b128 v[40:43], v17 offset:12608
	s_waitcnt lgkmcnt(11)
	v_fma_f32 v72, -v44, v112, v72
	v_fma_f32 v73, -v45, v113, v73
	v_fma_f32 v74, -v46, v114, v74
	v_fma_f32 v75, -v47, v115, v75
	ds_read_b128 v[44:47], v17 offset:12624
	s_waitcnt lgkmcnt(11)
	v_fma_f32 v72, -v48, v116, v72
	v_fma_f32 v73, -v49, v117, v73
	v_fma_f32 v74, -v50, v118, v74
	v_fma_f32 v75, -v51, v119, v75
	ds_read_b128 v[48:51], v17 offset:12640
	s_waitcnt lgkmcnt(11)
	v_fma_f32 v72, -v52, v120, v72
	v_fma_f32 v73, -v53, v121, v73
	v_fma_f32 v74, -v54, v122, v74
	v_fma_f32 v75, -v55, v123, v75
	ds_read_b128 v[52:55], v17 offset:12656
	s_waitcnt lgkmcnt(11)
	v_fma_f32 v72, -v56, v124, v72
	v_fma_f32 v73, -v57, v125, v73
	v_fma_f32 v74, -v58, v126, v74
	v_fma_f32 v75, -v59, v127, v75
	ds_read_b128 v[56:59], v17 offset:12672
	s_waitcnt lgkmcnt(11)
	v_fma_f32 v72, -v4, v128, v72
	v_fma_f32 v73, -v5, v129, v73
	v_fma_f32 v74, -v6, v130, v74
	v_fma_f32 v75, -v7, v131, v75
	ds_read_b128 v[4:7], v17 offset:12688
	s_waitcnt lgkmcnt(11)
	v_fma_f32 v72, -v8, v132, v72
	v_fma_f32 v73, -v9, v133, v73
	v_fma_f32 v74, -v10, v134, v74
	v_fma_f32 v75, -v11, v135, v75
	ds_read_b128 v[8:11], v17 offset:12704
	s_waitcnt lgkmcnt(11)
	v_fma_f32 v72, -v12, v136, v72
	v_fma_f32 v73, -v13, v137, v73
	v_fma_f32 v74, -v14, v138, v74
	v_fma_f32 v75, -v15, v139, v75
	ds_read_b128 v[12:15], v17 offset:12720
	v_add_f32_e32 v72, v72, v73
	v_add_f32_e32 v74, v74, v75
	v_add_f32_e32 v140, v140, v72
	v_add_f32_e32 v140, v140, v74
	s_waitcnt lgkmcnt(11)
	v_mul_f32_e64 v72, -v24, v92
	v_mul_f32_e64 v73, -v25, v93
	v_mul_f32_e64 v74, -v26, v94
	v_mul_f32_e64 v75, -v27, v95
	ds_read_b128 v[24:27], v17 offset:12736
	s_waitcnt lgkmcnt(11)
	v_fma_f32 v72, -v28, v96, v72
	v_fma_f32 v73, -v29, v97, v73
	v_fma_f32 v74, -v30, v98, v74
	v_fma_f32 v75, -v31, v99, v75
	ds_read_b128 v[28:31], v17 offset:12800
	s_waitcnt lgkmcnt(11)
	v_fma_f32 v72, -v32, v100, v72
	v_fma_f32 v73, -v33, v101, v73
	v_fma_f32 v74, -v34, v102, v74
	v_fma_f32 v75, -v35, v103, v75
	ds_read_b128 v[32:35], v17 offset:12816
	s_waitcnt lgkmcnt(11)
	v_fma_f32 v72, -v36, v104, v72
	v_fma_f32 v73, -v37, v105, v73
	v_fma_f32 v74, -v38, v106, v74
	v_fma_f32 v75, -v39, v107, v75
	ds_read_b128 v[36:39], v17 offset:12832
	s_waitcnt lgkmcnt(11)
	v_fma_f32 v72, -v40, v108, v72
	v_fma_f32 v73, -v41, v109, v73
	v_fma_f32 v74, -v42, v110, v74
	v_fma_f32 v75, -v43, v111, v75
	ds_read_b128 v[40:43], v17 offset:12848
	s_waitcnt lgkmcnt(11)
	v_fma_f32 v72, -v44, v112, v72
	v_fma_f32 v73, -v45, v113, v73
	v_fma_f32 v74, -v46, v114, v74
	v_fma_f32 v75, -v47, v115, v75
	ds_read_b128 v[44:47], v17 offset:12864
	s_waitcnt lgkmcnt(11)
	v_fma_f32 v72, -v48, v116, v72
	v_fma_f32 v73, -v49, v117, v73
	v_fma_f32 v74, -v50, v118, v74
	v_fma_f32 v75, -v51, v119, v75
	ds_read_b128 v[48:51], v17 offset:12880
	s_waitcnt lgkmcnt(11)
	v_fma_f32 v72, -v52, v120, v72
	v_fma_f32 v73, -v53, v121, v73
	v_fma_f32 v74, -v54, v122, v74
	v_fma_f32 v75, -v55, v123, v75
	ds_read_b128 v[52:55], v17 offset:12896
	s_waitcnt lgkmcnt(11)
	v_fma_f32 v72, -v56, v124, v72
	v_fma_f32 v73, -v57, v125, v73
	v_fma_f32 v74, -v58, v126, v74
	v_fma_f32 v75, -v59, v127, v75
	ds_read_b128 v[56:59], v17 offset:12912
	s_waitcnt lgkmcnt(11)
	v_fma_f32 v72, -v4, v128, v72
	v_fma_f32 v73, -v5, v129, v73
	v_fma_f32 v74, -v6, v130, v74
	v_fma_f32 v75, -v7, v131, v75
	ds_read_b128 v[4:7], v17 offset:12928
	s_waitcnt lgkmcnt(11)
	v_fma_f32 v72, -v8, v132, v72
	v_fma_f32 v73, -v9, v133, v73
	v_fma_f32 v74, -v10, v134, v74
	v_fma_f32 v75, -v11, v135, v75
	ds_read_b128 v[8:11], v17 offset:12944
	s_waitcnt lgkmcnt(11)
	v_fma_f32 v72, -v12, v136, v72
	v_fma_f32 v73, -v13, v137, v73
	v_fma_f32 v74, -v14, v138, v74
	v_fma_f32 v75, -v15, v139, v75
	ds_read_b128 v[12:15], v17 offset:12960
	s_waitcnt lgkmcnt(11)
	v_fma_f32 v72, -v24, v140, v72
	ds_read_b128 v[24:27], v17 offset:12976
	v_add_f32_e32 v72, v72, v73
	v_add_f32_e32 v74, v74, v75
	v_add_f32_e32 v141, v141, v72
	v_add_f32_e32 v141, v141, v74
	s_waitcnt lgkmcnt(11)
; #define LAS __attribute__((address_space(3)))
; __device__ __forceinline__ void even_prep(const Ctx& c, const Params& p, int e) {
;     ...
; #pragma unroll
;             for (int i = 1; i < 64; ++i) { const LAS f32x4* Lr = (const LAS f32x4*)(Lv + i * 64); float a0 = x[i], a1 = 0.f;
; #pragma unroll
;                 for (int j4 = 0; j4 < (i + 3) / 4; ++j4) { const f32x4 l = Lr[j4];
;                     if (4 * j4 + 0 < i) a0 -= l[0] * x[4 * j4 + 0];
;                     if (4 * j4 + 1 < i) a1 -= l[1] * x[4 * j4 + 1];
;                     if (4 * j4 + 2 < i) a0 -= l[2] * x[4 * j4 + 2];
;                     if (4 * j4 + 3 < i) a1 -= l[3] * x[4 * j4 + 3]; }
;                 x[i] = a0 + a1; }
	v_mul_f32_e64 v72, -v28, v92
	v_mul_f32_e64 v73, -v29, v93
	v_mul_f32_e64 v74, -v30, v94
	v_mul_f32_e64 v75, -v31, v95
	ds_read_b128 v[28:31], v17 offset:12992
	s_waitcnt lgkmcnt(11)
	v_fma_f32 v72, -v32, v96, v72
	v_fma_f32 v73, -v33, v97, v73
	v_fma_f32 v74, -v34, v98, v74
	v_fma_f32 v75, -v35, v99, v75
	ds_read_b128 v[32:35], v17 offset:13056
	s_waitcnt lgkmcnt(11)
	v_fma_f32 v72, -v36, v100, v72
	v_fma_f32 v73, -v37, v101, v73
	v_fma_f32 v74, -v38, v102, v74
	v_fma_f32 v75, -v39, v103, v75
	ds_read_b128 v[36:39], v17 offset:13072
	s_waitcnt lgkmcnt(11)
	v_fma_f32 v72, -v40, v104, v72
	v_fma_f32 v73, -v41, v105, v73
	v_fma_f32 v74, -v42, v106, v74
	v_fma_f32 v75, -v43, v107, v75
	ds_read_b128 v[40:43], v17 offset:13088
	s_waitcnt lgkmcnt(11)
	v_fma_f32 v72, -v44, v108, v72
	v_fma_f32 v73, -v45, v109, v73
	v_fma_f32 v74, -v46, v110, v74
	v_fma_f32 v75, -v47, v111, v75
	ds_read_b128 v[44:47], v17 offset:13104
	s_waitcnt lgkmcnt(11)
	v_fma_f32 v72, -v48, v112, v72
	v_fma_f32 v73, -v49, v113, v73
	v_fma_f32 v74, -v50, v114, v74
	v_fma_f32 v75, -v51, v115, v75
	ds_read_b128 v[48:51], v17 offset:13120
	s_waitcnt lgkmcnt(11)
	v_fma_f32 v72, -v52, v116, v72
	v_fma_f32 v73, -v53, v117, v73
	v_fma_f32 v74, -v54, v118, v74
	v_fma_f32 v75, -v55, v119, v75
	ds_read_b128 v[52:55], v17 offset:13136
	s_waitcnt lgkmcnt(11)
	v_fma_f32 v72, -v56, v120, v72
	v_fma_f32 v73, -v57, v121, v73
	v_fma_f32 v74, -v58, v122, v74
	v_fma_f32 v75, -v59, v123, v75
	ds_read_b128 v[56:59], v17 offset:13152
	s_waitcnt lgkmcnt(11)
	v_fma_f32 v72, -v4, v124, v72
	v_fma_f32 v73, -v5, v125, v73
	v_fma_f32 v74, -v6, v126, v74
	v_fma_f32 v75, -v7, v127, v75
	ds_read_b128 v[4:7], v17 offset:13168
	s_waitcnt lgkmcnt(11)
	v_fma_f32 v72, -v8, v128, v72
	v_fma_f32 v73, -v9, v129, v73
	v_fma_f32 v74, -v10, v130, v74
	v_fma_f32 v75, -v11, v131, v75
	ds_read_b128 v[8:11], v17 offset:13184
	s_waitcnt lgkmcnt(11)
	v_fma_f32 v72, -v12, v132, v72
	v_fma_f32 v73, -v13, v133, v73
	v_fma_f32 v74, -v14, v134, v74
	v_fma_f32 v75, -v15, v135, v75
	ds_read_b128 v[12:15], v17 offset:13200
	s_waitcnt lgkmcnt(11)
	v_fma_f32 v72, -v24, v136, v72
	v_fma_f32 v73, -v25, v137, v73
	v_fma_f32 v74, -v26, v138, v74
	v_fma_f32 v75, -v27, v139, v75
	ds_read_b128 v[24:27], v17 offset:13216
	s_waitcnt lgkmcnt(11)
	v_fma_f32 v72, -v28, v140, v72
	v_fma_f32 v73, -v29, v141, v73
	ds_read_b128 v[28:31], v17 offset:13232
	v_add_f32_e32 v72, v72, v73
	v_add_f32_e32 v74, v74, v75
	v_add_f32_e32 v142, v142, v72
	v_add_f32_e32 v142, v142, v74
	s_waitcnt lgkmcnt(11)
	v_mul_f32_e64 v72, -v32, v92
	v_mul_f32_e64 v73, -v33, v93
	v_mul_f32_e64 v74, -v34, v94
	v_mul_f32_e64 v75, -v35, v95
	ds_read_b128 v[32:35], v17 offset:13248
	s_waitcnt lgkmcnt(11)
	v_fma_f32 v72, -v36, v96, v72
	v_fma_f32 v73, -v37, v97, v73
	v_fma_f32 v74, -v38, v98, v74
	v_fma_f32 v75, -v39, v99, v75
	ds_read_b128 v[36:39], v17 offset:13312
	s_waitcnt lgkmcnt(11)
	v_fma_f32 v72, -v40, v100, v72
	v_fma_f32 v73, -v41, v101, v73
	v_fma_f32 v74, -v42, v102, v74
	v_fma_f32 v75, -v43, v103, v75
	ds_read_b128 v[40:43], v17 offset:13328
	s_waitcnt lgkmcnt(11)
	v_fma_f32 v72, -v44, v104, v72
	v_fma_f32 v73, -v45, v105, v73
	v_fma_f32 v74, -v46, v106, v74
	v_fma_f32 v75, -v47, v107, v75
	ds_read_b128 v[44:47], v17 offset:13344
	s_waitcnt lgkmcnt(11)
	v_fma_f32 v72, -v48, v108, v72
	v_fma_f32 v73, -v49, v109, v73
	v_fma_f32 v74, -v50, v110, v74
	v_fma_f32 v75, -v51, v111, v75
	ds_read_b128 v[48:51], v17 offset:13360
	s_waitcnt lgkmcnt(11)
	v_fma_f32 v72, -v52, v112, v72
	v_fma_f32 v73, -v53, v113, v73
	v_fma_f32 v74, -v54, v114, v74
	v_fma_f32 v75, -v55, v115, v75
	ds_read_b128 v[52:55], v17 offset:13376
	s_waitcnt lgkmcnt(11)
	v_fma_f32 v72, -v56, v116, v72
	v_fma_f32 v73, -v57, v117, v73
	v_fma_f32 v74, -v58, v118, v74
	v_fma_f32 v75, -v59, v119, v75
	ds_read_b128 v[56:59], v17 offset:13392
	s_waitcnt lgkmcnt(11)
	v_fma_f32 v72, -v4, v120, v72
	v_fma_f32 v73, -v5, v121, v73
	v_fma_f32 v74, -v6, v122, v74
	v_fma_f32 v75, -v7, v123, v75
	ds_read_b128 v[4:7], v17 offset:13408
	s_waitcnt lgkmcnt(11)
	v_fma_f32 v72, -v8, v124, v72
	v_fma_f32 v73, -v9, v125, v73
	v_fma_f32 v74, -v10, v126, v74
	v_fma_f32 v75, -v11, v127, v75
	ds_read_b128 v[8:11], v17 offset:13424
	s_waitcnt lgkmcnt(11)
	v_fma_f32 v72, -v12, v128, v72
	v_fma_f32 v73, -v13, v129, v73
	v_fma_f32 v74, -v14, v130, v74
	v_fma_f32 v75, -v15, v131, v75
	ds_read_b128 v[12:15], v17 offset:13440
	s_waitcnt lgkmcnt(11)
	v_fma_f32 v72, -v24, v132, v72
	v_fma_f32 v73, -v25, v133, v73
	v_fma_f32 v74, -v26, v134, v74
	v_fma_f32 v75, -v27, v135, v75
	ds_read_b128 v[24:27], v17 offset:13456
	s_waitcnt lgkmcnt(11)
	v_fma_f32 v72, -v28, v136, v72
	v_fma_f32 v73, -v29, v137, v73
	v_fma_f32 v74, -v30, v138, v74
	v_fma_f32 v75, -v31, v139, v75
	ds_read_b128 v[28:31], v17 offset:13472
	s_waitcnt lgkmcnt(11)
	v_fma_f32 v72, -v32, v140, v72
	v_fma_f32 v73, -v33, v141, v73
	v_fma_f32 v74, -v34, v142, v74
	ds_read_b128 v[32:35], v17 offset:13488
	v_add_f32_e32 v72, v72, v73
	v_add_f32_e32 v74, v74, v75
	v_add_f32_e32 v143, v143, v72
	v_add_f32_e32 v143, v143, v74
	s_waitcnt lgkmcnt(11)
	v_mul_f32_e64 v72, -v36, v92
	v_mul_f32_e64 v73, -v37, v93
	v_mul_f32_e64 v74, -v38, v94
	v_mul_f32_e64 v75, -v39, v95
	ds_read_b128 v[36:39], v17 offset:13504
	s_waitcnt lgkmcnt(11)
	v_fma_f32 v72, -v40, v96, v72
	v_fma_f32 v73, -v41, v97, v73
	v_fma_f32 v74, -v42, v98, v74
	v_fma_f32 v75, -v43, v99, v75
	ds_read_b128 v[40:43], v17 offset:13568
	s_waitcnt lgkmcnt(11)
	v_fma_f32 v72, -v44, v100, v72
	v_fma_f32 v73, -v45, v101, v73
	v_fma_f32 v74, -v46, v102, v74
	v_fma_f32 v75, -v47, v103, v75
	ds_read_b128 v[44:47], v17 offset:13584
	s_waitcnt lgkmcnt(11)
; #define LAS __attribute__((address_space(3)))
; __device__ __forceinline__ void even_prep(const Ctx& c, const Params& p, int e) {
;     ...
;             for (int i = 1; i < 64; ++i) { const LAS f32x4* Lr = (const LAS f32x4*)(Lv + i * 64); float a0 = x[i], a1 = 0.f;
; #pragma unroll
;                 for (int j4 = 0; j4 < (i + 3) / 4; ++j4) { const f32x4 l = Lr[j4];
;                     if (4 * j4 + 0 < i) a0 -= l[0] * x[4 * j4 + 0];
;                     if (4 * j4 + 1 < i) a1 -= l[1] * x[4 * j4 + 1];
;                     if (4 * j4 + 2 < i) a0 -= l[2] * x[4 * j4 + 2];
;                     if (4 * j4 + 3 < i) a1 -= l[3] * x[4 * j4 + 3]; }
;                 x[i] = a0 + a1; }
	v_fma_f32 v72, -v48, v104, v72
	v_fma_f32 v73, -v49, v105, v73
	v_fma_f32 v74, -v50, v106, v74
	v_fma_f32 v75, -v51, v107, v75
	ds_read_b128 v[48:51], v17 offset:13600
	s_waitcnt lgkmcnt(11)
	v_fma_f32 v72, -v52, v108, v72
	v_fma_f32 v73, -v53, v109, v73
	v_fma_f32 v74, -v54, v110, v74
	v_fma_f32 v75, -v55, v111, v75
	ds_read_b128 v[52:55], v17 offset:13616
	s_waitcnt lgkmcnt(11)
	v_fma_f32 v72, -v56, v112, v72
	v_fma_f32 v73, -v57, v113, v73
	v_fma_f32 v74, -v58, v114, v74
	v_fma_f32 v75, -v59, v115, v75
	ds_read_b128 v[56:59], v17 offset:13632
	s_waitcnt lgkmcnt(11)
	v_fma_f32 v72, -v4, v116, v72
	v_fma_f32 v73, -v5, v117, v73
	v_fma_f32 v74, -v6, v118, v74
	v_fma_f32 v75, -v7, v119, v75
	ds_read_b128 v[4:7], v17 offset:13648
	s_waitcnt lgkmcnt(11)
	v_fma_f32 v72, -v8, v120, v72
	v_fma_f32 v73, -v9, v121, v73
	v_fma_f32 v74, -v10, v122, v74
	v_fma_f32 v75, -v11, v123, v75
	ds_read_b128 v[8:11], v17 offset:13664
	s_waitcnt lgkmcnt(11)
	v_fma_f32 v72, -v12, v124, v72
	v_fma_f32 v73, -v13, v125, v73
	v_fma_f32 v74, -v14, v126, v74
	v_fma_f32 v75, -v15, v127, v75
	ds_read_b128 v[12:15], v17 offset:13680
	s_waitcnt lgkmcnt(11)
	v_fma_f32 v72, -v24, v128, v72
	v_fma_f32 v73, -v25, v129, v73
	v_fma_f32 v74, -v26, v130, v74
	v_fma_f32 v75, -v27, v131, v75
	ds_read_b128 v[24:27], v17 offset:13696
	s_waitcnt lgkmcnt(11)
	v_fma_f32 v72, -v28, v132, v72
	v_fma_f32 v73, -v29, v133, v73
	v_fma_f32 v74, -v30, v134, v74
	v_fma_f32 v75, -v31, v135, v75
	ds_read_b128 v[28:31], v17 offset:13712
	s_waitcnt lgkmcnt(11)
	v_fma_f32 v72, -v32, v136, v72
	v_fma_f32 v73, -v33, v137, v73
	v_fma_f32 v74, -v34, v138, v74
	v_fma_f32 v75, -v35, v139, v75
	ds_read_b128 v[32:35], v17 offset:13728
	s_waitcnt lgkmcnt(11)
	v_fma_f32 v72, -v36, v140, v72
	v_fma_f32 v73, -v37, v141, v73
	v_fma_f32 v74, -v38, v142, v74
	v_fma_f32 v75, -v39, v143, v75
	ds_read_b128 v[36:39], v17 offset:13744
	v_add_f32_e32 v72, v72, v73
	v_add_f32_e32 v74, v74, v75
	v_add_f32_e32 v60, v60, v72
	v_add_f32_e32 v60, v60, v74
	s_waitcnt lgkmcnt(11)
	v_mul_f32_e64 v72, -v40, v92
	v_mul_f32_e64 v73, -v41, v93
	v_mul_f32_e64 v74, -v42, v94
	v_mul_f32_e64 v75, -v43, v95
	ds_read_b128 v[40:43], v17 offset:13760
	s_waitcnt lgkmcnt(11)
	v_fma_f32 v72, -v44, v96, v72
	v_fma_f32 v73, -v45, v97, v73
	v_fma_f32 v74, -v46, v98, v74
	v_fma_f32 v75, -v47, v99, v75
	ds_read_b128 v[44:47], v17 offset:13776
	s_waitcnt lgkmcnt(11)
	v_fma_f32 v72, -v48, v100, v72
	v_fma_f32 v73, -v49, v101, v73
	v_fma_f32 v74, -v50, v102, v74
	v_fma_f32 v75, -v51, v103, v75
	ds_read_b128 v[48:51], v17 offset:13824
	s_waitcnt lgkmcnt(11)
	v_fma_f32 v72, -v52, v104, v72
	v_fma_f32 v73, -v53, v105, v73
	v_fma_f32 v74, -v54, v106, v74
	v_fma_f32 v75, -v55, v107, v75
	ds_read_b128 v[52:55], v17 offset:13840
	s_waitcnt lgkmcnt(11)
	v_fma_f32 v72, -v56, v108, v72
	v_fma_f32 v73, -v57, v109, v73
	v_fma_f32 v74, -v58, v110, v74
	v_fma_f32 v75, -v59, v111, v75
	ds_read_b128 v[56:59], v17 offset:13856
	s_waitcnt lgkmcnt(11)
	v_fma_f32 v72, -v4, v112, v72
	v_fma_f32 v73, -v5, v113, v73
	v_fma_f32 v74, -v6, v114, v74
	v_fma_f32 v75, -v7, v115, v75
	ds_read_b128 v[4:7], v17 offset:13872
	s_waitcnt lgkmcnt(11)
	v_fma_f32 v72, -v8, v116, v72
	v_fma_f32 v73, -v9, v117, v73
	v_fma_f32 v74, -v10, v118, v74
	v_fma_f32 v75, -v11, v119, v75
	ds_read_b128 v[8:11], v17 offset:13888
	s_waitcnt lgkmcnt(11)
	v_fma_f32 v72, -v12, v120, v72
	v_fma_f32 v73, -v13, v121, v73
	v_fma_f32 v74, -v14, v122, v74
	v_fma_f32 v75, -v15, v123, v75
	ds_read_b128 v[12:15], v17 offset:13904
	s_waitcnt lgkmcnt(11)
	v_fma_f32 v72, -v24, v124, v72
	v_fma_f32 v73, -v25, v125, v73
	v_fma_f32 v74, -v26, v126, v74
	v_fma_f32 v75, -v27, v127, v75
	ds_read_b128 v[24:27], v17 offset:13920
	s_waitcnt lgkmcnt(11)
	v_fma_f32 v72, -v28, v128, v72
	v_fma_f32 v73, -v29, v129, v73
	v_fma_f32 v74, -v30, v130, v74
	v_fma_f32 v75, -v31, v131, v75
	ds_read_b128 v[28:31], v17 offset:13936
	s_waitcnt lgkmcnt(11)
	v_fma_f32 v72, -v32, v132, v72
	v_fma_f32 v73, -v33, v133, v73
	v_fma_f32 v74, -v34, v134, v74
	v_fma_f32 v75, -v35, v135, v75
	ds_read_b128 v[32:35], v17 offset:13952
	s_waitcnt lgkmcnt(11)
	v_fma_f32 v72, -v36, v136, v72
	v_fma_f32 v73, -v37, v137, v73
	v_fma_f32 v74, -v38, v138, v74
	v_fma_f32 v75, -v39, v139, v75
	ds_read_b128 v[36:39], v17 offset:13968
	s_waitcnt lgkmcnt(11)
	v_fma_f32 v72, -v40, v140, v72
	v_fma_f32 v73, -v41, v141, v73
	v_fma_f32 v74, -v42, v142, v74
	v_fma_f32 v75, -v43, v143, v75
	ds_read_b128 v[40:43], v17 offset:13984
	s_waitcnt lgkmcnt(11)
	v_fma_f32 v72, -v44, v60, v72
	ds_read_b128 v[44:47], v17 offset:14000
	v_add_f32_e32 v72, v72, v73
	v_add_f32_e32 v74, v74, v75
	v_add_f32_e32 v61, v61, v72
	v_add_f32_e32 v61, v61, v74
	s_waitcnt lgkmcnt(11)
	v_mul_f32_e64 v72, -v48, v92
	v_mul_f32_e64 v73, -v49, v93
	v_mul_f32_e64 v74, -v50, v94
	v_mul_f32_e64 v75, -v51, v95
	ds_read_b128 v[48:51], v17 offset:14016
	s_waitcnt lgkmcnt(11)
	v_fma_f32 v72, -v52, v96, v72
	v_fma_f32 v73, -v53, v97, v73
	v_fma_f32 v74, -v54, v98, v74
	v_fma_f32 v75, -v55, v99, v75
	ds_read_b128 v[52:55], v17 offset:14032
	s_waitcnt lgkmcnt(11)
	v_fma_f32 v72, -v56, v100, v72
	v_fma_f32 v73, -v57, v101, v73
	v_fma_f32 v74, -v58, v102, v74
	v_fma_f32 v75, -v59, v103, v75
	ds_read_b128 v[56:59], v17 offset:14080
	s_waitcnt lgkmcnt(11)
	v_fma_f32 v72, -v4, v104, v72
	v_fma_f32 v73, -v5, v105, v73
	v_fma_f32 v74, -v6, v106, v74
	v_fma_f32 v75, -v7, v107, v75
	ds_read_b128 v[4:7], v17 offset:14096
	s_waitcnt lgkmcnt(11)
	v_fma_f32 v72, -v8, v108, v72
	v_fma_f32 v73, -v9, v109, v73
	v_fma_f32 v74, -v10, v110, v74
	v_fma_f32 v75, -v11, v111, v75
	ds_read_b128 v[8:11], v17 offset:14112
	s_waitcnt lgkmcnt(11)
; #define LAS __attribute__((address_space(3)))
; __device__ __forceinline__ void even_prep(const Ctx& c, const Params& p, int e) {
;     ...
;             for (int i = 1; i < 64; ++i) { const LAS f32x4* Lr = (const LAS f32x4*)(Lv + i * 64); float a0 = x[i], a1 = 0.f;
; #pragma unroll
;                 for (int j4 = 0; j4 < (i + 3) / 4; ++j4) { const f32x4 l = Lr[j4];
;                     if (4 * j4 + 0 < i) a0 -= l[0] * x[4 * j4 + 0];
;                     if (4 * j4 + 1 < i) a1 -= l[1] * x[4 * j4 + 1];
;                     if (4 * j4 + 2 < i) a0 -= l[2] * x[4 * j4 + 2];
;                     if (4 * j4 + 3 < i) a1 -= l[3] * x[4 * j4 + 3]; }
;                 x[i] = a0 + a1; }
	v_fma_f32 v72, -v12, v112, v72
	v_fma_f32 v73, -v13, v113, v73
	v_fma_f32 v74, -v14, v114, v74
	v_fma_f32 v75, -v15, v115, v75
	ds_read_b128 v[12:15], v17 offset:14128
	s_waitcnt lgkmcnt(11)
	v_fma_f32 v72, -v24, v116, v72
	v_fma_f32 v73, -v25, v117, v73
	v_fma_f32 v74, -v26, v118, v74
	v_fma_f32 v75, -v27, v119, v75
	ds_read_b128 v[24:27], v17 offset:14144
	s_waitcnt lgkmcnt(11)
	v_fma_f32 v72, -v28, v120, v72
	v_fma_f32 v73, -v29, v121, v73
	v_fma_f32 v74, -v30, v122, v74
	v_fma_f32 v75, -v31, v123, v75
	ds_read_b128 v[28:31], v17 offset:14160
	s_waitcnt lgkmcnt(11)
	v_fma_f32 v72, -v32, v124, v72
	v_fma_f32 v73, -v33, v125, v73
	v_fma_f32 v74, -v34, v126, v74
	v_fma_f32 v75, -v35, v127, v75
	ds_read_b128 v[32:35], v17 offset:14176
	s_waitcnt lgkmcnt(11)
	v_fma_f32 v72, -v36, v128, v72
	v_fma_f32 v73, -v37, v129, v73
	v_fma_f32 v74, -v38, v130, v74
	v_fma_f32 v75, -v39, v131, v75
	ds_read_b128 v[36:39], v17 offset:14192
	s_waitcnt lgkmcnt(11)
	v_fma_f32 v72, -v40, v132, v72
	v_fma_f32 v73, -v41, v133, v73
	v_fma_f32 v74, -v42, v134, v74
	v_fma_f32 v75, -v43, v135, v75
	ds_read_b128 v[40:43], v17 offset:14208
	s_waitcnt lgkmcnt(11)
	v_fma_f32 v72, -v44, v136, v72
	v_fma_f32 v73, -v45, v137, v73
	v_fma_f32 v74, -v46, v138, v74
	v_fma_f32 v75, -v47, v139, v75
	ds_read_b128 v[44:47], v17 offset:14224
	s_waitcnt lgkmcnt(11)
	v_fma_f32 v72, -v48, v140, v72
	v_fma_f32 v73, -v49, v141, v73
	v_fma_f32 v74, -v50, v142, v74
	v_fma_f32 v75, -v51, v143, v75
	ds_read_b128 v[48:51], v17 offset:14240
	s_waitcnt lgkmcnt(11)
	v_fma_f32 v72, -v52, v60, v72
	v_fma_f32 v73, -v53, v61, v73
	ds_read_b128 v[52:55], v17 offset:14256
	v_add_f32_e32 v72, v72, v73
	v_add_f32_e32 v74, v74, v75
	v_add_f32_e32 v62, v62, v72
	v_add_f32_e32 v62, v62, v74
	s_waitcnt lgkmcnt(11)
	v_mul_f32_e64 v72, -v56, v92
	v_mul_f32_e64 v73, -v57, v93
	v_mul_f32_e64 v74, -v58, v94
	v_mul_f32_e64 v75, -v59, v95
	ds_read_b128 v[56:59], v17 offset:14272
	s_waitcnt lgkmcnt(11)
	v_fma_f32 v72, -v4, v96, v72
	v_fma_f32 v73, -v5, v97, v73
	v_fma_f32 v74, -v6, v98, v74
	v_fma_f32 v75, -v7, v99, v75
	ds_read_b128 v[4:7], v17 offset:14288
	s_waitcnt lgkmcnt(11)
	v_fma_f32 v72, -v8, v100, v72
	v_fma_f32 v73, -v9, v101, v73
	v_fma_f32 v74, -v10, v102, v74
	v_fma_f32 v75, -v11, v103, v75
	ds_read_b128 v[8:11], v17 offset:14336
	s_waitcnt lgkmcnt(11)
	v_fma_f32 v72, -v12, v104, v72
	v_fma_f32 v73, -v13, v105, v73
	v_fma_f32 v74, -v14, v106, v74
	v_fma_f32 v75, -v15, v107, v75
	ds_read_b128 v[12:15], v17 offset:14352
	s_waitcnt lgkmcnt(11)
	v_fma_f32 v72, -v24, v108, v72
	v_fma_f32 v73, -v25, v109, v73
	v_fma_f32 v74, -v26, v110, v74
	v_fma_f32 v75, -v27, v111, v75
	ds_read_b128 v[24:27], v17 offset:14368
	s_waitcnt lgkmcnt(11)
	v_fma_f32 v72, -v28, v112, v72
	v_fma_f32 v73, -v29, v113, v73
	v_fma_f32 v74, -v30, v114, v74
	v_fma_f32 v75, -v31, v115, v75
	ds_read_b128 v[28:31], v17 offset:14384
	s_waitcnt lgkmcnt(11)
	v_fma_f32 v72, -v32, v116, v72
	v_fma_f32 v73, -v33, v117, v73
	v_fma_f32 v74, -v34, v118, v74
	v_fma_f32 v75, -v35, v119, v75
	ds_read_b128 v[32:35], v17 offset:14400
	s_waitcnt lgkmcnt(11)
	v_fma_f32 v72, -v36, v120, v72
	v_fma_f32 v73, -v37, v121, v73
	v_fma_f32 v74, -v38, v122, v74
	v_fma_f32 v75, -v39, v123, v75
	ds_read_b128 v[36:39], v17 offset:14416
	s_waitcnt lgkmcnt(11)
	v_fma_f32 v72, -v40, v124, v72
	v_fma_f32 v73, -v41, v125, v73
	v_fma_f32 v74, -v42, v126, v74
	v_fma_f32 v75, -v43, v127, v75
	ds_read_b128 v[40:43], v17 offset:14432
	s_waitcnt lgkmcnt(11)
	v_fma_f32 v72, -v44, v128, v72
	v_fma_f32 v73, -v45, v129, v73
	v_fma_f32 v74, -v46, v130, v74
	v_fma_f32 v75, -v47, v131, v75
	ds_read_b128 v[44:47], v17 offset:14448
	s_waitcnt lgkmcnt(11)
	v_fma_f32 v72, -v48, v132, v72
	v_fma_f32 v73, -v49, v133, v73
	v_fma_f32 v74, -v50, v134, v74
	v_fma_f32 v75, -v51, v135, v75
	ds_read_b128 v[48:51], v17 offset:14464
	s_waitcnt lgkmcnt(11)
	v_fma_f32 v72, -v52, v136, v72
	v_fma_f32 v73, -v53, v137, v73
	v_fma_f32 v74, -v54, v138, v74
	v_fma_f32 v75, -v55, v139, v75
	ds_read_b128 v[52:55], v17 offset:14480
	s_waitcnt lgkmcnt(11)
	v_fma_f32 v72, -v56, v140, v72
	v_fma_f32 v73, -v57, v141, v73
	v_fma_f32 v74, -v58, v142, v74
	v_fma_f32 v75, -v59, v143, v75
	ds_read_b128 v[56:59], v17 offset:14496
	s_waitcnt lgkmcnt(11)
	v_fma_f32 v72, -v4, v60, v72
	v_fma_f32 v73, -v5, v61, v73
	v_fma_f32 v74, -v6, v62, v74
	ds_read_b128 v[4:7], v17 offset:14512
	v_add_f32_e32 v72, v72, v73
	v_add_f32_e32 v74, v74, v75
	v_add_f32_e32 v63, v63, v72
	v_add_f32_e32 v63, v63, v74
	s_waitcnt lgkmcnt(11)
	v_mul_f32_e64 v72, -v8, v92
	v_mul_f32_e64 v73, -v9, v93
	v_mul_f32_e64 v74, -v10, v94
	v_mul_f32_e64 v75, -v11, v95
	ds_read_b128 v[8:11], v17 offset:14528
	s_waitcnt lgkmcnt(11)
	v_fma_f32 v72, -v12, v96, v72
	v_fma_f32 v73, -v13, v97, v73
	v_fma_f32 v74, -v14, v98, v74
	v_fma_f32 v75, -v15, v99, v75
	ds_read_b128 v[12:15], v17 offset:14544
	s_waitcnt lgkmcnt(11)
	v_fma_f32 v72, -v24, v100, v72
	v_fma_f32 v73, -v25, v101, v73
	v_fma_f32 v74, -v26, v102, v74
	v_fma_f32 v75, -v27, v103, v75
	ds_read_b128 v[24:27], v17 offset:14592
	s_waitcnt lgkmcnt(11)
	v_fma_f32 v72, -v28, v104, v72
	v_fma_f32 v73, -v29, v105, v73
	v_fma_f32 v74, -v30, v106, v74
	v_fma_f32 v75, -v31, v107, v75
	ds_read_b128 v[28:31], v17 offset:14608
	s_waitcnt lgkmcnt(11)
	v_fma_f32 v72, -v32, v108, v72
	v_fma_f32 v73, -v33, v109, v73
	v_fma_f32 v74, -v34, v110, v74
	v_fma_f32 v75, -v35, v111, v75
	ds_read_b128 v[32:35], v17 offset:14624
	s_waitcnt lgkmcnt(11)
	v_fma_f32 v72, -v36, v112, v72
	v_fma_f32 v73, -v37, v113, v73
	v_fma_f32 v74, -v38, v114, v74
	v_fma_f32 v75, -v39, v115, v75
	ds_read_b128 v[36:39], v17 offset:14640
	s_waitcnt lgkmcnt(11)
; #define LAS __attribute__((address_space(3)))
; __device__ __forceinline__ void even_prep(const Ctx& c, const Params& p, int e) {
;     ...
;             for (int i = 1; i < 64; ++i) { const LAS f32x4* Lr = (const LAS f32x4*)(Lv + i * 64); float a0 = x[i], a1 = 0.f;
; #pragma unroll
;                 for (int j4 = 0; j4 < (i + 3) / 4; ++j4) { const f32x4 l = Lr[j4];
;                     if (4 * j4 + 0 < i) a0 -= l[0] * x[4 * j4 + 0];
;                     if (4 * j4 + 1 < i) a1 -= l[1] * x[4 * j4 + 1];
;                     if (4 * j4 + 2 < i) a0 -= l[2] * x[4 * j4 + 2];
;                     if (4 * j4 + 3 < i) a1 -= l[3] * x[4 * j4 + 3]; }
;                 x[i] = a0 + a1; }
	v_fma_f32 v72, -v40, v116, v72
	v_fma_f32 v73, -v41, v117, v73
	v_fma_f32 v74, -v42, v118, v74
	v_fma_f32 v75, -v43, v119, v75
	ds_read_b128 v[40:43], v17 offset:14656
	s_waitcnt lgkmcnt(11)
	v_fma_f32 v72, -v44, v120, v72
	v_fma_f32 v73, -v45, v121, v73
	v_fma_f32 v74, -v46, v122, v74
	v_fma_f32 v75, -v47, v123, v75
	ds_read_b128 v[44:47], v17 offset:14672
	s_waitcnt lgkmcnt(11)
	v_fma_f32 v72, -v48, v124, v72
	v_fma_f32 v73, -v49, v125, v73
	v_fma_f32 v74, -v50, v126, v74
	v_fma_f32 v75, -v51, v127, v75
	ds_read_b128 v[48:51], v17 offset:14688
	s_waitcnt lgkmcnt(11)
	v_fma_f32 v72, -v52, v128, v72
	v_fma_f32 v73, -v53, v129, v73
	v_fma_f32 v74, -v54, v130, v74
	v_fma_f32 v75, -v55, v131, v75
	ds_read_b128 v[52:55], v17 offset:14704
	s_waitcnt lgkmcnt(11)
	v_fma_f32 v72, -v56, v132, v72
	v_fma_f32 v73, -v57, v133, v73
	v_fma_f32 v74, -v58, v134, v74
	v_fma_f32 v75, -v59, v135, v75
	ds_read_b128 v[56:59], v17 offset:14720
	s_waitcnt lgkmcnt(11)
	v_fma_f32 v72, -v4, v136, v72
	v_fma_f32 v73, -v5, v137, v73
	v_fma_f32 v74, -v6, v138, v74
	v_fma_f32 v75, -v7, v139, v75
	ds_read_b128 v[4:7], v17 offset:14736
	s_waitcnt lgkmcnt(11)
	v_fma_f32 v72, -v8, v140, v72
	v_fma_f32 v73, -v9, v141, v73
	v_fma_f32 v74, -v10, v142, v74
	v_fma_f32 v75, -v11, v143, v75
	ds_read_b128 v[8:11], v17 offset:14752
	s_waitcnt lgkmcnt(11)
	v_fma_f32 v72, -v12, v60, v72
	v_fma_f32 v73, -v13, v61, v73
	v_fma_f32 v74, -v14, v62, v74
	v_fma_f32 v75, -v15, v63, v75
	ds_read_b128 v[12:15], v17 offset:14768
	v_add_f32_e32 v72, v72, v73
	v_add_f32_e32 v74, v74, v75
	v_add_f32_e32 v64, v64, v72
	v_add_f32_e32 v64, v64, v74
	s_waitcnt lgkmcnt(11)
	v_mul_f32_e64 v72, -v24, v92
	v_mul_f32_e64 v73, -v25, v93
	v_mul_f32_e64 v74, -v26, v94
	v_mul_f32_e64 v75, -v27, v95
	ds_read_b128 v[24:27], v17 offset:14784
	s_waitcnt lgkmcnt(11)
	v_fma_f32 v72, -v28, v96, v72
	v_fma_f32 v73, -v29, v97, v73
	v_fma_f32 v74, -v30, v98, v74
	v_fma_f32 v75, -v31, v99, v75
	ds_read_b128 v[28:31], v17 offset:14800
	s_waitcnt lgkmcnt(11)
	v_fma_f32 v72, -v32, v100, v72
	v_fma_f32 v73, -v33, v101, v73
	v_fma_f32 v74, -v34, v102, v74
	v_fma_f32 v75, -v35, v103, v75
	ds_read_b128 v[32:35], v17 offset:14816
	s_waitcnt lgkmcnt(11)
	v_fma_f32 v72, -v36, v104, v72
	v_fma_f32 v73, -v37, v105, v73
	v_fma_f32 v74, -v38, v106, v74
	v_fma_f32 v75, -v39, v107, v75
	ds_read_b128 v[36:39], v17 offset:14848
	s_waitcnt lgkmcnt(11)
	v_fma_f32 v72, -v40, v108, v72
	v_fma_f32 v73, -v41, v109, v73
	v_fma_f32 v74, -v42, v110, v74
	v_fma_f32 v75, -v43, v111, v75
	ds_read_b128 v[40:43], v17 offset:14864
	s_waitcnt lgkmcnt(11)
	v_fma_f32 v72, -v44, v112, v72
	v_fma_f32 v73, -v45, v113, v73
	v_fma_f32 v74, -v46, v114, v74
	v_fma_f32 v75, -v47, v115, v75
	ds_read_b128 v[44:47], v17 offset:14880
	s_waitcnt lgkmcnt(11)
	v_fma_f32 v72, -v48, v116, v72
	v_fma_f32 v73, -v49, v117, v73
	v_fma_f32 v74, -v50, v118, v74
	v_fma_f32 v75, -v51, v119, v75
	ds_read_b128 v[48:51], v17 offset:14896
	s_waitcnt lgkmcnt(11)
	v_fma_f32 v72, -v52, v120, v72
	v_fma_f32 v73, -v53, v121, v73
	v_fma_f32 v74, -v54, v122, v74
	v_fma_f32 v75, -v55, v123, v75
	ds_read_b128 v[52:55], v17 offset:14912
	s_waitcnt lgkmcnt(11)
	v_fma_f32 v72, -v56, v124, v72
	v_fma_f32 v73, -v57, v125, v73
	v_fma_f32 v74, -v58, v126, v74
	v_fma_f32 v75, -v59, v127, v75
	ds_read_b128 v[56:59], v17 offset:14928
	s_waitcnt lgkmcnt(11)
	v_fma_f32 v72, -v4, v128, v72
	v_fma_f32 v73, -v5, v129, v73
	v_fma_f32 v74, -v6, v130, v74
	v_fma_f32 v75, -v7, v131, v75
	ds_read_b128 v[4:7], v17 offset:14944
	s_waitcnt lgkmcnt(11)
	v_fma_f32 v72, -v8, v132, v72
	v_fma_f32 v73, -v9, v133, v73
	v_fma_f32 v74, -v10, v134, v74
	v_fma_f32 v75, -v11, v135, v75
	ds_read_b128 v[8:11], v17 offset:14960
	s_waitcnt lgkmcnt(11)
	v_fma_f32 v72, -v12, v136, v72
	v_fma_f32 v73, -v13, v137, v73
	v_fma_f32 v74, -v14, v138, v74
	v_fma_f32 v75, -v15, v139, v75
	ds_read_b128 v[12:15], v17 offset:14976
	s_waitcnt lgkmcnt(11)
	v_fma_f32 v72, -v24, v140, v72
	v_fma_f32 v73, -v25, v141, v73
	v_fma_f32 v74, -v26, v142, v74
	v_fma_f32 v75, -v27, v143, v75
	ds_read_b128 v[24:27], v17 offset:14992
	s_waitcnt lgkmcnt(11)
	v_fma_f32 v72, -v28, v60, v72
	v_fma_f32 v73, -v29, v61, v73
	v_fma_f32 v74, -v30, v62, v74
	v_fma_f32 v75, -v31, v63, v75
	ds_read_b128 v[28:31], v17 offset:15008
	s_waitcnt lgkmcnt(11)
	v_fma_f32 v72, -v32, v64, v72
	ds_read_b128 v[32:35], v17 offset:15024
	v_add_f32_e32 v72, v72, v73
	v_add_f32_e32 v74, v74, v75
	v_add_f32_e32 v65, v65, v72
	v_add_f32_e32 v65, v65, v74
	s_waitcnt lgkmcnt(11)
	v_mul_f32_e64 v72, -v36, v92
	v_mul_f32_e64 v73, -v37, v93
	v_mul_f32_e64 v74, -v38, v94
	v_mul_f32_e64 v75, -v39, v95
	ds_read_b128 v[36:39], v17 offset:15040
	s_waitcnt lgkmcnt(11)
	v_fma_f32 v72, -v40, v96, v72
	v_fma_f32 v73, -v41, v97, v73
	v_fma_f32 v74, -v42, v98, v74
	v_fma_f32 v75, -v43, v99, v75
	ds_read_b128 v[40:43], v17 offset:15056
	s_waitcnt lgkmcnt(11)
	v_fma_f32 v72, -v44, v100, v72
	v_fma_f32 v73, -v45, v101, v73
	v_fma_f32 v74, -v46, v102, v74
	v_fma_f32 v75, -v47, v103, v75
	ds_read_b128 v[44:47], v17 offset:15072
	s_waitcnt lgkmcnt(11)
	v_fma_f32 v72, -v48, v104, v72
	v_fma_f32 v73, -v49, v105, v73
	v_fma_f32 v74, -v50, v106, v74
	v_fma_f32 v75, -v51, v107, v75
	ds_read_b128 v[48:51], v17 offset:15104
	s_waitcnt lgkmcnt(11)
	v_fma_f32 v72, -v52, v108, v72
	v_fma_f32 v73, -v53, v109, v73
	v_fma_f32 v74, -v54, v110, v74
	v_fma_f32 v75, -v55, v111, v75
	ds_read_b128 v[52:55], v17 offset:15120
	s_waitcnt lgkmcnt(11)
	v_fma_f32 v72, -v56, v112, v72
	v_fma_f32 v73, -v57, v113, v73
	v_fma_f32 v74, -v58, v114, v74
	v_fma_f32 v75, -v59, v115, v75
	ds_read_b128 v[56:59], v17 offset:15136
	s_waitcnt lgkmcnt(11)
; #define LAS __attribute__((address_space(3)))
; __device__ __forceinline__ void even_prep(const Ctx& c, const Params& p, int e) {
;     ...
;             for (int i = 1; i < 64; ++i) { const LAS f32x4* Lr = (const LAS f32x4*)(Lv + i * 64); float a0 = x[i], a1 = 0.f;
; #pragma unroll
;                 for (int j4 = 0; j4 < (i + 3) / 4; ++j4) { const f32x4 l = Lr[j4];
;                     if (4 * j4 + 0 < i) a0 -= l[0] * x[4 * j4 + 0];
;                     if (4 * j4 + 1 < i) a1 -= l[1] * x[4 * j4 + 1];
;                     if (4 * j4 + 2 < i) a0 -= l[2] * x[4 * j4 + 2];
;                     if (4 * j4 + 3 < i) a1 -= l[3] * x[4 * j4 + 3]; }
;                 x[i] = a0 + a1; }
	v_fma_f32 v72, -v4, v116, v72
	v_fma_f32 v73, -v5, v117, v73
	v_fma_f32 v74, -v6, v118, v74
	v_fma_f32 v75, -v7, v119, v75
	ds_read_b128 v[4:7], v17 offset:15152
	s_waitcnt lgkmcnt(11)
	v_fma_f32 v72, -v8, v120, v72
	v_fma_f32 v73, -v9, v121, v73
	v_fma_f32 v74, -v10, v122, v74
	v_fma_f32 v75, -v11, v123, v75
	ds_read_b128 v[8:11], v17 offset:15168
	s_waitcnt lgkmcnt(11)
	v_fma_f32 v72, -v12, v124, v72
	v_fma_f32 v73, -v13, v125, v73
	v_fma_f32 v74, -v14, v126, v74
	v_fma_f32 v75, -v15, v127, v75
	ds_read_b128 v[12:15], v17 offset:15184
	s_waitcnt lgkmcnt(11)
	v_fma_f32 v72, -v24, v128, v72
	v_fma_f32 v73, -v25, v129, v73
	v_fma_f32 v74, -v26, v130, v74
	v_fma_f32 v75, -v27, v131, v75
	ds_read_b128 v[24:27], v17 offset:15200
	s_waitcnt lgkmcnt(11)
	v_fma_f32 v72, -v28, v132, v72
	v_fma_f32 v73, -v29, v133, v73
	v_fma_f32 v74, -v30, v134, v74
	v_fma_f32 v75, -v31, v135, v75
	ds_read_b128 v[28:31], v17 offset:15216
	s_waitcnt lgkmcnt(11)
	v_fma_f32 v72, -v32, v136, v72
	v_fma_f32 v73, -v33, v137, v73
	v_fma_f32 v74, -v34, v138, v74
	v_fma_f32 v75, -v35, v139, v75
	ds_read_b128 v[32:35], v17 offset:15232
	s_waitcnt lgkmcnt(11)
	v_fma_f32 v72, -v36, v140, v72
	v_fma_f32 v73, -v37, v141, v73
	v_fma_f32 v74, -v38, v142, v74
	v_fma_f32 v75, -v39, v143, v75
	ds_read_b128 v[36:39], v17 offset:15248
	s_waitcnt lgkmcnt(11)
	v_fma_f32 v72, -v40, v60, v72
	v_fma_f32 v73, -v41, v61, v73
	v_fma_f32 v74, -v42, v62, v74
	v_fma_f32 v75, -v43, v63, v75
	ds_read_b128 v[40:43], v17 offset:15264
	s_waitcnt lgkmcnt(11)
	v_fma_f32 v72, -v44, v64, v72
	v_fma_f32 v73, -v45, v65, v73
	ds_read_b128 v[44:47], v17 offset:15280
	v_add_f32_e32 v72, v72, v73
	v_add_f32_e32 v74, v74, v75
	v_add_f32_e32 v66, v66, v72
	v_add_f32_e32 v66, v66, v74
	s_waitcnt lgkmcnt(11)
	v_mul_f32_e64 v72, -v48, v92
	v_mul_f32_e64 v73, -v49, v93
	v_mul_f32_e64 v74, -v50, v94
	v_mul_f32_e64 v75, -v51, v95
	ds_read_b128 v[48:51], v17 offset:15296
	s_waitcnt lgkmcnt(11)
	v_fma_f32 v72, -v52, v96, v72
	v_fma_f32 v73, -v53, v97, v73
	v_fma_f32 v74, -v54, v98, v74
	v_fma_f32 v75, -v55, v99, v75
	ds_read_b128 v[52:55], v17 offset:15312
	s_waitcnt lgkmcnt(11)
	v_fma_f32 v72, -v56, v100, v72
	v_fma_f32 v73, -v57, v101, v73
	v_fma_f32 v74, -v58, v102, v74
	v_fma_f32 v75, -v59, v103, v75
	ds_read_b128 v[56:59], v17 offset:15328
	s_waitcnt lgkmcnt(11)
	v_fma_f32 v72, -v4, v104, v72
	v_fma_f32 v73, -v5, v105, v73
	v_fma_f32 v74, -v6, v106, v74
	v_fma_f32 v75, -v7, v107, v75
	ds_read_b128 v[4:7], v17 offset:15360
	s_waitcnt lgkmcnt(11)
	v_fma_f32 v72, -v8, v108, v72
	v_fma_f32 v73, -v9, v109, v73
	v_fma_f32 v74, -v10, v110, v74
	v_fma_f32 v75, -v11, v111, v75
	ds_read_b128 v[8:11], v17 offset:15376
	s_waitcnt lgkmcnt(11)
	v_fma_f32 v72, -v12, v112, v72
	v_fma_f32 v73, -v13, v113, v73
	v_fma_f32 v74, -v14, v114, v74
	v_fma_f32 v75, -v15, v115, v75
	ds_read_b128 v[12:15], v17 offset:15392
	s_waitcnt lgkmcnt(11)
	v_fma_f32 v72, -v24, v116, v72
	v_fma_f32 v73, -v25, v117, v73
	v_fma_f32 v74, -v26, v118, v74
	v_fma_f32 v75, -v27, v119, v75
	ds_read_b128 v[24:27], v17 offset:15408
	s_waitcnt lgkmcnt(11)
	v_fma_f32 v72, -v28, v120, v72
	v_fma_f32 v73, -v29, v121, v73
	v_fma_f32 v74, -v30, v122, v74
	v_fma_f32 v75, -v31, v123, v75
	ds_read_b128 v[28:31], v17 offset:15424
	s_waitcnt lgkmcnt(11)
	v_fma_f32 v72, -v32, v124, v72
	v_fma_f32 v73, -v33, v125, v73
	v_fma_f32 v74, -v34, v126, v74
	v_fma_f32 v75, -v35, v127, v75
	ds_read_b128 v[32:35], v17 offset:15440
	s_waitcnt lgkmcnt(11)
	v_fma_f32 v72, -v36, v128, v72
	v_fma_f32 v73, -v37, v129, v73
	v_fma_f32 v74, -v38, v130, v74
	v_fma_f32 v75, -v39, v131, v75
	ds_read_b128 v[36:39], v17 offset:15456
	s_waitcnt lgkmcnt(11)
	v_fma_f32 v72, -v40, v132, v72
	v_fma_f32 v73, -v41, v133, v73
	v_fma_f32 v74, -v42, v134, v74
	v_fma_f32 v75, -v43, v135, v75
	ds_read_b128 v[40:43], v17 offset:15472
	s_waitcnt lgkmcnt(11)
	v_fma_f32 v72, -v44, v136, v72
	v_fma_f32 v73, -v45, v137, v73
	v_fma_f32 v74, -v46, v138, v74
	v_fma_f32 v75, -v47, v139, v75
	ds_read_b128 v[44:47], v17 offset:15488
	s_waitcnt lgkmcnt(11)
	v_fma_f32 v72, -v48, v140, v72
	v_fma_f32 v73, -v49, v141, v73
	v_fma_f32 v74, -v50, v142, v74
	v_fma_f32 v75, -v51, v143, v75
	ds_read_b128 v[48:51], v17 offset:15504
	s_waitcnt lgkmcnt(11)
	v_fma_f32 v72, -v52, v60, v72
	v_fma_f32 v73, -v53, v61, v73
	v_fma_f32 v74, -v54, v62, v74
	v_fma_f32 v75, -v55, v63, v75
	ds_read_b128 v[52:55], v17 offset:15520
	s_waitcnt lgkmcnt(11)
	v_fma_f32 v72, -v56, v64, v72
	v_fma_f32 v73, -v57, v65, v73
	v_fma_f32 v74, -v58, v66, v74
	ds_read_b128 v[56:59], v17 offset:15536
	v_add_f32_e32 v72, v72, v73
	v_add_f32_e32 v74, v74, v75
	v_add_f32_e32 v67, v67, v72
	v_add_f32_e32 v67, v67, v74
	s_waitcnt lgkmcnt(11)
	v_mul_f32_e64 v72, -v4, v92
	v_mul_f32_e64 v73, -v5, v93
	v_mul_f32_e64 v74, -v6, v94
	v_mul_f32_e64 v75, -v7, v95
	ds_read_b128 v[4:7], v17 offset:15552
	s_waitcnt lgkmcnt(11)
	v_fma_f32 v72, -v8, v96, v72
	v_fma_f32 v73, -v9, v97, v73
	v_fma_f32 v74, -v10, v98, v74
	v_fma_f32 v75, -v11, v99, v75
	ds_read_b128 v[8:11], v17 offset:15568
	s_waitcnt lgkmcnt(11)
	v_fma_f32 v72, -v12, v100, v72
	v_fma_f32 v73, -v13, v101, v73
	v_fma_f32 v74, -v14, v102, v74
	v_fma_f32 v75, -v15, v103, v75
	ds_read_b128 v[12:15], v17 offset:15584
	s_waitcnt lgkmcnt(11)
	v_fma_f32 v72, -v24, v104, v72
	v_fma_f32 v73, -v25, v105, v73
	v_fma_f32 v74, -v26, v106, v74
	v_fma_f32 v75, -v27, v107, v75
	ds_read_b128 v[24:27], v17 offset:15616
	s_waitcnt lgkmcnt(11)
	v_fma_f32 v72, -v28, v108, v72
	v_fma_f32 v73, -v29, v109, v73
	v_fma_f32 v74, -v30, v110, v74
	v_fma_f32 v75, -v31, v111, v75
	ds_read_b128 v[28:31], v17 offset:15632
	s_waitcnt lgkmcnt(11)
; #define LAS __attribute__((address_space(3)))
; __device__ __forceinline__ void even_prep(const Ctx& c, const Params& p, int e) {
;     ...
;             for (int i = 1; i < 64; ++i) { const LAS f32x4* Lr = (const LAS f32x4*)(Lv + i * 64); float a0 = x[i], a1 = 0.f;
; #pragma unroll
;                 for (int j4 = 0; j4 < (i + 3) / 4; ++j4) { const f32x4 l = Lr[j4];
;                     if (4 * j4 + 0 < i) a0 -= l[0] * x[4 * j4 + 0];
;                     if (4 * j4 + 1 < i) a1 -= l[1] * x[4 * j4 + 1];
;                     if (4 * j4 + 2 < i) a0 -= l[2] * x[4 * j4 + 2];
;                     if (4 * j4 + 3 < i) a1 -= l[3] * x[4 * j4 + 3]; }
;                 x[i] = a0 + a1; }
	v_fma_f32 v72, -v32, v112, v72
	v_fma_f32 v73, -v33, v113, v73
	v_fma_f32 v74, -v34, v114, v74
	v_fma_f32 v75, -v35, v115, v75
	ds_read_b128 v[32:35], v17 offset:15648
	s_waitcnt lgkmcnt(11)
	v_fma_f32 v72, -v36, v116, v72
	v_fma_f32 v73, -v37, v117, v73
	v_fma_f32 v74, -v38, v118, v74
	v_fma_f32 v75, -v39, v119, v75
	ds_read_b128 v[36:39], v17 offset:15664
	s_waitcnt lgkmcnt(11)
	v_fma_f32 v72, -v40, v120, v72
	v_fma_f32 v73, -v41, v121, v73
	v_fma_f32 v74, -v42, v122, v74
	v_fma_f32 v75, -v43, v123, v75
	ds_read_b128 v[40:43], v17 offset:15680
	s_waitcnt lgkmcnt(11)
	v_fma_f32 v72, -v44, v124, v72
	v_fma_f32 v73, -v45, v125, v73
	v_fma_f32 v74, -v46, v126, v74
	v_fma_f32 v75, -v47, v127, v75
	ds_read_b128 v[44:47], v17 offset:15696
	s_waitcnt lgkmcnt(11)
	v_fma_f32 v72, -v48, v128, v72
	v_fma_f32 v73, -v49, v129, v73
	v_fma_f32 v74, -v50, v130, v74
	v_fma_f32 v75, -v51, v131, v75
	ds_read_b128 v[48:51], v17 offset:15712
	s_waitcnt lgkmcnt(11)
	v_fma_f32 v72, -v52, v132, v72
	v_fma_f32 v73, -v53, v133, v73
	v_fma_f32 v74, -v54, v134, v74
	v_fma_f32 v75, -v55, v135, v75
	ds_read_b128 v[52:55], v17 offset:15728
	s_waitcnt lgkmcnt(11)
	v_fma_f32 v72, -v56, v136, v72
	v_fma_f32 v73, -v57, v137, v73
	v_fma_f32 v74, -v58, v138, v74
	v_fma_f32 v75, -v59, v139, v75
	ds_read_b128 v[56:59], v17 offset:15744
	s_waitcnt lgkmcnt(11)
	v_fma_f32 v72, -v4, v140, v72
	v_fma_f32 v73, -v5, v141, v73
	v_fma_f32 v74, -v6, v142, v74
	v_fma_f32 v75, -v7, v143, v75
	ds_read_b128 v[4:7], v17 offset:15760
	s_waitcnt lgkmcnt(11)
	v_fma_f32 v72, -v8, v60, v72
	v_fma_f32 v73, -v9, v61, v73
	v_fma_f32 v74, -v10, v62, v74
	v_fma_f32 v75, -v11, v63, v75
	ds_read_b128 v[8:11], v17 offset:15776
	s_waitcnt lgkmcnt(11)
	v_fma_f32 v72, -v12, v64, v72
	v_fma_f32 v73, -v13, v65, v73
	v_fma_f32 v74, -v14, v66, v74
	v_fma_f32 v75, -v15, v67, v75
	ds_read_b128 v[12:15], v17 offset:15792
	v_add_f32_e32 v72, v72, v73
	v_add_f32_e32 v74, v74, v75
	v_add_f32_e32 v68, v68, v72
	v_add_f32_e32 v68, v68, v74
	s_waitcnt lgkmcnt(11)
	v_mul_f32_e64 v72, -v24, v92
	v_mul_f32_e64 v73, -v25, v93
	v_mul_f32_e64 v74, -v26, v94
	v_mul_f32_e64 v75, -v27, v95
	ds_read_b128 v[24:27], v17 offset:15808
	s_waitcnt lgkmcnt(11)
	v_fma_f32 v72, -v28, v96, v72
	v_fma_f32 v73, -v29, v97, v73
	v_fma_f32 v74, -v30, v98, v74
	v_fma_f32 v75, -v31, v99, v75
	ds_read_b128 v[28:31], v17 offset:15824
	s_waitcnt lgkmcnt(11)
	v_fma_f32 v72, -v32, v100, v72
	v_fma_f32 v73, -v33, v101, v73
	v_fma_f32 v74, -v34, v102, v74
	v_fma_f32 v75, -v35, v103, v75
	ds_read_b128 v[32:35], v17 offset:15840
	s_waitcnt lgkmcnt(11)
	v_fma_f32 v72, -v36, v104, v72
	v_fma_f32 v73, -v37, v105, v73
	v_fma_f32 v74, -v38, v106, v74
	v_fma_f32 v75, -v39, v107, v75
	ds_read_b128 v[36:39], v17 offset:15856
	s_waitcnt lgkmcnt(11)
	v_fma_f32 v72, -v40, v108, v72
	v_fma_f32 v73, -v41, v109, v73
	v_fma_f32 v74, -v42, v110, v74
	v_fma_f32 v75, -v43, v111, v75
	ds_read_b128 v[40:43], v17 offset:15872
	s_waitcnt lgkmcnt(11)
	v_fma_f32 v72, -v44, v112, v72
	v_fma_f32 v73, -v45, v113, v73
	v_fma_f32 v74, -v46, v114, v74
	v_fma_f32 v75, -v47, v115, v75
	ds_read_b128 v[44:47], v17 offset:15888
	s_waitcnt lgkmcnt(11)
	v_fma_f32 v72, -v48, v116, v72
	v_fma_f32 v73, -v49, v117, v73
	v_fma_f32 v74, -v50, v118, v74
	v_fma_f32 v75, -v51, v119, v75
	ds_read_b128 v[48:51], v17 offset:15904
	s_waitcnt lgkmcnt(11)
	v_fma_f32 v72, -v52, v120, v72
	v_fma_f32 v73, -v53, v121, v73
	v_fma_f32 v74, -v54, v122, v74
	v_fma_f32 v75, -v55, v123, v75
	ds_read_b128 v[52:55], v17 offset:15920
	s_waitcnt lgkmcnt(11)
	v_fma_f32 v72, -v56, v124, v72
	v_fma_f32 v73, -v57, v125, v73
	v_fma_f32 v74, -v58, v126, v74
	v_fma_f32 v75, -v59, v127, v75
	ds_read_b128 v[56:59], v17 offset:15936
	s_waitcnt lgkmcnt(11)
	v_fma_f32 v72, -v4, v128, v72
	v_fma_f32 v73, -v5, v129, v73
	v_fma_f32 v74, -v6, v130, v74
	v_fma_f32 v75, -v7, v131, v75
	ds_read_b128 v[4:7], v17 offset:15952
	s_waitcnt lgkmcnt(11)
	v_fma_f32 v72, -v8, v132, v72
	v_fma_f32 v73, -v9, v133, v73
	v_fma_f32 v74, -v10, v134, v74
	v_fma_f32 v75, -v11, v135, v75
	ds_read_b128 v[8:11], v17 offset:15968
	s_waitcnt lgkmcnt(11)
	v_fma_f32 v72, -v12, v136, v72
	v_fma_f32 v73, -v13, v137, v73
	v_fma_f32 v74, -v14, v138, v74
	v_fma_f32 v75, -v15, v139, v75
	ds_read_b128 v[12:15], v17 offset:15984
	s_waitcnt lgkmcnt(11)
	v_fma_f32 v72, -v24, v140, v72
	v_fma_f32 v73, -v25, v141, v73
	v_fma_f32 v74, -v26, v142, v74
	v_fma_f32 v75, -v27, v143, v75
	ds_read_b128 v[24:27], v17 offset:16000
	s_waitcnt lgkmcnt(11)
	v_fma_f32 v72, -v28, v60, v72
	v_fma_f32 v73, -v29, v61, v73
	v_fma_f32 v74, -v30, v62, v74
	v_fma_f32 v75, -v31, v63, v75
	ds_read_b128 v[28:31], v17 offset:16016
	s_waitcnt lgkmcnt(11)
	v_fma_f32 v72, -v32, v64, v72
	v_fma_f32 v73, -v33, v65, v73
	v_fma_f32 v74, -v34, v66, v74
	v_fma_f32 v75, -v35, v67, v75
	ds_read_b128 v[32:35], v17 offset:16032
	s_waitcnt lgkmcnt(11)
	v_fma_f32 v72, -v36, v68, v72
	ds_read_b128 v[36:39], v17 offset:16048
	v_add_f32_e32 v72, v72, v73
	v_add_f32_e32 v74, v74, v75
	v_add_f32_e32 v69, v69, v72
	v_add_f32_e32 v69, v69, v74
	s_waitcnt lgkmcnt(11)
	v_mul_f32_e64 v72, -v40, v92
	v_mul_f32_e64 v73, -v41, v93
	v_mul_f32_e64 v74, -v42, v94
	v_mul_f32_e64 v75, -v43, v95
	ds_read_b128 v[40:43], v17 offset:16064
	s_waitcnt lgkmcnt(11)
	v_fma_f32 v72, -v44, v96, v72
	v_fma_f32 v73, -v45, v97, v73
	v_fma_f32 v74, -v46, v98, v74
	v_fma_f32 v75, -v47, v99, v75
	ds_read_b128 v[44:47], v17 offset:16080
	s_waitcnt lgkmcnt(11)
	v_fma_f32 v72, -v48, v100, v72
	v_fma_f32 v73, -v49, v101, v73
	v_fma_f32 v74, -v50, v102, v74
	v_fma_f32 v75, -v51, v103, v75
	ds_read_b128 v[48:51], v17 offset:16096
	s_waitcnt lgkmcnt(11)
; #define LAS __attribute__((address_space(3)))
; __device__ __forceinline__ void even_prep(const Ctx& c, const Params& p, int e) {
;     ...
;             for (int i = 1; i < 64; ++i) { const LAS f32x4* Lr = (const LAS f32x4*)(Lv + i * 64); float a0 = x[i], a1 = 0.f;
; #pragma unroll
;                 for (int j4 = 0; j4 < (i + 3) / 4; ++j4) { const f32x4 l = Lr[j4];
;                     if (4 * j4 + 0 < i) a0 -= l[0] * x[4 * j4 + 0];
;                     if (4 * j4 + 1 < i) a1 -= l[1] * x[4 * j4 + 1];
;                     if (4 * j4 + 2 < i) a0 -= l[2] * x[4 * j4 + 2];
;                     if (4 * j4 + 3 < i) a1 -= l[3] * x[4 * j4 + 3]; }
;                 x[i] = a0 + a1; }
	v_fma_f32 v72, -v52, v104, v72
	v_fma_f32 v73, -v53, v105, v73
	v_fma_f32 v74, -v54, v106, v74
	v_fma_f32 v75, -v55, v107, v75
	ds_read_b128 v[52:55], v17 offset:16112
	s_waitcnt lgkmcnt(11)
	v_fma_f32 v72, -v56, v108, v72
	v_fma_f32 v73, -v57, v109, v73
	v_fma_f32 v74, -v58, v110, v74
	v_fma_f32 v75, -v59, v111, v75
	ds_read_b128 v[56:59], v17 offset:16128
	s_waitcnt lgkmcnt(11)
	v_fma_f32 v72, -v4, v112, v72
	v_fma_f32 v73, -v5, v113, v73
	v_fma_f32 v74, -v6, v114, v74
	v_fma_f32 v75, -v7, v115, v75
	ds_read_b128 v[4:7], v17 offset:16144
	s_waitcnt lgkmcnt(11)
	v_fma_f32 v72, -v8, v116, v72
	v_fma_f32 v73, -v9, v117, v73
	v_fma_f32 v74, -v10, v118, v74
	v_fma_f32 v75, -v11, v119, v75
	ds_read_b128 v[8:11], v17 offset:16160
	s_waitcnt lgkmcnt(11)
	v_fma_f32 v72, -v12, v120, v72
	v_fma_f32 v73, -v13, v121, v73
	v_fma_f32 v74, -v14, v122, v74
	v_fma_f32 v75, -v15, v123, v75
	ds_read_b128 v[12:15], v17 offset:16176
	s_waitcnt lgkmcnt(11)
	v_fma_f32 v72, -v24, v124, v72
	v_fma_f32 v73, -v25, v125, v73
	v_fma_f32 v74, -v26, v126, v74
	v_fma_f32 v75, -v27, v127, v75
	ds_read_b128 v[24:27], v17 offset:16192
	s_waitcnt lgkmcnt(11)
	v_fma_f32 v72, -v28, v128, v72
	v_fma_f32 v73, -v29, v129, v73
	v_fma_f32 v74, -v30, v130, v74
	v_fma_f32 v75, -v31, v131, v75
	ds_read_b128 v[28:31], v17 offset:16208
	s_waitcnt lgkmcnt(11)
	v_fma_f32 v72, -v32, v132, v72
	v_fma_f32 v73, -v33, v133, v73
	v_fma_f32 v74, -v34, v134, v74
	v_fma_f32 v75, -v35, v135, v75
	ds_read_b128 v[32:35], v17 offset:16224
	s_waitcnt lgkmcnt(11)
	v_fma_f32 v72, -v36, v136, v72
	v_fma_f32 v73, -v37, v137, v73
	v_fma_f32 v74, -v38, v138, v74
	v_fma_f32 v75, -v39, v139, v75
	ds_read_b128 v[36:39], v17 offset:16240
	s_waitcnt lgkmcnt(11)
	v_fma_f32 v72, -v40, v140, v72
	v_fma_f32 v73, -v41, v141, v73
	v_fma_f32 v74, -v42, v142, v74
	v_fma_f32 v75, -v43, v143, v75
	ds_read_b128 v[40:43], v17 offset:16256
	s_waitcnt lgkmcnt(11)
	v_fma_f32 v72, -v44, v60, v72
	v_fma_f32 v73, -v45, v61, v73
	v_fma_f32 v74, -v46, v62, v74
	v_fma_f32 v75, -v47, v63, v75
	ds_read_b128 v[44:47], v17 offset:16272
	s_waitcnt lgkmcnt(11)
	v_fma_f32 v72, -v48, v64, v72
	v_fma_f32 v73, -v49, v65, v73
	v_fma_f32 v74, -v50, v66, v74
	v_fma_f32 v75, -v51, v67, v75
	ds_read_b128 v[48:51], v17 offset:16288
	s_waitcnt lgkmcnt(11)
	v_fma_f32 v72, -v52, v68, v72
	v_fma_f32 v73, -v53, v69, v73
	ds_read_b128 v[52:55], v17 offset:16304
	v_add_f32_e32 v72, v72, v73
	v_add_f32_e32 v74, v74, v75
	v_add_f32_e32 v70, v70, v72
	v_add_f32_e32 v70, v70, v74
	s_waitcnt lgkmcnt(11)
	v_mul_f32_e64 v72, -v56, v92
	v_mul_f32_e64 v73, -v57, v93
	v_mul_f32_e64 v74, -v58, v94
	v_mul_f32_e64 v75, -v59, v95
	ds_read_b128 v[56:59], v17 offset:16320
	s_waitcnt lgkmcnt(11)
	v_fma_f32 v72, -v4, v96, v72
	v_fma_f32 v73, -v5, v97, v73
	v_fma_f32 v74, -v6, v98, v74
	v_fma_f32 v75, -v7, v99, v75
	ds_read_b128 v[4:7], v17 offset:16336
	s_waitcnt lgkmcnt(11)
	v_fma_f32 v72, -v8, v100, v72
	v_fma_f32 v73, -v9, v101, v73
	v_fma_f32 v74, -v10, v102, v74
	v_fma_f32 v75, -v11, v103, v75
	ds_read_b128 v[8:11], v17 offset:16352
	s_waitcnt lgkmcnt(11)
	v_fma_f32 v72, -v12, v104, v72
	v_fma_f32 v73, -v13, v105, v73
	v_fma_f32 v74, -v14, v106, v74
	v_fma_f32 v75, -v15, v107, v75
	ds_read_b128 v[12:15], v17 offset:16368
	s_waitcnt lgkmcnt(11)
	v_fma_f32 v72, -v24, v108, v72
	v_fma_f32 v73, -v25, v109, v73
	v_fma_f32 v74, -v26, v110, v74
	v_fma_f32 v75, -v27, v111, v75
	s_waitcnt lgkmcnt(10)
	v_fma_f32 v72, -v28, v112, v72
	v_fma_f32 v73, -v29, v113, v73
	v_fma_f32 v74, -v30, v114, v74
	v_fma_f32 v75, -v31, v115, v75
	s_waitcnt lgkmcnt(9)
	v_fma_f32 v72, -v32, v116, v72
	v_fma_f32 v73, -v33, v117, v73
	v_fma_f32 v74, -v34, v118, v74
	v_fma_f32 v75, -v35, v119, v75
	s_waitcnt lgkmcnt(8)
	v_fma_f32 v72, -v36, v120, v72
	v_fma_f32 v73, -v37, v121, v73
	v_fma_f32 v74, -v38, v122, v74
	v_fma_f32 v75, -v39, v123, v75
	s_waitcnt lgkmcnt(7)
	v_fma_f32 v72, -v40, v124, v72
	v_fma_f32 v73, -v41, v125, v73
	v_fma_f32 v74, -v42, v126, v74
	v_fma_f32 v75, -v43, v127, v75
	s_waitcnt lgkmcnt(6)
	v_fma_f32 v72, -v44, v128, v72
	v_fma_f32 v73, -v45, v129, v73
	v_fma_f32 v74, -v46, v130, v74
	v_fma_f32 v75, -v47, v131, v75
	s_waitcnt lgkmcnt(5)
	v_fma_f32 v72, -v48, v132, v72
	v_fma_f32 v73, -v49, v133, v73
	v_fma_f32 v74, -v50, v134, v74
	v_fma_f32 v75, -v51, v135, v75
	s_waitcnt lgkmcnt(4)
	v_fma_f32 v72, -v52, v136, v72
	v_fma_f32 v73, -v53, v137, v73
	v_fma_f32 v74, -v54, v138, v74
	v_fma_f32 v75, -v55, v139, v75
	s_waitcnt lgkmcnt(3)
	v_fma_f32 v72, -v56, v140, v72
	v_fma_f32 v73, -v57, v141, v73
	v_fma_f32 v74, -v58, v142, v74
	v_fma_f32 v75, -v59, v143, v75
	s_waitcnt lgkmcnt(2)
	v_fma_f32 v72, -v4, v60, v72
	v_fma_f32 v73, -v5, v61, v73
	v_fma_f32 v74, -v6, v62, v74
	v_fma_f32 v75, -v7, v63, v75
	s_waitcnt lgkmcnt(1)
; #define LAS __attribute__((address_space(3)))
; __device__ __forceinline__ void even_prep(const Ctx& c, const Params& p, int e) {
;     ...
;             for (int i = 1; i < 64; ++i) { const LAS f32x4* Lr = (const LAS f32x4*)(Lv + i * 64); float a0 = x[i], a1 = 0.f;
; #pragma unroll
;                 for (int j4 = 0; j4 < (i + 3) / 4; ++j4) { const f32x4 l = Lr[j4];
;                     if (4 * j4 + 0 < i) a0 -= l[0] * x[4 * j4 + 0];
;                     if (4 * j4 + 1 < i) a1 -= l[1] * x[4 * j4 + 1];
;                     if (4 * j4 + 2 < i) a0 -= l[2] * x[4 * j4 + 2];
;                     if (4 * j4 + 3 < i) a1 -= l[3] * x[4 * j4 + 3]; }
;                 x[i] = a0 + a1; }
;             LAS float* dstl = (tid_i < 128) ? VB : KBG; const float sg = (tid_i < 128) ? 1.f : -1.f;
; #pragma unroll
;             for (int i = 0; i < 64; ++i) dstl[i * 128 + cc] = x[i] * sg; }
	v_fma_f32 v72, -v8, v64, v72
	v_fma_f32 v73, -v9, v65, v73
	v_fma_f32 v74, -v10, v66, v74
	v_fma_f32 v75, -v11, v67, v75
	s_waitcnt lgkmcnt(0)
	v_fma_f32 v72, -v12, v68, v72
	v_fma_f32 v73, -v13, v69, v73
	v_fma_f32 v74, -v14, v70, v74
	v_add_f32_e32 v72, v72, v73
	v_add_f32_e32 v74, v74, v75
	v_add_f32_e32 v71, v71, v72
	v_add_f32_e32 v71, v71, v74
	v_cndmask_b32_e64 v1, -v92, v92, s[4:5]
	v_cndmask_b32_e64 v2, -v93, v93, s[4:5]
	ds_write2st64_b32 v16, v1, v2 offset0:0 offset1:2
	v_cndmask_b32_e64 v1, -v94, v94, s[4:5]
	v_cndmask_b32_e64 v2, -v95, v95, s[4:5]
	ds_write2st64_b32 v16, v1, v2 offset0:4 offset1:6
	v_cndmask_b32_e64 v1, -v96, v96, s[4:5]
	v_cndmask_b32_e64 v2, -v97, v97, s[4:5]
	ds_write2st64_b32 v16, v1, v2 offset0:8 offset1:10
	v_cndmask_b32_e64 v1, -v98, v98, s[4:5]
	v_cndmask_b32_e64 v2, -v99, v99, s[4:5]
	ds_write2st64_b32 v16, v1, v2 offset0:12 offset1:14
	v_cndmask_b32_e64 v1, -v100, v100, s[4:5]
	v_cndmask_b32_e64 v2, -v101, v101, s[4:5]
	ds_write2st64_b32 v16, v1, v2 offset0:16 offset1:18
	v_cndmask_b32_e64 v1, -v102, v102, s[4:5]
	v_cndmask_b32_e64 v2, -v103, v103, s[4:5]
	ds_write2st64_b32 v16, v1, v2 offset0:20 offset1:22
	v_cndmask_b32_e64 v1, -v104, v104, s[4:5]
	v_cndmask_b32_e64 v2, -v105, v105, s[4:5]
	ds_write2st64_b32 v16, v1, v2 offset0:24 offset1:26
	v_cndmask_b32_e64 v1, -v106, v106, s[4:5]
	v_cndmask_b32_e64 v2, -v107, v107, s[4:5]
	ds_write2st64_b32 v16, v1, v2 offset0:28 offset1:30
	v_cndmask_b32_e64 v1, -v108, v108, s[4:5]
	v_cndmask_b32_e64 v2, -v109, v109, s[4:5]
	ds_write2st64_b32 v16, v1, v2 offset0:32 offset1:34
	v_cndmask_b32_e64 v1, -v110, v110, s[4:5]
	v_cndmask_b32_e64 v2, -v111, v111, s[4:5]
	ds_write2st64_b32 v16, v1, v2 offset0:36 offset1:38
	v_cndmask_b32_e64 v1, -v112, v112, s[4:5]
	v_cndmask_b32_e64 v2, -v113, v113, s[4:5]
	ds_write2st64_b32 v16, v1, v2 offset0:40 offset1:42
	v_cndmask_b32_e64 v1, -v114, v114, s[4:5]
	v_cndmask_b32_e64 v2, -v115, v115, s[4:5]
	ds_write2st64_b32 v16, v1, v2 offset0:44 offset1:46
	v_cndmask_b32_e64 v1, -v116, v116, s[4:5]
	v_cndmask_b32_e64 v2, -v117, v117, s[4:5]
	ds_write2st64_b32 v16, v1, v2 offset0:48 offset1:50
	v_cndmask_b32_e64 v1, -v118, v118, s[4:5]
	v_cndmask_b32_e64 v2, -v119, v119, s[4:5]
	ds_write2st64_b32 v16, v1, v2 offset0:52 offset1:54
	v_cndmask_b32_e64 v1, -v120, v120, s[4:5]
	v_cndmask_b32_e64 v2, -v121, v121, s[4:5]
	ds_write2st64_b32 v16, v1, v2 offset0:56 offset1:58
	v_cndmask_b32_e64 v1, -v122, v122, s[4:5]
	v_cndmask_b32_e64 v2, -v123, v123, s[4:5]
	s_waitcnt lgkmcnt(7)
	ds_write2st64_b32 v16, v1, v2 offset0:60 offset1:62
	v_cndmask_b32_e64 v1, -v124, v124, s[4:5]
	v_cndmask_b32_e64 v2, -v125, v125, s[4:5]
	ds_write2st64_b32 v16, v1, v2 offset0:64 offset1:66
	v_cndmask_b32_e64 v1, -v126, v126, s[4:5]
	v_cndmask_b32_e64 v2, -v127, v127, s[4:5]
	ds_write2st64_b32 v16, v1, v2 offset0:68 offset1:70
	v_cndmask_b32_e64 v1, -v128, v128, s[4:5]
	v_cndmask_b32_e64 v2, -v129, v129, s[4:5]
	ds_write2st64_b32 v16, v1, v2 offset0:72 offset1:74
	v_cndmask_b32_e64 v1, -v130, v130, s[4:5]
	v_cndmask_b32_e64 v2, -v131, v131, s[4:5]
	ds_write2st64_b32 v16, v1, v2 offset0:76 offset1:78
	v_cndmask_b32_e64 v1, -v132, v132, s[4:5]
	v_cndmask_b32_e64 v2, -v133, v133, s[4:5]
	ds_write2st64_b32 v16, v1, v2 offset0:80 offset1:82
	v_cndmask_b32_e64 v1, -v134, v134, s[4:5]
	v_cndmask_b32_e64 v2, -v135, v135, s[4:5]
	ds_write2st64_b32 v16, v1, v2 offset0:84 offset1:86
	v_cndmask_b32_e64 v1, -v136, v136, s[4:5]
	v_cndmask_b32_e64 v2, -v137, v137, s[4:5]
	ds_write2st64_b32 v16, v1, v2 offset0:88 offset1:90
	v_cndmask_b32_e64 v1, -v138, v138, s[4:5]
	v_cndmask_b32_e64 v2, -v139, v139, s[4:5]
	s_waitcnt lgkmcnt(7)
	ds_write2st64_b32 v16, v1, v2 offset0:92 offset1:94
	v_cndmask_b32_e64 v1, -v140, v140, s[4:5]
	v_cndmask_b32_e64 v2, -v141, v141, s[4:5]
	ds_write2st64_b32 v16, v1, v2 offset0:96 offset1:98
	v_cndmask_b32_e64 v1, -v142, v142, s[4:5]
	v_cndmask_b32_e64 v2, -v143, v143, s[4:5]
	ds_write2st64_b32 v16, v1, v2 offset0:100 offset1:102
	v_cndmask_b32_e64 v1, -v60, v60, s[4:5]
	v_cndmask_b32_e64 v2, -v61, v61, s[4:5]
	ds_write2st64_b32 v16, v1, v2 offset0:104 offset1:106
	v_cndmask_b32_e64 v1, -v62, v62, s[4:5]
	v_cndmask_b32_e64 v2, -v63, v63, s[4:5]
	ds_write2st64_b32 v16, v1, v2 offset0:108 offset1:110
	v_cndmask_b32_e64 v1, -v64, v64, s[4:5]
	v_cndmask_b32_e64 v2, -v65, v65, s[4:5]
	ds_write2st64_b32 v16, v1, v2 offset0:112 offset1:114
	v_cndmask_b32_e64 v1, -v66, v66, s[4:5]
	v_cndmask_b32_e64 v2, -v67, v67, s[4:5]
	ds_write2st64_b32 v16, v1, v2 offset0:116 offset1:118
	v_cndmask_b32_e64 v1, -v68, v68, s[4:5]
	v_cndmask_b32_e64 v2, -v69, v69, s[4:5]
	ds_write2st64_b32 v16, v1, v2 offset0:120 offset1:122
	v_cndmask_b32_e64 v1, -v70, v70, s[4:5]
	v_cndmask_b32_e64 v2, -v71, v71, s[4:5]
	s_waitcnt lgkmcnt(7)
	ds_write2st64_b32 v16, v1, v2 offset0:124 offset1:126
